# RWKV scan state stored row-interleaved so each packed op serves both rows; removes 4 scalar adds per token (single accumulation chain)
# speedup vs baseline: 1.0058x; 1.0009x over previous
; DEV float reduce8_dpp(float v) { v += DPPF(v, 0xB1); v += DPPF(v, 0x4E); v += DPPF(v, 0x141); return v; }
;     ...
;                 for (int tok = 0; tok < 32; ++tok) {
;                     const float* bs = base0 + tok * 384;
;                     const f32x4 a0 = *(const f32x4*)bs, a1 = *(const f32x4*)(bs + 4);
;                     const f32x4 w0 = *(const f32x4*)(bs + 64), w1 = *(const f32x4*)(bs + 68);
;                     const f32x4 b0 = *(const f32x4*)(bs + 128), b1 = *(const f32x4*)(bs + 132);
;                     const f32x4 k0 = *(const f32x4*)(bs + 192), k1 = *(const f32x4*)(bs + 196);
;                     const f32x4 r0 = *(const f32x4*)(bs + 256), r1 = *(const f32x4*)(bs + 260);
;                     const f32x2 vv = *(const f32x2*)(op + (size_t)(buf * 32 + tok) * 384 + 320 + 2 * vp);
;                     const f32x2 av[4] = {(f32x2){a0[0], a0[1]}, (f32x2){a0[2], a0[3]}, (f32x2){a1[0], a1[1]}, (f32x2){a1[2], a1[3]}};
;                     const f32x2 wv[4] = {(f32x2){w0[0], w0[1]}, (f32x2){w0[2], w0[3]}, (f32x2){w1[0], w1[1]}, (f32x2){w1[2], w1[3]}};
;                     const f32x2 bv[4] = {(f32x2){b0[0], b0[1]}, (f32x2){b0[2], b0[3]}, (f32x2){b1[0], b1[1]}, (f32x2){b1[2], b1[3]}};
;                     const f32x2 kv[4] = {(f32x2){k0[0], k0[1]}, (f32x2){k0[2], k0[3]}, (f32x2){k1[0], k1[1]}, (f32x2){k1[2], k1[3]}};
;                     const f32x2 rv[4] = {(f32x2){r0[0], r0[1]}, (f32x2){r0[2], r0[3]}, (f32x2){r1[0], r1[1]}, (f32x2){r1[2], r1[3]}};
;                     float yo[2];
; #pragma unroll
;                     for (int i = 0; i < 2; ++i) {
;                         f32x2 sa2 = st[i][0] * av[0]; sa2 += st[i][1] * av[1]; sa2 += st[i][2] * av[2]; sa2 += st[i][3] * av[3];
;                         const float sa = reduce8_dpp(sa2[0] + sa2[1]);
;                         const float vi = vv[i];
;                         f32x2 y2 = (f32x2){0.f, 0.f};
; #pragma unroll
;                         for (int j = 0; j < 4; ++j) { st[i][j] = st[i][j] * wv[j] + sa * bv[j] + vi * kv[j]; y2 += st[i][j] * rv[j]; }
;                         yo[i] = reduce8_dpp(y2[0] + y2[1]);
;                     }
;                     if (kq == 0) *(f32x2*)(yb + tok * 64) = (f32x2){yo[0], yo[1]};
.LBB0_465:
	s_and_b32 s0, s2, 1
	s_mul_i32 s1, s0, 0xc000
	s_lshl_b32 s0, s0, 13
	v_add_u32_e32 v20, s1, v94
	v_add_u32_e32 v22, s1, v128
	v_add_u32_e32 v21, s0, v123
	ds_read_b128 v[24:27], v20
	ds_read_b128 v[28:31], v20 offset:16
	ds_read_b128 v[32:35], v20 offset:256
	ds_read_b128 v[36:39], v20 offset:272
	ds_read_b128 v[40:43], v20 offset:512
	ds_read_b128 v[44:47], v20 offset:528
	ds_read_b128 v[48:51], v20 offset:768
	ds_read_b128 v[52:55], v20 offset:784
	ds_read_b128 v[56:59], v20 offset:1024
	ds_read_b128 v[60:63], v20 offset:1040
	ds_read_b64 v[64:65], v22 offset:1280
	ds_read_b128 v[186:189], v20 offset:1536
	ds_read_b128 v[190:193], v20 offset:1552
	ds_read_b128 v[194:197], v20 offset:1792
	ds_read_b128 v[198:201], v20 offset:1808
	ds_read_b128 v[202:205], v20 offset:2048
	ds_read_b128 v[206:209], v20 offset:2064
	ds_read_b128 v[210:213], v20 offset:2304
	ds_read_b128 v[214:217], v20 offset:2320
	ds_read_b128 v[218:221], v20 offset:2560
	ds_read_b128 v[222:225], v20 offset:2576
	ds_read_b64 v[226:227], v22 offset:2816
	s_waitcnt lgkmcnt(11)
	v_pk_mul_f32 v[16:17], v[0:1], v[24:25] op_sel_hi:[1,0]
	v_pk_fma_f32 v[16:17], v[2:3], v[24:25], v[16:17] op_sel:[0,1,0]
	v_pk_fma_f32 v[16:17], v[4:5], v[26:27], v[16:17] op_sel_hi:[1,0,1]
	v_pk_fma_f32 v[16:17], v[6:7], v[26:27], v[16:17] op_sel:[0,1,0]
	v_pk_fma_f32 v[16:17], v[8:9], v[28:29], v[16:17] op_sel_hi:[1,0,1]
	v_pk_fma_f32 v[16:17], v[10:11], v[28:29], v[16:17] op_sel:[0,1,0]
	v_pk_fma_f32 v[16:17], v[12:13], v[30:31], v[16:17] op_sel_hi:[1,0,1]
	v_pk_fma_f32 v[16:17], v[14:15], v[30:31], v[16:17] op_sel:[0,1,0]
	v_pk_mul_f32 v[0:1], v[0:1], v[32:33] op_sel_hi:[1,0]
	v_pk_mul_f32 v[2:3], v[2:3], v[32:33] op_sel:[0,1]
	v_add_f32_dpp v16, v16, v16 quad_perm:[1,0,3,2] row_mask:0xf bank_mask:0xf bound_ctrl:1
	v_add_f32_dpp v17, v17, v17 quad_perm:[1,0,3,2] row_mask:0xf bank_mask:0xf bound_ctrl:1
	v_pk_mul_f32 v[4:5], v[4:5], v[34:35] op_sel_hi:[1,0]
	v_pk_mul_f32 v[6:7], v[6:7], v[34:35] op_sel:[0,1]
	v_add_f32_dpp v16, v16, v16 quad_perm:[2,3,0,1] row_mask:0xf bank_mask:0xf bound_ctrl:1
	v_add_f32_dpp v17, v17, v17 quad_perm:[2,3,0,1] row_mask:0xf bank_mask:0xf bound_ctrl:1
	v_pk_mul_f32 v[8:9], v[8:9], v[36:37] op_sel_hi:[1,0]
	v_pk_mul_f32 v[10:11], v[10:11], v[36:37] op_sel:[0,1]
	v_add_f32_dpp v228, v16, v16 row_half_mirror row_mask:0xf bank_mask:0xf bound_ctrl:1
	v_add_f32_dpp v229, v17, v17 row_half_mirror row_mask:0xf bank_mask:0xf bound_ctrl:1
	v_pk_mul_f32 v[12:13], v[12:13], v[38:39] op_sel_hi:[1,0]
	v_pk_mul_f32 v[14:15], v[14:15], v[38:39] op_sel:[0,1]
	v_pk_fma_f32 v[0:1], v[64:65], v[48:49], v[0:1] op_sel_hi:[1,0,1]
	v_pk_fma_f32 v[2:3], v[64:65], v[48:49], v[2:3] op_sel:[0,1,0]
	v_pk_fma_f32 v[4:5], v[64:65], v[50:51], v[4:5] op_sel_hi:[1,0,1]
	v_pk_fma_f32 v[6:7], v[64:65], v[50:51], v[6:7] op_sel:[0,1,0]
	v_pk_fma_f32 v[8:9], v[64:65], v[52:53], v[8:9] op_sel_hi:[1,0,1]
	v_pk_fma_f32 v[10:11], v[64:65], v[52:53], v[10:11] op_sel:[0,1,0]
	v_pk_fma_f32 v[12:13], v[64:65], v[54:55], v[12:13] op_sel_hi:[1,0,1]
	v_pk_fma_f32 v[14:15], v[64:65], v[54:55], v[14:15] op_sel:[0,1,0]
	v_pk_fma_f32 v[0:1], v[228:229], v[40:41], v[0:1] op_sel_hi:[1,0,1]
	v_pk_fma_f32 v[2:3], v[228:229], v[40:41], v[2:3] op_sel:[0,1,0]
	v_pk_fma_f32 v[4:5], v[228:229], v[42:43], v[4:5] op_sel_hi:[1,0,1]
	v_pk_fma_f32 v[6:7], v[228:229], v[42:43], v[6:7] op_sel:[0,1,0]
	v_pk_fma_f32 v[8:9], v[228:229], v[44:45], v[8:9] op_sel_hi:[1,0,1]
	v_pk_fma_f32 v[10:11], v[228:229], v[44:45], v[10:11] op_sel:[0,1,0]
	v_pk_fma_f32 v[12:13], v[228:229], v[46:47], v[12:13] op_sel_hi:[1,0,1]
	v_pk_fma_f32 v[14:15], v[228:229], v[46:47], v[14:15] op_sel:[0,1,0]
	v_pk_mul_f32 v[116:117], v[0:1], v[56:57] op_sel_hi:[1,0]
	v_pk_fma_f32 v[116:117], v[2:3], v[56:57], v[116:117] op_sel:[0,1,0]
	v_pk_fma_f32 v[116:117], v[4:5], v[58:59], v[116:117] op_sel_hi:[1,0,1]
	v_pk_fma_f32 v[116:117], v[6:7], v[58:59], v[116:117] op_sel:[0,1,0]
	v_pk_fma_f32 v[116:117], v[8:9], v[60:61], v[116:117] op_sel_hi:[1,0,1]
	v_pk_fma_f32 v[116:117], v[10:11], v[60:61], v[116:117] op_sel:[0,1,0]
	v_pk_fma_f32 v[116:117], v[12:13], v[62:63], v[116:117] op_sel_hi:[1,0,1]
	v_pk_fma_f32 v[116:117], v[14:15], v[62:63], v[116:117] op_sel:[0,1,0]
	ds_read_b128 v[24:27], v20 offset:3072
	ds_read_b128 v[28:31], v20 offset:3088
	v_add_f32_dpp v240, v116, v116 quad_perm:[1,0,3,2] row_mask:0xf bank_mask:0xf bound_ctrl:1
	v_add_f32_dpp v241, v117, v117 quad_perm:[1,0,3,2] row_mask:0xf bank_mask:0xf bound_ctrl:1
	ds_read_b128 v[32:35], v20 offset:3328
	v_add_f32_dpp v240, v240, v240 quad_perm:[2,3,0,1] row_mask:0xf bank_mask:0xf bound_ctrl:1
	v_add_f32_dpp v241, v241, v241 quad_perm:[2,3,0,1] row_mask:0xf bank_mask:0xf bound_ctrl:1
	ds_read_b128 v[36:39], v20 offset:3344
	v_add_f32_dpp v240, v240, v240 row_half_mirror row_mask:0xf bank_mask:0xf bound_ctrl:1
	v_add_f32_dpp v241, v241, v241 row_half_mirror row_mask:0xf bank_mask:0xf bound_ctrl:1
	ds_read_b128 v[40:43], v20 offset:3584
	ds_read_b128 v[44:47], v20 offset:3600
	ds_read_b128 v[48:51], v20 offset:3840
	ds_read_b128 v[52:55], v20 offset:3856
	ds_read_b128 v[56:59], v20 offset:4096
	ds_read_b128 v[60:63], v20 offset:4112
	ds_read_b64 v[64:65], v22 offset:4352
	ds_write_b64 v21, v[240:241]
	s_waitcnt lgkmcnt(12)
; DEV float reduce8_dpp(float v) { v += DPPF(v, 0xB1); v += DPPF(v, 0x4E); v += DPPF(v, 0x141); return v; }
;     ...
;                     const float* bs = base0 + tok * 384;
;                     const f32x4 a0 = *(const f32x4*)bs, a1 = *(const f32x4*)(bs + 4);
;                     const f32x4 w0 = *(const f32x4*)(bs + 64), w1 = *(const f32x4*)(bs + 68);
;                     const f32x4 b0 = *(const f32x4*)(bs + 128), b1 = *(const f32x4*)(bs + 132);
;                     const f32x4 k0 = *(const f32x4*)(bs + 192), k1 = *(const f32x4*)(bs + 196);
;                     const f32x4 r0 = *(const f32x4*)(bs + 256), r1 = *(const f32x4*)(bs + 260);
;                     const f32x2 vv = *(const f32x2*)(op + (size_t)(buf * 32 + tok) * 384 + 320 + 2 * vp);
;                     const f32x2 av[4] = {(f32x2){a0[0], a0[1]}, (f32x2){a0[2], a0[3]}, (f32x2){a1[0], a1[1]}, (f32x2){a1[2], a1[3]}};
;                     const f32x2 wv[4] = {(f32x2){w0[0], w0[1]}, (f32x2){w0[2], w0[3]}, (f32x2){w1[0], w1[1]}, (f32x2){w1[2], w1[3]}};
;                     const f32x2 bv[4] = {(f32x2){b0[0], b0[1]}, (f32x2){b0[2], b0[3]}, (f32x2){b1[0], b1[1]}, (f32x2){b1[2], b1[3]}};
;                     const f32x2 kv[4] = {(f32x2){k0[0], k0[1]}, (f32x2){k0[2], k0[3]}, (f32x2){k1[0], k1[1]}, (f32x2){k1[2], k1[3]}};
;                     const f32x2 rv[4] = {(f32x2){r0[0], r0[1]}, (f32x2){r0[2], r0[3]}, (f32x2){r1[0], r1[1]}, (f32x2){r1[2], r1[3]}};
;                     float yo[2];
; #pragma unroll
;                     for (int i = 0; i < 2; ++i) {
;                         f32x2 sa2 = st[i][0] * av[0]; sa2 += st[i][1] * av[1]; sa2 += st[i][2] * av[2]; sa2 += st[i][3] * av[3];
;                         const float sa = reduce8_dpp(sa2[0] + sa2[1]);
;                         const float vi = vv[i];
;                         f32x2 y2 = (f32x2){0.f, 0.f};
; #pragma unroll
;                         for (int j = 0; j < 4; ++j) { st[i][j] = st[i][j] * wv[j] + sa * bv[j] + vi * kv[j]; y2 += st[i][j] * rv[j]; }
;                         yo[i] = reduce8_dpp(y2[0] + y2[1]);
;                     }
;                     if (kq == 0) *(f32x2*)(yb + tok * 64) = (f32x2){yo[0], yo[1]};
	v_pk_mul_f32 v[16:17], v[0:1], v[186:187] op_sel_hi:[1,0]
	v_pk_fma_f32 v[16:17], v[2:3], v[186:187], v[16:17] op_sel:[0,1,0]
	v_pk_fma_f32 v[16:17], v[4:5], v[188:189], v[16:17] op_sel_hi:[1,0,1]
	v_pk_fma_f32 v[16:17], v[6:7], v[188:189], v[16:17] op_sel:[0,1,0]
	v_pk_fma_f32 v[16:17], v[8:9], v[190:191], v[16:17] op_sel_hi:[1,0,1]
	v_pk_fma_f32 v[16:17], v[10:11], v[190:191], v[16:17] op_sel:[0,1,0]
	v_pk_fma_f32 v[16:17], v[12:13], v[192:193], v[16:17] op_sel_hi:[1,0,1]
	v_pk_fma_f32 v[16:17], v[14:15], v[192:193], v[16:17] op_sel:[0,1,0]
	v_pk_mul_f32 v[0:1], v[0:1], v[194:195] op_sel_hi:[1,0]
	v_pk_mul_f32 v[2:3], v[2:3], v[194:195] op_sel:[0,1]
	v_add_f32_dpp v16, v16, v16 quad_perm:[1,0,3,2] row_mask:0xf bank_mask:0xf bound_ctrl:1
	v_add_f32_dpp v17, v17, v17 quad_perm:[1,0,3,2] row_mask:0xf bank_mask:0xf bound_ctrl:1
	v_pk_mul_f32 v[4:5], v[4:5], v[196:197] op_sel_hi:[1,0]
	v_pk_mul_f32 v[6:7], v[6:7], v[196:197] op_sel:[0,1]
	v_add_f32_dpp v16, v16, v16 quad_perm:[2,3,0,1] row_mask:0xf bank_mask:0xf bound_ctrl:1
	v_add_f32_dpp v17, v17, v17 quad_perm:[2,3,0,1] row_mask:0xf bank_mask:0xf bound_ctrl:1
	v_pk_mul_f32 v[8:9], v[8:9], v[198:199] op_sel_hi:[1,0]
	v_pk_mul_f32 v[10:11], v[10:11], v[198:199] op_sel:[0,1]
	v_add_f32_dpp v228, v16, v16 row_half_mirror row_mask:0xf bank_mask:0xf bound_ctrl:1
	v_add_f32_dpp v229, v17, v17 row_half_mirror row_mask:0xf bank_mask:0xf bound_ctrl:1
	v_pk_mul_f32 v[12:13], v[12:13], v[200:201] op_sel_hi:[1,0]
	v_pk_mul_f32 v[14:15], v[14:15], v[200:201] op_sel:[0,1]
	v_pk_fma_f32 v[0:1], v[226:227], v[210:211], v[0:1] op_sel_hi:[1,0,1]
	v_pk_fma_f32 v[2:3], v[226:227], v[210:211], v[2:3] op_sel:[0,1,0]
	v_pk_fma_f32 v[4:5], v[226:227], v[212:213], v[4:5] op_sel_hi:[1,0,1]
	v_pk_fma_f32 v[6:7], v[226:227], v[212:213], v[6:7] op_sel:[0,1,0]
	v_pk_fma_f32 v[8:9], v[226:227], v[214:215], v[8:9] op_sel_hi:[1,0,1]
	v_pk_fma_f32 v[10:11], v[226:227], v[214:215], v[10:11] op_sel:[0,1,0]
	v_pk_fma_f32 v[12:13], v[226:227], v[216:217], v[12:13] op_sel_hi:[1,0,1]
	v_pk_fma_f32 v[14:15], v[226:227], v[216:217], v[14:15] op_sel:[0,1,0]
	v_pk_fma_f32 v[0:1], v[228:229], v[202:203], v[0:1] op_sel_hi:[1,0,1]
	v_pk_fma_f32 v[2:3], v[228:229], v[202:203], v[2:3] op_sel:[0,1,0]
	v_pk_fma_f32 v[4:5], v[228:229], v[204:205], v[4:5] op_sel_hi:[1,0,1]
	v_pk_fma_f32 v[6:7], v[228:229], v[204:205], v[6:7] op_sel:[0,1,0]
	v_pk_fma_f32 v[8:9], v[228:229], v[206:207], v[8:9] op_sel_hi:[1,0,1]
	v_pk_fma_f32 v[10:11], v[228:229], v[206:207], v[10:11] op_sel:[0,1,0]
	v_pk_fma_f32 v[12:13], v[228:229], v[208:209], v[12:13] op_sel_hi:[1,0,1]
	v_pk_fma_f32 v[14:15], v[228:229], v[208:209], v[14:15] op_sel:[0,1,0]
	v_pk_mul_f32 v[116:117], v[0:1], v[218:219] op_sel_hi:[1,0]
	v_pk_fma_f32 v[116:117], v[2:3], v[218:219], v[116:117] op_sel:[0,1,0]
	v_pk_fma_f32 v[116:117], v[4:5], v[220:221], v[116:117] op_sel_hi:[1,0,1]
	v_pk_fma_f32 v[116:117], v[6:7], v[220:221], v[116:117] op_sel:[0,1,0]
	v_pk_fma_f32 v[116:117], v[8:9], v[222:223], v[116:117] op_sel_hi:[1,0,1]
	v_pk_fma_f32 v[116:117], v[10:11], v[222:223], v[116:117] op_sel:[0,1,0]
	v_pk_fma_f32 v[116:117], v[12:13], v[224:225], v[116:117] op_sel_hi:[1,0,1]
	v_pk_fma_f32 v[116:117], v[14:15], v[224:225], v[116:117] op_sel:[0,1,0]
	ds_read_b128 v[186:189], v20 offset:4608
	ds_read_b128 v[190:193], v20 offset:4624
	v_add_f32_dpp v240, v116, v116 quad_perm:[1,0,3,2] row_mask:0xf bank_mask:0xf bound_ctrl:1
	v_add_f32_dpp v241, v117, v117 quad_perm:[1,0,3,2] row_mask:0xf bank_mask:0xf bound_ctrl:1
	ds_read_b128 v[194:197], v20 offset:4864
	v_add_f32_dpp v240, v240, v240 quad_perm:[2,3,0,1] row_mask:0xf bank_mask:0xf bound_ctrl:1
	v_add_f32_dpp v241, v241, v241 quad_perm:[2,3,0,1] row_mask:0xf bank_mask:0xf bound_ctrl:1
	ds_read_b128 v[198:201], v20 offset:4880
	v_add_f32_dpp v240, v240, v240 row_half_mirror row_mask:0xf bank_mask:0xf bound_ctrl:1
	v_add_f32_dpp v241, v241, v241 row_half_mirror row_mask:0xf bank_mask:0xf bound_ctrl:1
	ds_read_b128 v[202:205], v20 offset:5120
	ds_read_b128 v[206:209], v20 offset:5136
	ds_read_b128 v[210:213], v20 offset:5376
	ds_read_b128 v[214:217], v20 offset:5392
	ds_read_b128 v[218:221], v20 offset:5632
	ds_read_b128 v[222:225], v20 offset:5648
	ds_read_b64 v[226:227], v22 offset:5888
	ds_write_b64 v21, v[240:241] offset:256
	s_waitcnt lgkmcnt(12)
; DEV float reduce8_dpp(float v) { v += DPPF(v, 0xB1); v += DPPF(v, 0x4E); v += DPPF(v, 0x141); return v; }
;     ...
;                     const float* bs = base0 + tok * 384;
;                     const f32x4 a0 = *(const f32x4*)bs, a1 = *(const f32x4*)(bs + 4);
;                     const f32x4 w0 = *(const f32x4*)(bs + 64), w1 = *(const f32x4*)(bs + 68);
;                     const f32x4 b0 = *(const f32x4*)(bs + 128), b1 = *(const f32x4*)(bs + 132);
;                     const f32x4 k0 = *(const f32x4*)(bs + 192), k1 = *(const f32x4*)(bs + 196);
;                     const f32x4 r0 = *(const f32x4*)(bs + 256), r1 = *(const f32x4*)(bs + 260);
;                     const f32x2 vv = *(const f32x2*)(op + (size_t)(buf * 32 + tok) * 384 + 320 + 2 * vp);
;                     const f32x2 av[4] = {(f32x2){a0[0], a0[1]}, (f32x2){a0[2], a0[3]}, (f32x2){a1[0], a1[1]}, (f32x2){a1[2], a1[3]}};
;                     const f32x2 wv[4] = {(f32x2){w0[0], w0[1]}, (f32x2){w0[2], w0[3]}, (f32x2){w1[0], w1[1]}, (f32x2){w1[2], w1[3]}};
;                     const f32x2 bv[4] = {(f32x2){b0[0], b0[1]}, (f32x2){b0[2], b0[3]}, (f32x2){b1[0], b1[1]}, (f32x2){b1[2], b1[3]}};
;                     const f32x2 kv[4] = {(f32x2){k0[0], k0[1]}, (f32x2){k0[2], k0[3]}, (f32x2){k1[0], k1[1]}, (f32x2){k1[2], k1[3]}};
;                     const f32x2 rv[4] = {(f32x2){r0[0], r0[1]}, (f32x2){r0[2], r0[3]}, (f32x2){r1[0], r1[1]}, (f32x2){r1[2], r1[3]}};
;                     float yo[2];
; #pragma unroll
;                     for (int i = 0; i < 2; ++i) {
;                         f32x2 sa2 = st[i][0] * av[0]; sa2 += st[i][1] * av[1]; sa2 += st[i][2] * av[2]; sa2 += st[i][3] * av[3];
;                         const float sa = reduce8_dpp(sa2[0] + sa2[1]);
;                         const float vi = vv[i];
;                         f32x2 y2 = (f32x2){0.f, 0.f};
; #pragma unroll
;                         for (int j = 0; j < 4; ++j) { st[i][j] = st[i][j] * wv[j] + sa * bv[j] + vi * kv[j]; y2 += st[i][j] * rv[j]; }
;                         yo[i] = reduce8_dpp(y2[0] + y2[1]);
;                     }
;                     if (kq == 0) *(f32x2*)(yb + tok * 64) = (f32x2){yo[0], yo[1]};
	v_pk_mul_f32 v[16:17], v[0:1], v[24:25] op_sel_hi:[1,0]
	v_pk_fma_f32 v[16:17], v[2:3], v[24:25], v[16:17] op_sel:[0,1,0]
	v_pk_fma_f32 v[16:17], v[4:5], v[26:27], v[16:17] op_sel_hi:[1,0,1]
	v_pk_fma_f32 v[16:17], v[6:7], v[26:27], v[16:17] op_sel:[0,1,0]
	v_pk_fma_f32 v[16:17], v[8:9], v[28:29], v[16:17] op_sel_hi:[1,0,1]
	v_pk_fma_f32 v[16:17], v[10:11], v[28:29], v[16:17] op_sel:[0,1,0]
	v_pk_fma_f32 v[16:17], v[12:13], v[30:31], v[16:17] op_sel_hi:[1,0,1]
	v_pk_fma_f32 v[16:17], v[14:15], v[30:31], v[16:17] op_sel:[0,1,0]
	v_pk_mul_f32 v[0:1], v[0:1], v[32:33] op_sel_hi:[1,0]
	v_pk_mul_f32 v[2:3], v[2:3], v[32:33] op_sel:[0,1]
	v_add_f32_dpp v16, v16, v16 quad_perm:[1,0,3,2] row_mask:0xf bank_mask:0xf bound_ctrl:1
	v_add_f32_dpp v17, v17, v17 quad_perm:[1,0,3,2] row_mask:0xf bank_mask:0xf bound_ctrl:1
	v_pk_mul_f32 v[4:5], v[4:5], v[34:35] op_sel_hi:[1,0]
	v_pk_mul_f32 v[6:7], v[6:7], v[34:35] op_sel:[0,1]
	v_add_f32_dpp v16, v16, v16 quad_perm:[2,3,0,1] row_mask:0xf bank_mask:0xf bound_ctrl:1
	v_add_f32_dpp v17, v17, v17 quad_perm:[2,3,0,1] row_mask:0xf bank_mask:0xf bound_ctrl:1
	v_pk_mul_f32 v[8:9], v[8:9], v[36:37] op_sel_hi:[1,0]
	v_pk_mul_f32 v[10:11], v[10:11], v[36:37] op_sel:[0,1]
	v_add_f32_dpp v228, v16, v16 row_half_mirror row_mask:0xf bank_mask:0xf bound_ctrl:1
	v_add_f32_dpp v229, v17, v17 row_half_mirror row_mask:0xf bank_mask:0xf bound_ctrl:1
	v_pk_mul_f32 v[12:13], v[12:13], v[38:39] op_sel_hi:[1,0]
	v_pk_mul_f32 v[14:15], v[14:15], v[38:39] op_sel:[0,1]
	v_pk_fma_f32 v[0:1], v[64:65], v[48:49], v[0:1] op_sel_hi:[1,0,1]
	v_pk_fma_f32 v[2:3], v[64:65], v[48:49], v[2:3] op_sel:[0,1,0]
	v_pk_fma_f32 v[4:5], v[64:65], v[50:51], v[4:5] op_sel_hi:[1,0,1]
	v_pk_fma_f32 v[6:7], v[64:65], v[50:51], v[6:7] op_sel:[0,1,0]
	v_pk_fma_f32 v[8:9], v[64:65], v[52:53], v[8:9] op_sel_hi:[1,0,1]
	v_pk_fma_f32 v[10:11], v[64:65], v[52:53], v[10:11] op_sel:[0,1,0]
	v_pk_fma_f32 v[12:13], v[64:65], v[54:55], v[12:13] op_sel_hi:[1,0,1]
	v_pk_fma_f32 v[14:15], v[64:65], v[54:55], v[14:15] op_sel:[0,1,0]
	v_pk_fma_f32 v[0:1], v[228:229], v[40:41], v[0:1] op_sel_hi:[1,0,1]
	v_pk_fma_f32 v[2:3], v[228:229], v[40:41], v[2:3] op_sel:[0,1,0]
	v_pk_fma_f32 v[4:5], v[228:229], v[42:43], v[4:5] op_sel_hi:[1,0,1]
	v_pk_fma_f32 v[6:7], v[228:229], v[42:43], v[6:7] op_sel:[0,1,0]
	v_pk_fma_f32 v[8:9], v[228:229], v[44:45], v[8:9] op_sel_hi:[1,0,1]
	v_pk_fma_f32 v[10:11], v[228:229], v[44:45], v[10:11] op_sel:[0,1,0]
	v_pk_fma_f32 v[12:13], v[228:229], v[46:47], v[12:13] op_sel_hi:[1,0,1]
	v_pk_fma_f32 v[14:15], v[228:229], v[46:47], v[14:15] op_sel:[0,1,0]
	v_pk_mul_f32 v[116:117], v[0:1], v[56:57] op_sel_hi:[1,0]
	v_pk_fma_f32 v[116:117], v[2:3], v[56:57], v[116:117] op_sel:[0,1,0]
	v_pk_fma_f32 v[116:117], v[4:5], v[58:59], v[116:117] op_sel_hi:[1,0,1]
	v_pk_fma_f32 v[116:117], v[6:7], v[58:59], v[116:117] op_sel:[0,1,0]
	v_pk_fma_f32 v[116:117], v[8:9], v[60:61], v[116:117] op_sel_hi:[1,0,1]
	v_pk_fma_f32 v[116:117], v[10:11], v[60:61], v[116:117] op_sel:[0,1,0]
	v_pk_fma_f32 v[116:117], v[12:13], v[62:63], v[116:117] op_sel_hi:[1,0,1]
	v_pk_fma_f32 v[116:117], v[14:15], v[62:63], v[116:117] op_sel:[0,1,0]
	ds_read_b128 v[24:27], v20 offset:6144
	ds_read_b128 v[28:31], v20 offset:6160
	v_add_f32_dpp v240, v116, v116 quad_perm:[1,0,3,2] row_mask:0xf bank_mask:0xf bound_ctrl:1
	v_add_f32_dpp v241, v117, v117 quad_perm:[1,0,3,2] row_mask:0xf bank_mask:0xf bound_ctrl:1
	ds_read_b128 v[32:35], v20 offset:6400
	v_add_f32_dpp v240, v240, v240 quad_perm:[2,3,0,1] row_mask:0xf bank_mask:0xf bound_ctrl:1
	v_add_f32_dpp v241, v241, v241 quad_perm:[2,3,0,1] row_mask:0xf bank_mask:0xf bound_ctrl:1
	ds_read_b128 v[36:39], v20 offset:6416
	v_add_f32_dpp v240, v240, v240 row_half_mirror row_mask:0xf bank_mask:0xf bound_ctrl:1
	v_add_f32_dpp v241, v241, v241 row_half_mirror row_mask:0xf bank_mask:0xf bound_ctrl:1
	ds_read_b128 v[40:43], v20 offset:6656
	ds_read_b128 v[44:47], v20 offset:6672
	ds_read_b128 v[48:51], v20 offset:6912
	ds_read_b128 v[52:55], v20 offset:6928
	ds_read_b128 v[56:59], v20 offset:7168
	ds_read_b128 v[60:63], v20 offset:7184
	ds_read_b64 v[64:65], v22 offset:7424
	ds_write_b64 v21, v[240:241] offset:512
	s_waitcnt lgkmcnt(12)
	v_pk_mul_f32 v[16:17], v[0:1], v[186:187] op_sel_hi:[1,0]
	v_pk_fma_f32 v[16:17], v[2:3], v[186:187], v[16:17] op_sel:[0,1,0]
	v_pk_fma_f32 v[16:17], v[4:5], v[188:189], v[16:17] op_sel_hi:[1,0,1]
	v_pk_fma_f32 v[16:17], v[6:7], v[188:189], v[16:17] op_sel:[0,1,0]
	v_pk_fma_f32 v[16:17], v[8:9], v[190:191], v[16:17] op_sel_hi:[1,0,1]
	v_pk_fma_f32 v[16:17], v[10:11], v[190:191], v[16:17] op_sel:[0,1,0]
	v_pk_fma_f32 v[16:17], v[12:13], v[192:193], v[16:17] op_sel_hi:[1,0,1]
	v_pk_fma_f32 v[16:17], v[14:15], v[192:193], v[16:17] op_sel:[0,1,0]
	v_pk_mul_f32 v[0:1], v[0:1], v[194:195] op_sel_hi:[1,0]
	v_pk_mul_f32 v[2:3], v[2:3], v[194:195] op_sel:[0,1]
	v_add_f32_dpp v16, v16, v16 quad_perm:[1,0,3,2] row_mask:0xf bank_mask:0xf bound_ctrl:1
	v_add_f32_dpp v17, v17, v17 quad_perm:[1,0,3,2] row_mask:0xf bank_mask:0xf bound_ctrl:1
	v_pk_mul_f32 v[4:5], v[4:5], v[196:197] op_sel_hi:[1,0]
	v_pk_mul_f32 v[6:7], v[6:7], v[196:197] op_sel:[0,1]
	v_add_f32_dpp v16, v16, v16 quad_perm:[2,3,0,1] row_mask:0xf bank_mask:0xf bound_ctrl:1
	v_add_f32_dpp v17, v17, v17 quad_perm:[2,3,0,1] row_mask:0xf bank_mask:0xf bound_ctrl:1
	v_pk_mul_f32 v[8:9], v[8:9], v[198:199] op_sel_hi:[1,0]
	v_pk_mul_f32 v[10:11], v[10:11], v[198:199] op_sel:[0,1]
	v_add_f32_dpp v228, v16, v16 row_half_mirror row_mask:0xf bank_mask:0xf bound_ctrl:1
	v_add_f32_dpp v229, v17, v17 row_half_mirror row_mask:0xf bank_mask:0xf bound_ctrl:1
; DEV float reduce8_dpp(float v) { v += DPPF(v, 0xB1); v += DPPF(v, 0x4E); v += DPPF(v, 0x141); return v; }
;     ...
;                     const float* bs = base0 + tok * 384;
;                     const f32x4 a0 = *(const f32x4*)bs, a1 = *(const f32x4*)(bs + 4);
;                     const f32x4 w0 = *(const f32x4*)(bs + 64), w1 = *(const f32x4*)(bs + 68);
;                     const f32x4 b0 = *(const f32x4*)(bs + 128), b1 = *(const f32x4*)(bs + 132);
;                     const f32x4 k0 = *(const f32x4*)(bs + 192), k1 = *(const f32x4*)(bs + 196);
;                     const f32x4 r0 = *(const f32x4*)(bs + 256), r1 = *(const f32x4*)(bs + 260);
;                     const f32x2 vv = *(const f32x2*)(op + (size_t)(buf * 32 + tok) * 384 + 320 + 2 * vp);
;                     const f32x2 av[4] = {(f32x2){a0[0], a0[1]}, (f32x2){a0[2], a0[3]}, (f32x2){a1[0], a1[1]}, (f32x2){a1[2], a1[3]}};
;                     const f32x2 wv[4] = {(f32x2){w0[0], w0[1]}, (f32x2){w0[2], w0[3]}, (f32x2){w1[0], w1[1]}, (f32x2){w1[2], w1[3]}};
;                     const f32x2 bv[4] = {(f32x2){b0[0], b0[1]}, (f32x2){b0[2], b0[3]}, (f32x2){b1[0], b1[1]}, (f32x2){b1[2], b1[3]}};
;                     const f32x2 kv[4] = {(f32x2){k0[0], k0[1]}, (f32x2){k0[2], k0[3]}, (f32x2){k1[0], k1[1]}, (f32x2){k1[2], k1[3]}};
;                     const f32x2 rv[4] = {(f32x2){r0[0], r0[1]}, (f32x2){r0[2], r0[3]}, (f32x2){r1[0], r1[1]}, (f32x2){r1[2], r1[3]}};
;                     float yo[2];
; #pragma unroll
;                     for (int i = 0; i < 2; ++i) {
;                         f32x2 sa2 = st[i][0] * av[0]; sa2 += st[i][1] * av[1]; sa2 += st[i][2] * av[2]; sa2 += st[i][3] * av[3];
;                         const float sa = reduce8_dpp(sa2[0] + sa2[1]);
;                         const float vi = vv[i];
;                         f32x2 y2 = (f32x2){0.f, 0.f};
; #pragma unroll
;                         for (int j = 0; j < 4; ++j) { st[i][j] = st[i][j] * wv[j] + sa * bv[j] + vi * kv[j]; y2 += st[i][j] * rv[j]; }
;                         yo[i] = reduce8_dpp(y2[0] + y2[1]);
;                     }
;                     if (kq == 0) *(f32x2*)(yb + tok * 64) = (f32x2){yo[0], yo[1]};
	v_pk_mul_f32 v[12:13], v[12:13], v[200:201] op_sel_hi:[1,0]
	v_pk_mul_f32 v[14:15], v[14:15], v[200:201] op_sel:[0,1]
	v_pk_fma_f32 v[0:1], v[226:227], v[210:211], v[0:1] op_sel_hi:[1,0,1]
	v_pk_fma_f32 v[2:3], v[226:227], v[210:211], v[2:3] op_sel:[0,1,0]
	v_pk_fma_f32 v[4:5], v[226:227], v[212:213], v[4:5] op_sel_hi:[1,0,1]
	v_pk_fma_f32 v[6:7], v[226:227], v[212:213], v[6:7] op_sel:[0,1,0]
	v_pk_fma_f32 v[8:9], v[226:227], v[214:215], v[8:9] op_sel_hi:[1,0,1]
	v_pk_fma_f32 v[10:11], v[226:227], v[214:215], v[10:11] op_sel:[0,1,0]
	v_pk_fma_f32 v[12:13], v[226:227], v[216:217], v[12:13] op_sel_hi:[1,0,1]
	v_pk_fma_f32 v[14:15], v[226:227], v[216:217], v[14:15] op_sel:[0,1,0]
	v_pk_fma_f32 v[0:1], v[228:229], v[202:203], v[0:1] op_sel_hi:[1,0,1]
	v_pk_fma_f32 v[2:3], v[228:229], v[202:203], v[2:3] op_sel:[0,1,0]
	v_pk_fma_f32 v[4:5], v[228:229], v[204:205], v[4:5] op_sel_hi:[1,0,1]
	v_pk_fma_f32 v[6:7], v[228:229], v[204:205], v[6:7] op_sel:[0,1,0]
	v_pk_fma_f32 v[8:9], v[228:229], v[206:207], v[8:9] op_sel_hi:[1,0,1]
	v_pk_fma_f32 v[10:11], v[228:229], v[206:207], v[10:11] op_sel:[0,1,0]
	v_pk_fma_f32 v[12:13], v[228:229], v[208:209], v[12:13] op_sel_hi:[1,0,1]
	v_pk_fma_f32 v[14:15], v[228:229], v[208:209], v[14:15] op_sel:[0,1,0]
	v_pk_mul_f32 v[116:117], v[0:1], v[218:219] op_sel_hi:[1,0]
	v_pk_fma_f32 v[116:117], v[2:3], v[218:219], v[116:117] op_sel:[0,1,0]
	v_pk_fma_f32 v[116:117], v[4:5], v[220:221], v[116:117] op_sel_hi:[1,0,1]
	v_pk_fma_f32 v[116:117], v[6:7], v[220:221], v[116:117] op_sel:[0,1,0]
	v_pk_fma_f32 v[116:117], v[8:9], v[222:223], v[116:117] op_sel_hi:[1,0,1]
	v_pk_fma_f32 v[116:117], v[10:11], v[222:223], v[116:117] op_sel:[0,1,0]
	v_pk_fma_f32 v[116:117], v[12:13], v[224:225], v[116:117] op_sel_hi:[1,0,1]
	v_pk_fma_f32 v[116:117], v[14:15], v[224:225], v[116:117] op_sel:[0,1,0]
	ds_read_b128 v[186:189], v20 offset:7680
	ds_read_b128 v[190:193], v20 offset:7696
	v_add_f32_dpp v240, v116, v116 quad_perm:[1,0,3,2] row_mask:0xf bank_mask:0xf bound_ctrl:1
	v_add_f32_dpp v241, v117, v117 quad_perm:[1,0,3,2] row_mask:0xf bank_mask:0xf bound_ctrl:1
	ds_read_b128 v[194:197], v20 offset:7936
	v_add_f32_dpp v240, v240, v240 quad_perm:[2,3,0,1] row_mask:0xf bank_mask:0xf bound_ctrl:1
	v_add_f32_dpp v241, v241, v241 quad_perm:[2,3,0,1] row_mask:0xf bank_mask:0xf bound_ctrl:1
	ds_read_b128 v[198:201], v20 offset:7952
	v_add_f32_dpp v240, v240, v240 row_half_mirror row_mask:0xf bank_mask:0xf bound_ctrl:1
	v_add_f32_dpp v241, v241, v241 row_half_mirror row_mask:0xf bank_mask:0xf bound_ctrl:1
	ds_read_b128 v[202:205], v20 offset:8192
	ds_read_b128 v[206:209], v20 offset:8208
	ds_read_b128 v[210:213], v20 offset:8448
	ds_read_b128 v[214:217], v20 offset:8464
	ds_read_b128 v[218:221], v20 offset:8704
	ds_read_b128 v[222:225], v20 offset:8720
	ds_read_b64 v[226:227], v22 offset:8960
	ds_write_b64 v21, v[240:241] offset:768
	s_waitcnt lgkmcnt(12)
	v_pk_mul_f32 v[16:17], v[0:1], v[24:25] op_sel_hi:[1,0]
	v_pk_fma_f32 v[16:17], v[2:3], v[24:25], v[16:17] op_sel:[0,1,0]
	v_pk_fma_f32 v[16:17], v[4:5], v[26:27], v[16:17] op_sel_hi:[1,0,1]
	v_pk_fma_f32 v[16:17], v[6:7], v[26:27], v[16:17] op_sel:[0,1,0]
	v_pk_fma_f32 v[16:17], v[8:9], v[28:29], v[16:17] op_sel_hi:[1,0,1]
	v_pk_fma_f32 v[16:17], v[10:11], v[28:29], v[16:17] op_sel:[0,1,0]
	v_pk_fma_f32 v[16:17], v[12:13], v[30:31], v[16:17] op_sel_hi:[1,0,1]
	v_pk_fma_f32 v[16:17], v[14:15], v[30:31], v[16:17] op_sel:[0,1,0]
	v_pk_mul_f32 v[0:1], v[0:1], v[32:33] op_sel_hi:[1,0]
	v_pk_mul_f32 v[2:3], v[2:3], v[32:33] op_sel:[0,1]
	v_add_f32_dpp v16, v16, v16 quad_perm:[1,0,3,2] row_mask:0xf bank_mask:0xf bound_ctrl:1
	v_add_f32_dpp v17, v17, v17 quad_perm:[1,0,3,2] row_mask:0xf bank_mask:0xf bound_ctrl:1
	v_pk_mul_f32 v[4:5], v[4:5], v[34:35] op_sel_hi:[1,0]
	v_pk_mul_f32 v[6:7], v[6:7], v[34:35] op_sel:[0,1]
	v_add_f32_dpp v16, v16, v16 quad_perm:[2,3,0,1] row_mask:0xf bank_mask:0xf bound_ctrl:1
	v_add_f32_dpp v17, v17, v17 quad_perm:[2,3,0,1] row_mask:0xf bank_mask:0xf bound_ctrl:1
	v_pk_mul_f32 v[8:9], v[8:9], v[36:37] op_sel_hi:[1,0]
	v_pk_mul_f32 v[10:11], v[10:11], v[36:37] op_sel:[0,1]
	v_add_f32_dpp v228, v16, v16 row_half_mirror row_mask:0xf bank_mask:0xf bound_ctrl:1
	v_add_f32_dpp v229, v17, v17 row_half_mirror row_mask:0xf bank_mask:0xf bound_ctrl:1
	v_pk_mul_f32 v[12:13], v[12:13], v[38:39] op_sel_hi:[1,0]
	v_pk_mul_f32 v[14:15], v[14:15], v[38:39] op_sel:[0,1]
	v_pk_fma_f32 v[0:1], v[64:65], v[48:49], v[0:1] op_sel_hi:[1,0,1]
	v_pk_fma_f32 v[2:3], v[64:65], v[48:49], v[2:3] op_sel:[0,1,0]
	v_pk_fma_f32 v[4:5], v[64:65], v[50:51], v[4:5] op_sel_hi:[1,0,1]
	v_pk_fma_f32 v[6:7], v[64:65], v[50:51], v[6:7] op_sel:[0,1,0]
	v_pk_fma_f32 v[8:9], v[64:65], v[52:53], v[8:9] op_sel_hi:[1,0,1]
	v_pk_fma_f32 v[10:11], v[64:65], v[52:53], v[10:11] op_sel:[0,1,0]
	v_pk_fma_f32 v[12:13], v[64:65], v[54:55], v[12:13] op_sel_hi:[1,0,1]
	v_pk_fma_f32 v[14:15], v[64:65], v[54:55], v[14:15] op_sel:[0,1,0]
	v_pk_fma_f32 v[0:1], v[228:229], v[40:41], v[0:1] op_sel_hi:[1,0,1]
	v_pk_fma_f32 v[2:3], v[228:229], v[40:41], v[2:3] op_sel:[0,1,0]
	v_pk_fma_f32 v[4:5], v[228:229], v[42:43], v[4:5] op_sel_hi:[1,0,1]
	v_pk_fma_f32 v[6:7], v[228:229], v[42:43], v[6:7] op_sel:[0,1,0]
	v_pk_fma_f32 v[8:9], v[228:229], v[44:45], v[8:9] op_sel_hi:[1,0,1]
	v_pk_fma_f32 v[10:11], v[228:229], v[44:45], v[10:11] op_sel:[0,1,0]
	v_pk_fma_f32 v[12:13], v[228:229], v[46:47], v[12:13] op_sel_hi:[1,0,1]
	v_pk_fma_f32 v[14:15], v[228:229], v[46:47], v[14:15] op_sel:[0,1,0]
	v_pk_mul_f32 v[116:117], v[0:1], v[56:57] op_sel_hi:[1,0]
	v_pk_fma_f32 v[116:117], v[2:3], v[56:57], v[116:117] op_sel:[0,1,0]
; DEV float reduce8_dpp(float v) { v += DPPF(v, 0xB1); v += DPPF(v, 0x4E); v += DPPF(v, 0x141); return v; }
;     ...
;                     const float* bs = base0 + tok * 384;
;                     const f32x4 a0 = *(const f32x4*)bs, a1 = *(const f32x4*)(bs + 4);
;                     const f32x4 w0 = *(const f32x4*)(bs + 64), w1 = *(const f32x4*)(bs + 68);
;                     const f32x4 b0 = *(const f32x4*)(bs + 128), b1 = *(const f32x4*)(bs + 132);
;                     const f32x4 k0 = *(const f32x4*)(bs + 192), k1 = *(const f32x4*)(bs + 196);
;                     const f32x4 r0 = *(const f32x4*)(bs + 256), r1 = *(const f32x4*)(bs + 260);
;                     const f32x2 vv = *(const f32x2*)(op + (size_t)(buf * 32 + tok) * 384 + 320 + 2 * vp);
;                     const f32x2 av[4] = {(f32x2){a0[0], a0[1]}, (f32x2){a0[2], a0[3]}, (f32x2){a1[0], a1[1]}, (f32x2){a1[2], a1[3]}};
;                     const f32x2 wv[4] = {(f32x2){w0[0], w0[1]}, (f32x2){w0[2], w0[3]}, (f32x2){w1[0], w1[1]}, (f32x2){w1[2], w1[3]}};
;                     const f32x2 bv[4] = {(f32x2){b0[0], b0[1]}, (f32x2){b0[2], b0[3]}, (f32x2){b1[0], b1[1]}, (f32x2){b1[2], b1[3]}};
;                     const f32x2 kv[4] = {(f32x2){k0[0], k0[1]}, (f32x2){k0[2], k0[3]}, (f32x2){k1[0], k1[1]}, (f32x2){k1[2], k1[3]}};
;                     const f32x2 rv[4] = {(f32x2){r0[0], r0[1]}, (f32x2){r0[2], r0[3]}, (f32x2){r1[0], r1[1]}, (f32x2){r1[2], r1[3]}};
;                     float yo[2];
; #pragma unroll
;                     for (int i = 0; i < 2; ++i) {
;                         f32x2 sa2 = st[i][0] * av[0]; sa2 += st[i][1] * av[1]; sa2 += st[i][2] * av[2]; sa2 += st[i][3] * av[3];
;                         const float sa = reduce8_dpp(sa2[0] + sa2[1]);
;                         const float vi = vv[i];
;                         f32x2 y2 = (f32x2){0.f, 0.f};
; #pragma unroll
;                         for (int j = 0; j < 4; ++j) { st[i][j] = st[i][j] * wv[j] + sa * bv[j] + vi * kv[j]; y2 += st[i][j] * rv[j]; }
;                         yo[i] = reduce8_dpp(y2[0] + y2[1]);
;                     }
;                     if (kq == 0) *(f32x2*)(yb + tok * 64) = (f32x2){yo[0], yo[1]};
	v_pk_fma_f32 v[116:117], v[4:5], v[58:59], v[116:117] op_sel_hi:[1,0,1]
	v_pk_fma_f32 v[116:117], v[6:7], v[58:59], v[116:117] op_sel:[0,1,0]
	v_pk_fma_f32 v[116:117], v[8:9], v[60:61], v[116:117] op_sel_hi:[1,0,1]
	v_pk_fma_f32 v[116:117], v[10:11], v[60:61], v[116:117] op_sel:[0,1,0]
	v_pk_fma_f32 v[116:117], v[12:13], v[62:63], v[116:117] op_sel_hi:[1,0,1]
	v_pk_fma_f32 v[116:117], v[14:15], v[62:63], v[116:117] op_sel:[0,1,0]
	ds_read_b128 v[24:27], v20 offset:9216
	ds_read_b128 v[28:31], v20 offset:9232
	v_add_f32_dpp v240, v116, v116 quad_perm:[1,0,3,2] row_mask:0xf bank_mask:0xf bound_ctrl:1
	v_add_f32_dpp v241, v117, v117 quad_perm:[1,0,3,2] row_mask:0xf bank_mask:0xf bound_ctrl:1
	ds_read_b128 v[32:35], v20 offset:9472
	v_add_f32_dpp v240, v240, v240 quad_perm:[2,3,0,1] row_mask:0xf bank_mask:0xf bound_ctrl:1
	v_add_f32_dpp v241, v241, v241 quad_perm:[2,3,0,1] row_mask:0xf bank_mask:0xf bound_ctrl:1
	ds_read_b128 v[36:39], v20 offset:9488
	v_add_f32_dpp v240, v240, v240 row_half_mirror row_mask:0xf bank_mask:0xf bound_ctrl:1
	v_add_f32_dpp v241, v241, v241 row_half_mirror row_mask:0xf bank_mask:0xf bound_ctrl:1
	ds_read_b128 v[40:43], v20 offset:9728
	ds_read_b128 v[44:47], v20 offset:9744
	ds_read_b128 v[48:51], v20 offset:9984
	ds_read_b128 v[52:55], v20 offset:10000
	ds_read_b128 v[56:59], v20 offset:10240
	ds_read_b128 v[60:63], v20 offset:10256
	ds_read_b64 v[64:65], v22 offset:10496
	ds_write_b64 v21, v[240:241] offset:1024
	s_waitcnt lgkmcnt(12)
	v_pk_mul_f32 v[16:17], v[0:1], v[186:187] op_sel_hi:[1,0]
	v_pk_fma_f32 v[16:17], v[2:3], v[186:187], v[16:17] op_sel:[0,1,0]
	v_pk_fma_f32 v[16:17], v[4:5], v[188:189], v[16:17] op_sel_hi:[1,0,1]
	v_pk_fma_f32 v[16:17], v[6:7], v[188:189], v[16:17] op_sel:[0,1,0]
	v_pk_fma_f32 v[16:17], v[8:9], v[190:191], v[16:17] op_sel_hi:[1,0,1]
	v_pk_fma_f32 v[16:17], v[10:11], v[190:191], v[16:17] op_sel:[0,1,0]
	v_pk_fma_f32 v[16:17], v[12:13], v[192:193], v[16:17] op_sel_hi:[1,0,1]
	v_pk_fma_f32 v[16:17], v[14:15], v[192:193], v[16:17] op_sel:[0,1,0]
	v_pk_mul_f32 v[0:1], v[0:1], v[194:195] op_sel_hi:[1,0]
	v_pk_mul_f32 v[2:3], v[2:3], v[194:195] op_sel:[0,1]
	v_add_f32_dpp v16, v16, v16 quad_perm:[1,0,3,2] row_mask:0xf bank_mask:0xf bound_ctrl:1
	v_add_f32_dpp v17, v17, v17 quad_perm:[1,0,3,2] row_mask:0xf bank_mask:0xf bound_ctrl:1
	v_pk_mul_f32 v[4:5], v[4:5], v[196:197] op_sel_hi:[1,0]
	v_pk_mul_f32 v[6:7], v[6:7], v[196:197] op_sel:[0,1]
	v_add_f32_dpp v16, v16, v16 quad_perm:[2,3,0,1] row_mask:0xf bank_mask:0xf bound_ctrl:1
	v_add_f32_dpp v17, v17, v17 quad_perm:[2,3,0,1] row_mask:0xf bank_mask:0xf bound_ctrl:1
	v_pk_mul_f32 v[8:9], v[8:9], v[198:199] op_sel_hi:[1,0]
	v_pk_mul_f32 v[10:11], v[10:11], v[198:199] op_sel:[0,1]
	v_add_f32_dpp v228, v16, v16 row_half_mirror row_mask:0xf bank_mask:0xf bound_ctrl:1
	v_add_f32_dpp v229, v17, v17 row_half_mirror row_mask:0xf bank_mask:0xf bound_ctrl:1
	v_pk_mul_f32 v[12:13], v[12:13], v[200:201] op_sel_hi:[1,0]
	v_pk_mul_f32 v[14:15], v[14:15], v[200:201] op_sel:[0,1]
	v_pk_fma_f32 v[0:1], v[226:227], v[210:211], v[0:1] op_sel_hi:[1,0,1]
	v_pk_fma_f32 v[2:3], v[226:227], v[210:211], v[2:3] op_sel:[0,1,0]
	v_pk_fma_f32 v[4:5], v[226:227], v[212:213], v[4:5] op_sel_hi:[1,0,1]
	v_pk_fma_f32 v[6:7], v[226:227], v[212:213], v[6:7] op_sel:[0,1,0]
	v_pk_fma_f32 v[8:9], v[226:227], v[214:215], v[8:9] op_sel_hi:[1,0,1]
	v_pk_fma_f32 v[10:11], v[226:227], v[214:215], v[10:11] op_sel:[0,1,0]
	v_pk_fma_f32 v[12:13], v[226:227], v[216:217], v[12:13] op_sel_hi:[1,0,1]
	v_pk_fma_f32 v[14:15], v[226:227], v[216:217], v[14:15] op_sel:[0,1,0]
	v_pk_fma_f32 v[0:1], v[228:229], v[202:203], v[0:1] op_sel_hi:[1,0,1]
	v_pk_fma_f32 v[2:3], v[228:229], v[202:203], v[2:3] op_sel:[0,1,0]
	v_pk_fma_f32 v[4:5], v[228:229], v[204:205], v[4:5] op_sel_hi:[1,0,1]
	v_pk_fma_f32 v[6:7], v[228:229], v[204:205], v[6:7] op_sel:[0,1,0]
	v_pk_fma_f32 v[8:9], v[228:229], v[206:207], v[8:9] op_sel_hi:[1,0,1]
	v_pk_fma_f32 v[10:11], v[228:229], v[206:207], v[10:11] op_sel:[0,1,0]
	v_pk_fma_f32 v[12:13], v[228:229], v[208:209], v[12:13] op_sel_hi:[1,0,1]
	v_pk_fma_f32 v[14:15], v[228:229], v[208:209], v[14:15] op_sel:[0,1,0]
	v_pk_mul_f32 v[116:117], v[0:1], v[218:219] op_sel_hi:[1,0]
	v_pk_fma_f32 v[116:117], v[2:3], v[218:219], v[116:117] op_sel:[0,1,0]
	v_pk_fma_f32 v[116:117], v[4:5], v[220:221], v[116:117] op_sel_hi:[1,0,1]
	v_pk_fma_f32 v[116:117], v[6:7], v[220:221], v[116:117] op_sel:[0,1,0]
	v_pk_fma_f32 v[116:117], v[8:9], v[222:223], v[116:117] op_sel_hi:[1,0,1]
	v_pk_fma_f32 v[116:117], v[10:11], v[222:223], v[116:117] op_sel:[0,1,0]
	v_pk_fma_f32 v[116:117], v[12:13], v[224:225], v[116:117] op_sel_hi:[1,0,1]
	v_pk_fma_f32 v[116:117], v[14:15], v[224:225], v[116:117] op_sel:[0,1,0]
	ds_read_b128 v[186:189], v20 offset:10752
	ds_read_b128 v[190:193], v20 offset:10768
	v_add_f32_dpp v240, v116, v116 quad_perm:[1,0,3,2] row_mask:0xf bank_mask:0xf bound_ctrl:1
	v_add_f32_dpp v241, v117, v117 quad_perm:[1,0,3,2] row_mask:0xf bank_mask:0xf bound_ctrl:1
	ds_read_b128 v[194:197], v20 offset:11008
	v_add_f32_dpp v240, v240, v240 quad_perm:[2,3,0,1] row_mask:0xf bank_mask:0xf bound_ctrl:1
	v_add_f32_dpp v241, v241, v241 quad_perm:[2,3,0,1] row_mask:0xf bank_mask:0xf bound_ctrl:1
	ds_read_b128 v[198:201], v20 offset:11024
	v_add_f32_dpp v240, v240, v240 row_half_mirror row_mask:0xf bank_mask:0xf bound_ctrl:1
	v_add_f32_dpp v241, v241, v241 row_half_mirror row_mask:0xf bank_mask:0xf bound_ctrl:1
	ds_read_b128 v[202:205], v20 offset:11264
	ds_read_b128 v[206:209], v20 offset:11280
	ds_read_b128 v[210:213], v20 offset:11520
	ds_read_b128 v[214:217], v20 offset:11536
	ds_read_b128 v[218:221], v20 offset:11776
	ds_read_b128 v[222:225], v20 offset:11792
	ds_read_b64 v[226:227], v22 offset:12032
	ds_write_b64 v21, v[240:241] offset:1280
	s_waitcnt lgkmcnt(12)
; DEV float reduce8_dpp(float v) { v += DPPF(v, 0xB1); v += DPPF(v, 0x4E); v += DPPF(v, 0x141); return v; }
;     ...
;                     const float* bs = base0 + tok * 384;
;                     const f32x4 a0 = *(const f32x4*)bs, a1 = *(const f32x4*)(bs + 4);
;                     const f32x4 w0 = *(const f32x4*)(bs + 64), w1 = *(const f32x4*)(bs + 68);
;                     const f32x4 b0 = *(const f32x4*)(bs + 128), b1 = *(const f32x4*)(bs + 132);
;                     const f32x4 k0 = *(const f32x4*)(bs + 192), k1 = *(const f32x4*)(bs + 196);
;                     const f32x4 r0 = *(const f32x4*)(bs + 256), r1 = *(const f32x4*)(bs + 260);
;                     const f32x2 vv = *(const f32x2*)(op + (size_t)(buf * 32 + tok) * 384 + 320 + 2 * vp);
;                     const f32x2 av[4] = {(f32x2){a0[0], a0[1]}, (f32x2){a0[2], a0[3]}, (f32x2){a1[0], a1[1]}, (f32x2){a1[2], a1[3]}};
;                     const f32x2 wv[4] = {(f32x2){w0[0], w0[1]}, (f32x2){w0[2], w0[3]}, (f32x2){w1[0], w1[1]}, (f32x2){w1[2], w1[3]}};
;                     const f32x2 bv[4] = {(f32x2){b0[0], b0[1]}, (f32x2){b0[2], b0[3]}, (f32x2){b1[0], b1[1]}, (f32x2){b1[2], b1[3]}};
;                     const f32x2 kv[4] = {(f32x2){k0[0], k0[1]}, (f32x2){k0[2], k0[3]}, (f32x2){k1[0], k1[1]}, (f32x2){k1[2], k1[3]}};
;                     const f32x2 rv[4] = {(f32x2){r0[0], r0[1]}, (f32x2){r0[2], r0[3]}, (f32x2){r1[0], r1[1]}, (f32x2){r1[2], r1[3]}};
;                     float yo[2];
; #pragma unroll
;                     for (int i = 0; i < 2; ++i) {
;                         f32x2 sa2 = st[i][0] * av[0]; sa2 += st[i][1] * av[1]; sa2 += st[i][2] * av[2]; sa2 += st[i][3] * av[3];
;                         const float sa = reduce8_dpp(sa2[0] + sa2[1]);
;                         const float vi = vv[i];
;                         f32x2 y2 = (f32x2){0.f, 0.f};
; #pragma unroll
;                         for (int j = 0; j < 4; ++j) { st[i][j] = st[i][j] * wv[j] + sa * bv[j] + vi * kv[j]; y2 += st[i][j] * rv[j]; }
;                         yo[i] = reduce8_dpp(y2[0] + y2[1]);
;                     }
;                     if (kq == 0) *(f32x2*)(yb + tok * 64) = (f32x2){yo[0], yo[1]};
	v_pk_mul_f32 v[16:17], v[0:1], v[24:25] op_sel_hi:[1,0]
	v_pk_fma_f32 v[16:17], v[2:3], v[24:25], v[16:17] op_sel:[0,1,0]
	v_pk_fma_f32 v[16:17], v[4:5], v[26:27], v[16:17] op_sel_hi:[1,0,1]
	v_pk_fma_f32 v[16:17], v[6:7], v[26:27], v[16:17] op_sel:[0,1,0]
	v_pk_fma_f32 v[16:17], v[8:9], v[28:29], v[16:17] op_sel_hi:[1,0,1]
	v_pk_fma_f32 v[16:17], v[10:11], v[28:29], v[16:17] op_sel:[0,1,0]
	v_pk_fma_f32 v[16:17], v[12:13], v[30:31], v[16:17] op_sel_hi:[1,0,1]
	v_pk_fma_f32 v[16:17], v[14:15], v[30:31], v[16:17] op_sel:[0,1,0]
	v_pk_mul_f32 v[0:1], v[0:1], v[32:33] op_sel_hi:[1,0]
	v_pk_mul_f32 v[2:3], v[2:3], v[32:33] op_sel:[0,1]
	v_add_f32_dpp v16, v16, v16 quad_perm:[1,0,3,2] row_mask:0xf bank_mask:0xf bound_ctrl:1
	v_add_f32_dpp v17, v17, v17 quad_perm:[1,0,3,2] row_mask:0xf bank_mask:0xf bound_ctrl:1
	v_pk_mul_f32 v[4:5], v[4:5], v[34:35] op_sel_hi:[1,0]
	v_pk_mul_f32 v[6:7], v[6:7], v[34:35] op_sel:[0,1]
	v_add_f32_dpp v16, v16, v16 quad_perm:[2,3,0,1] row_mask:0xf bank_mask:0xf bound_ctrl:1
	v_add_f32_dpp v17, v17, v17 quad_perm:[2,3,0,1] row_mask:0xf bank_mask:0xf bound_ctrl:1
	v_pk_mul_f32 v[8:9], v[8:9], v[36:37] op_sel_hi:[1,0]
	v_pk_mul_f32 v[10:11], v[10:11], v[36:37] op_sel:[0,1]
	v_add_f32_dpp v228, v16, v16 row_half_mirror row_mask:0xf bank_mask:0xf bound_ctrl:1
	v_add_f32_dpp v229, v17, v17 row_half_mirror row_mask:0xf bank_mask:0xf bound_ctrl:1
	v_pk_mul_f32 v[12:13], v[12:13], v[38:39] op_sel_hi:[1,0]
	v_pk_mul_f32 v[14:15], v[14:15], v[38:39] op_sel:[0,1]
	v_pk_fma_f32 v[0:1], v[64:65], v[48:49], v[0:1] op_sel_hi:[1,0,1]
	v_pk_fma_f32 v[2:3], v[64:65], v[48:49], v[2:3] op_sel:[0,1,0]
	v_pk_fma_f32 v[4:5], v[64:65], v[50:51], v[4:5] op_sel_hi:[1,0,1]
	v_pk_fma_f32 v[6:7], v[64:65], v[50:51], v[6:7] op_sel:[0,1,0]
	v_pk_fma_f32 v[8:9], v[64:65], v[52:53], v[8:9] op_sel_hi:[1,0,1]
	v_pk_fma_f32 v[10:11], v[64:65], v[52:53], v[10:11] op_sel:[0,1,0]
	v_pk_fma_f32 v[12:13], v[64:65], v[54:55], v[12:13] op_sel_hi:[1,0,1]
	v_pk_fma_f32 v[14:15], v[64:65], v[54:55], v[14:15] op_sel:[0,1,0]
	v_pk_fma_f32 v[0:1], v[228:229], v[40:41], v[0:1] op_sel_hi:[1,0,1]
	v_pk_fma_f32 v[2:3], v[228:229], v[40:41], v[2:3] op_sel:[0,1,0]
	v_pk_fma_f32 v[4:5], v[228:229], v[42:43], v[4:5] op_sel_hi:[1,0,1]
	v_pk_fma_f32 v[6:7], v[228:229], v[42:43], v[6:7] op_sel:[0,1,0]
	v_pk_fma_f32 v[8:9], v[228:229], v[44:45], v[8:9] op_sel_hi:[1,0,1]
	v_pk_fma_f32 v[10:11], v[228:229], v[44:45], v[10:11] op_sel:[0,1,0]
	v_pk_fma_f32 v[12:13], v[228:229], v[46:47], v[12:13] op_sel_hi:[1,0,1]
	v_pk_fma_f32 v[14:15], v[228:229], v[46:47], v[14:15] op_sel:[0,1,0]
	v_pk_mul_f32 v[116:117], v[0:1], v[56:57] op_sel_hi:[1,0]
	v_pk_fma_f32 v[116:117], v[2:3], v[56:57], v[116:117] op_sel:[0,1,0]
	v_pk_fma_f32 v[116:117], v[4:5], v[58:59], v[116:117] op_sel_hi:[1,0,1]
	v_pk_fma_f32 v[116:117], v[6:7], v[58:59], v[116:117] op_sel:[0,1,0]
	v_pk_fma_f32 v[116:117], v[8:9], v[60:61], v[116:117] op_sel_hi:[1,0,1]
	v_pk_fma_f32 v[116:117], v[10:11], v[60:61], v[116:117] op_sel:[0,1,0]
	v_pk_fma_f32 v[116:117], v[12:13], v[62:63], v[116:117] op_sel_hi:[1,0,1]
	v_pk_fma_f32 v[116:117], v[14:15], v[62:63], v[116:117] op_sel:[0,1,0]
	ds_read_b128 v[24:27], v20 offset:12288
	ds_read_b128 v[28:31], v20 offset:12304
	v_add_f32_dpp v240, v116, v116 quad_perm:[1,0,3,2] row_mask:0xf bank_mask:0xf bound_ctrl:1
	v_add_f32_dpp v241, v117, v117 quad_perm:[1,0,3,2] row_mask:0xf bank_mask:0xf bound_ctrl:1
	ds_read_b128 v[32:35], v20 offset:12544
	v_add_f32_dpp v240, v240, v240 quad_perm:[2,3,0,1] row_mask:0xf bank_mask:0xf bound_ctrl:1
	v_add_f32_dpp v241, v241, v241 quad_perm:[2,3,0,1] row_mask:0xf bank_mask:0xf bound_ctrl:1
	ds_read_b128 v[36:39], v20 offset:12560
	v_add_f32_dpp v240, v240, v240 row_half_mirror row_mask:0xf bank_mask:0xf bound_ctrl:1
	v_add_f32_dpp v241, v241, v241 row_half_mirror row_mask:0xf bank_mask:0xf bound_ctrl:1
	ds_read_b128 v[40:43], v20 offset:12800
	ds_read_b128 v[44:47], v20 offset:12816
	ds_read_b128 v[48:51], v20 offset:13056
	ds_read_b128 v[52:55], v20 offset:13072
	ds_read_b128 v[56:59], v20 offset:13312
	ds_read_b128 v[60:63], v20 offset:13328
	ds_read_b64 v[64:65], v22 offset:13568
	ds_write_b64 v21, v[240:241] offset:1536
	s_waitcnt lgkmcnt(12)
	v_pk_mul_f32 v[16:17], v[0:1], v[186:187] op_sel_hi:[1,0]
	v_pk_fma_f32 v[16:17], v[2:3], v[186:187], v[16:17] op_sel:[0,1,0]
	v_pk_fma_f32 v[16:17], v[4:5], v[188:189], v[16:17] op_sel_hi:[1,0,1]
	v_pk_fma_f32 v[16:17], v[6:7], v[188:189], v[16:17] op_sel:[0,1,0]
	v_pk_fma_f32 v[16:17], v[8:9], v[190:191], v[16:17] op_sel_hi:[1,0,1]
	v_pk_fma_f32 v[16:17], v[10:11], v[190:191], v[16:17] op_sel:[0,1,0]
	v_pk_fma_f32 v[16:17], v[12:13], v[192:193], v[16:17] op_sel_hi:[1,0,1]
	v_pk_fma_f32 v[16:17], v[14:15], v[192:193], v[16:17] op_sel:[0,1,0]
	v_pk_mul_f32 v[0:1], v[0:1], v[194:195] op_sel_hi:[1,0]
	v_pk_mul_f32 v[2:3], v[2:3], v[194:195] op_sel:[0,1]
	v_add_f32_dpp v16, v16, v16 quad_perm:[1,0,3,2] row_mask:0xf bank_mask:0xf bound_ctrl:1
	v_add_f32_dpp v17, v17, v17 quad_perm:[1,0,3,2] row_mask:0xf bank_mask:0xf bound_ctrl:1
	v_pk_mul_f32 v[4:5], v[4:5], v[196:197] op_sel_hi:[1,0]
	v_pk_mul_f32 v[6:7], v[6:7], v[196:197] op_sel:[0,1]
	v_add_f32_dpp v16, v16, v16 quad_perm:[2,3,0,1] row_mask:0xf bank_mask:0xf bound_ctrl:1
	v_add_f32_dpp v17, v17, v17 quad_perm:[2,3,0,1] row_mask:0xf bank_mask:0xf bound_ctrl:1
	v_pk_mul_f32 v[8:9], v[8:9], v[198:199] op_sel_hi:[1,0]
	v_pk_mul_f32 v[10:11], v[10:11], v[198:199] op_sel:[0,1]
	v_add_f32_dpp v228, v16, v16 row_half_mirror row_mask:0xf bank_mask:0xf bound_ctrl:1
	v_add_f32_dpp v229, v17, v17 row_half_mirror row_mask:0xf bank_mask:0xf bound_ctrl:1
; DEV float reduce8_dpp(float v) { v += DPPF(v, 0xB1); v += DPPF(v, 0x4E); v += DPPF(v, 0x141); return v; }
;     ...
;                     const float* bs = base0 + tok * 384;
;                     const f32x4 a0 = *(const f32x4*)bs, a1 = *(const f32x4*)(bs + 4);
;                     const f32x4 w0 = *(const f32x4*)(bs + 64), w1 = *(const f32x4*)(bs + 68);
;                     const f32x4 b0 = *(const f32x4*)(bs + 128), b1 = *(const f32x4*)(bs + 132);
;                     const f32x4 k0 = *(const f32x4*)(bs + 192), k1 = *(const f32x4*)(bs + 196);
;                     const f32x4 r0 = *(const f32x4*)(bs + 256), r1 = *(const f32x4*)(bs + 260);
;                     const f32x2 vv = *(const f32x2*)(op + (size_t)(buf * 32 + tok) * 384 + 320 + 2 * vp);
;                     const f32x2 av[4] = {(f32x2){a0[0], a0[1]}, (f32x2){a0[2], a0[3]}, (f32x2){a1[0], a1[1]}, (f32x2){a1[2], a1[3]}};
;                     const f32x2 wv[4] = {(f32x2){w0[0], w0[1]}, (f32x2){w0[2], w0[3]}, (f32x2){w1[0], w1[1]}, (f32x2){w1[2], w1[3]}};
;                     const f32x2 bv[4] = {(f32x2){b0[0], b0[1]}, (f32x2){b0[2], b0[3]}, (f32x2){b1[0], b1[1]}, (f32x2){b1[2], b1[3]}};
;                     const f32x2 kv[4] = {(f32x2){k0[0], k0[1]}, (f32x2){k0[2], k0[3]}, (f32x2){k1[0], k1[1]}, (f32x2){k1[2], k1[3]}};
;                     const f32x2 rv[4] = {(f32x2){r0[0], r0[1]}, (f32x2){r0[2], r0[3]}, (f32x2){r1[0], r1[1]}, (f32x2){r1[2], r1[3]}};
;                     float yo[2];
; #pragma unroll
;                     for (int i = 0; i < 2; ++i) {
;                         f32x2 sa2 = st[i][0] * av[0]; sa2 += st[i][1] * av[1]; sa2 += st[i][2] * av[2]; sa2 += st[i][3] * av[3];
;                         const float sa = reduce8_dpp(sa2[0] + sa2[1]);
;                         const float vi = vv[i];
;                         f32x2 y2 = (f32x2){0.f, 0.f};
; #pragma unroll
;                         for (int j = 0; j < 4; ++j) { st[i][j] = st[i][j] * wv[j] + sa * bv[j] + vi * kv[j]; y2 += st[i][j] * rv[j]; }
;                         yo[i] = reduce8_dpp(y2[0] + y2[1]);
;                     }
;                     if (kq == 0) *(f32x2*)(yb + tok * 64) = (f32x2){yo[0], yo[1]};
	v_pk_mul_f32 v[12:13], v[12:13], v[200:201] op_sel_hi:[1,0]
	v_pk_mul_f32 v[14:15], v[14:15], v[200:201] op_sel:[0,1]
	v_pk_fma_f32 v[0:1], v[226:227], v[210:211], v[0:1] op_sel_hi:[1,0,1]
	v_pk_fma_f32 v[2:3], v[226:227], v[210:211], v[2:3] op_sel:[0,1,0]
	v_pk_fma_f32 v[4:5], v[226:227], v[212:213], v[4:5] op_sel_hi:[1,0,1]
	v_pk_fma_f32 v[6:7], v[226:227], v[212:213], v[6:7] op_sel:[0,1,0]
	v_pk_fma_f32 v[8:9], v[226:227], v[214:215], v[8:9] op_sel_hi:[1,0,1]
	v_pk_fma_f32 v[10:11], v[226:227], v[214:215], v[10:11] op_sel:[0,1,0]
	v_pk_fma_f32 v[12:13], v[226:227], v[216:217], v[12:13] op_sel_hi:[1,0,1]
	v_pk_fma_f32 v[14:15], v[226:227], v[216:217], v[14:15] op_sel:[0,1,0]
	v_pk_fma_f32 v[0:1], v[228:229], v[202:203], v[0:1] op_sel_hi:[1,0,1]
	v_pk_fma_f32 v[2:3], v[228:229], v[202:203], v[2:3] op_sel:[0,1,0]
	v_pk_fma_f32 v[4:5], v[228:229], v[204:205], v[4:5] op_sel_hi:[1,0,1]
	v_pk_fma_f32 v[6:7], v[228:229], v[204:205], v[6:7] op_sel:[0,1,0]
	v_pk_fma_f32 v[8:9], v[228:229], v[206:207], v[8:9] op_sel_hi:[1,0,1]
	v_pk_fma_f32 v[10:11], v[228:229], v[206:207], v[10:11] op_sel:[0,1,0]
	v_pk_fma_f32 v[12:13], v[228:229], v[208:209], v[12:13] op_sel_hi:[1,0,1]
	v_pk_fma_f32 v[14:15], v[228:229], v[208:209], v[14:15] op_sel:[0,1,0]
	v_pk_mul_f32 v[116:117], v[0:1], v[218:219] op_sel_hi:[1,0]
	v_pk_fma_f32 v[116:117], v[2:3], v[218:219], v[116:117] op_sel:[0,1,0]
	v_pk_fma_f32 v[116:117], v[4:5], v[220:221], v[116:117] op_sel_hi:[1,0,1]
	v_pk_fma_f32 v[116:117], v[6:7], v[220:221], v[116:117] op_sel:[0,1,0]
	v_pk_fma_f32 v[116:117], v[8:9], v[222:223], v[116:117] op_sel_hi:[1,0,1]
	v_pk_fma_f32 v[116:117], v[10:11], v[222:223], v[116:117] op_sel:[0,1,0]
	v_pk_fma_f32 v[116:117], v[12:13], v[224:225], v[116:117] op_sel_hi:[1,0,1]
	v_pk_fma_f32 v[116:117], v[14:15], v[224:225], v[116:117] op_sel:[0,1,0]
	ds_read_b128 v[186:189], v20 offset:13824
	ds_read_b128 v[190:193], v20 offset:13840
	v_add_f32_dpp v240, v116, v116 quad_perm:[1,0,3,2] row_mask:0xf bank_mask:0xf bound_ctrl:1
	v_add_f32_dpp v241, v117, v117 quad_perm:[1,0,3,2] row_mask:0xf bank_mask:0xf bound_ctrl:1
	ds_read_b128 v[194:197], v20 offset:14080
	v_add_f32_dpp v240, v240, v240 quad_perm:[2,3,0,1] row_mask:0xf bank_mask:0xf bound_ctrl:1
	v_add_f32_dpp v241, v241, v241 quad_perm:[2,3,0,1] row_mask:0xf bank_mask:0xf bound_ctrl:1
	ds_read_b128 v[198:201], v20 offset:14096
	v_add_f32_dpp v240, v240, v240 row_half_mirror row_mask:0xf bank_mask:0xf bound_ctrl:1
	v_add_f32_dpp v241, v241, v241 row_half_mirror row_mask:0xf bank_mask:0xf bound_ctrl:1
	ds_read_b128 v[202:205], v20 offset:14336
	ds_read_b128 v[206:209], v20 offset:14352
	ds_read_b128 v[210:213], v20 offset:14592
	ds_read_b128 v[214:217], v20 offset:14608
	ds_read_b128 v[218:221], v20 offset:14848
	ds_read_b128 v[222:225], v20 offset:14864
	ds_read_b64 v[226:227], v22 offset:15104
	ds_write_b64 v21, v[240:241] offset:1792
	s_waitcnt lgkmcnt(12)
	v_pk_mul_f32 v[16:17], v[0:1], v[24:25] op_sel_hi:[1,0]
	v_pk_fma_f32 v[16:17], v[2:3], v[24:25], v[16:17] op_sel:[0,1,0]
	v_pk_fma_f32 v[16:17], v[4:5], v[26:27], v[16:17] op_sel_hi:[1,0,1]
	v_pk_fma_f32 v[16:17], v[6:7], v[26:27], v[16:17] op_sel:[0,1,0]
	v_pk_fma_f32 v[16:17], v[8:9], v[28:29], v[16:17] op_sel_hi:[1,0,1]
	v_pk_fma_f32 v[16:17], v[10:11], v[28:29], v[16:17] op_sel:[0,1,0]
	v_pk_fma_f32 v[16:17], v[12:13], v[30:31], v[16:17] op_sel_hi:[1,0,1]
	v_pk_fma_f32 v[16:17], v[14:15], v[30:31], v[16:17] op_sel:[0,1,0]
	v_pk_mul_f32 v[0:1], v[0:1], v[32:33] op_sel_hi:[1,0]
	v_pk_mul_f32 v[2:3], v[2:3], v[32:33] op_sel:[0,1]
	v_add_f32_dpp v16, v16, v16 quad_perm:[1,0,3,2] row_mask:0xf bank_mask:0xf bound_ctrl:1
	v_add_f32_dpp v17, v17, v17 quad_perm:[1,0,3,2] row_mask:0xf bank_mask:0xf bound_ctrl:1
	v_pk_mul_f32 v[4:5], v[4:5], v[34:35] op_sel_hi:[1,0]
	v_pk_mul_f32 v[6:7], v[6:7], v[34:35] op_sel:[0,1]
	v_add_f32_dpp v16, v16, v16 quad_perm:[2,3,0,1] row_mask:0xf bank_mask:0xf bound_ctrl:1
	v_add_f32_dpp v17, v17, v17 quad_perm:[2,3,0,1] row_mask:0xf bank_mask:0xf bound_ctrl:1
	v_pk_mul_f32 v[8:9], v[8:9], v[36:37] op_sel_hi:[1,0]
	v_pk_mul_f32 v[10:11], v[10:11], v[36:37] op_sel:[0,1]
	v_add_f32_dpp v228, v16, v16 row_half_mirror row_mask:0xf bank_mask:0xf bound_ctrl:1
	v_add_f32_dpp v229, v17, v17 row_half_mirror row_mask:0xf bank_mask:0xf bound_ctrl:1
	v_pk_mul_f32 v[12:13], v[12:13], v[38:39] op_sel_hi:[1,0]
	v_pk_mul_f32 v[14:15], v[14:15], v[38:39] op_sel:[0,1]
	v_pk_fma_f32 v[0:1], v[64:65], v[48:49], v[0:1] op_sel_hi:[1,0,1]
	v_pk_fma_f32 v[2:3], v[64:65], v[48:49], v[2:3] op_sel:[0,1,0]
	v_pk_fma_f32 v[4:5], v[64:65], v[50:51], v[4:5] op_sel_hi:[1,0,1]
	v_pk_fma_f32 v[6:7], v[64:65], v[50:51], v[6:7] op_sel:[0,1,0]
	v_pk_fma_f32 v[8:9], v[64:65], v[52:53], v[8:9] op_sel_hi:[1,0,1]
	v_pk_fma_f32 v[10:11], v[64:65], v[52:53], v[10:11] op_sel:[0,1,0]
	v_pk_fma_f32 v[12:13], v[64:65], v[54:55], v[12:13] op_sel_hi:[1,0,1]
	v_pk_fma_f32 v[14:15], v[64:65], v[54:55], v[14:15] op_sel:[0,1,0]
	v_pk_fma_f32 v[0:1], v[228:229], v[40:41], v[0:1] op_sel_hi:[1,0,1]
	v_pk_fma_f32 v[2:3], v[228:229], v[40:41], v[2:3] op_sel:[0,1,0]
	v_pk_fma_f32 v[4:5], v[228:229], v[42:43], v[4:5] op_sel_hi:[1,0,1]
	v_pk_fma_f32 v[6:7], v[228:229], v[42:43], v[6:7] op_sel:[0,1,0]
	v_pk_fma_f32 v[8:9], v[228:229], v[44:45], v[8:9] op_sel_hi:[1,0,1]
	v_pk_fma_f32 v[10:11], v[228:229], v[44:45], v[10:11] op_sel:[0,1,0]
	v_pk_fma_f32 v[12:13], v[228:229], v[46:47], v[12:13] op_sel_hi:[1,0,1]
	v_pk_fma_f32 v[14:15], v[228:229], v[46:47], v[14:15] op_sel:[0,1,0]
	v_pk_mul_f32 v[116:117], v[0:1], v[56:57] op_sel_hi:[1,0]
	v_pk_fma_f32 v[116:117], v[2:3], v[56:57], v[116:117] op_sel:[0,1,0]
; DEV float reduce8_dpp(float v) { v += DPPF(v, 0xB1); v += DPPF(v, 0x4E); v += DPPF(v, 0x141); return v; }
;     ...
;                     const float* bs = base0 + tok * 384;
;                     const f32x4 a0 = *(const f32x4*)bs, a1 = *(const f32x4*)(bs + 4);
;                     const f32x4 w0 = *(const f32x4*)(bs + 64), w1 = *(const f32x4*)(bs + 68);
;                     const f32x4 b0 = *(const f32x4*)(bs + 128), b1 = *(const f32x4*)(bs + 132);
;                     const f32x4 k0 = *(const f32x4*)(bs + 192), k1 = *(const f32x4*)(bs + 196);
;                     const f32x4 r0 = *(const f32x4*)(bs + 256), r1 = *(const f32x4*)(bs + 260);
;                     const f32x2 vv = *(const f32x2*)(op + (size_t)(buf * 32 + tok) * 384 + 320 + 2 * vp);
;                     const f32x2 av[4] = {(f32x2){a0[0], a0[1]}, (f32x2){a0[2], a0[3]}, (f32x2){a1[0], a1[1]}, (f32x2){a1[2], a1[3]}};
;                     const f32x2 wv[4] = {(f32x2){w0[0], w0[1]}, (f32x2){w0[2], w0[3]}, (f32x2){w1[0], w1[1]}, (f32x2){w1[2], w1[3]}};
;                     const f32x2 bv[4] = {(f32x2){b0[0], b0[1]}, (f32x2){b0[2], b0[3]}, (f32x2){b1[0], b1[1]}, (f32x2){b1[2], b1[3]}};
;                     const f32x2 kv[4] = {(f32x2){k0[0], k0[1]}, (f32x2){k0[2], k0[3]}, (f32x2){k1[0], k1[1]}, (f32x2){k1[2], k1[3]}};
;                     const f32x2 rv[4] = {(f32x2){r0[0], r0[1]}, (f32x2){r0[2], r0[3]}, (f32x2){r1[0], r1[1]}, (f32x2){r1[2], r1[3]}};
;                     float yo[2];
; #pragma unroll
;                     for (int i = 0; i < 2; ++i) {
;                         f32x2 sa2 = st[i][0] * av[0]; sa2 += st[i][1] * av[1]; sa2 += st[i][2] * av[2]; sa2 += st[i][3] * av[3];
;                         const float sa = reduce8_dpp(sa2[0] + sa2[1]);
;                         const float vi = vv[i];
;                         f32x2 y2 = (f32x2){0.f, 0.f};
; #pragma unroll
;                         for (int j = 0; j < 4; ++j) { st[i][j] = st[i][j] * wv[j] + sa * bv[j] + vi * kv[j]; y2 += st[i][j] * rv[j]; }
;                         yo[i] = reduce8_dpp(y2[0] + y2[1]);
;                     }
;                     if (kq == 0) *(f32x2*)(yb + tok * 64) = (f32x2){yo[0], yo[1]};
	v_pk_fma_f32 v[116:117], v[4:5], v[58:59], v[116:117] op_sel_hi:[1,0,1]
	v_pk_fma_f32 v[116:117], v[6:7], v[58:59], v[116:117] op_sel:[0,1,0]
	v_pk_fma_f32 v[116:117], v[8:9], v[60:61], v[116:117] op_sel_hi:[1,0,1]
	v_pk_fma_f32 v[116:117], v[10:11], v[60:61], v[116:117] op_sel:[0,1,0]
	v_pk_fma_f32 v[116:117], v[12:13], v[62:63], v[116:117] op_sel_hi:[1,0,1]
	v_pk_fma_f32 v[116:117], v[14:15], v[62:63], v[116:117] op_sel:[0,1,0]
	ds_read_b128 v[24:27], v20 offset:15360
	ds_read_b128 v[28:31], v20 offset:15376
	v_add_f32_dpp v240, v116, v116 quad_perm:[1,0,3,2] row_mask:0xf bank_mask:0xf bound_ctrl:1
	v_add_f32_dpp v241, v117, v117 quad_perm:[1,0,3,2] row_mask:0xf bank_mask:0xf bound_ctrl:1
	ds_read_b128 v[32:35], v20 offset:15616
	v_add_f32_dpp v240, v240, v240 quad_perm:[2,3,0,1] row_mask:0xf bank_mask:0xf bound_ctrl:1
	v_add_f32_dpp v241, v241, v241 quad_perm:[2,3,0,1] row_mask:0xf bank_mask:0xf bound_ctrl:1
	ds_read_b128 v[36:39], v20 offset:15632
	v_add_f32_dpp v240, v240, v240 row_half_mirror row_mask:0xf bank_mask:0xf bound_ctrl:1
	v_add_f32_dpp v241, v241, v241 row_half_mirror row_mask:0xf bank_mask:0xf bound_ctrl:1
	ds_read_b128 v[40:43], v20 offset:15872
	ds_read_b128 v[44:47], v20 offset:15888
	ds_read_b128 v[48:51], v20 offset:16128
	ds_read_b128 v[52:55], v20 offset:16144
	ds_read_b128 v[56:59], v20 offset:16384
	ds_read_b128 v[60:63], v20 offset:16400
	ds_read_b64 v[64:65], v22 offset:16640
	ds_write_b64 v21, v[240:241] offset:2048
	s_waitcnt lgkmcnt(12)
	v_pk_mul_f32 v[16:17], v[0:1], v[186:187] op_sel_hi:[1,0]
	v_pk_fma_f32 v[16:17], v[2:3], v[186:187], v[16:17] op_sel:[0,1,0]
	v_pk_fma_f32 v[16:17], v[4:5], v[188:189], v[16:17] op_sel_hi:[1,0,1]
	v_pk_fma_f32 v[16:17], v[6:7], v[188:189], v[16:17] op_sel:[0,1,0]
	v_pk_fma_f32 v[16:17], v[8:9], v[190:191], v[16:17] op_sel_hi:[1,0,1]
	v_pk_fma_f32 v[16:17], v[10:11], v[190:191], v[16:17] op_sel:[0,1,0]
	v_pk_fma_f32 v[16:17], v[12:13], v[192:193], v[16:17] op_sel_hi:[1,0,1]
	v_pk_fma_f32 v[16:17], v[14:15], v[192:193], v[16:17] op_sel:[0,1,0]
	v_pk_mul_f32 v[0:1], v[0:1], v[194:195] op_sel_hi:[1,0]
	v_pk_mul_f32 v[2:3], v[2:3], v[194:195] op_sel:[0,1]
	v_add_f32_dpp v16, v16, v16 quad_perm:[1,0,3,2] row_mask:0xf bank_mask:0xf bound_ctrl:1
	v_add_f32_dpp v17, v17, v17 quad_perm:[1,0,3,2] row_mask:0xf bank_mask:0xf bound_ctrl:1
	v_pk_mul_f32 v[4:5], v[4:5], v[196:197] op_sel_hi:[1,0]
	v_pk_mul_f32 v[6:7], v[6:7], v[196:197] op_sel:[0,1]
	v_add_f32_dpp v16, v16, v16 quad_perm:[2,3,0,1] row_mask:0xf bank_mask:0xf bound_ctrl:1
	v_add_f32_dpp v17, v17, v17 quad_perm:[2,3,0,1] row_mask:0xf bank_mask:0xf bound_ctrl:1
	v_pk_mul_f32 v[8:9], v[8:9], v[198:199] op_sel_hi:[1,0]
	v_pk_mul_f32 v[10:11], v[10:11], v[198:199] op_sel:[0,1]
	v_add_f32_dpp v228, v16, v16 row_half_mirror row_mask:0xf bank_mask:0xf bound_ctrl:1
	v_add_f32_dpp v229, v17, v17 row_half_mirror row_mask:0xf bank_mask:0xf bound_ctrl:1
	v_pk_mul_f32 v[12:13], v[12:13], v[200:201] op_sel_hi:[1,0]
	v_pk_mul_f32 v[14:15], v[14:15], v[200:201] op_sel:[0,1]
	v_pk_fma_f32 v[0:1], v[226:227], v[210:211], v[0:1] op_sel_hi:[1,0,1]
	v_pk_fma_f32 v[2:3], v[226:227], v[210:211], v[2:3] op_sel:[0,1,0]
	v_pk_fma_f32 v[4:5], v[226:227], v[212:213], v[4:5] op_sel_hi:[1,0,1]
	v_pk_fma_f32 v[6:7], v[226:227], v[212:213], v[6:7] op_sel:[0,1,0]
	v_pk_fma_f32 v[8:9], v[226:227], v[214:215], v[8:9] op_sel_hi:[1,0,1]
	v_pk_fma_f32 v[10:11], v[226:227], v[214:215], v[10:11] op_sel:[0,1,0]
	v_pk_fma_f32 v[12:13], v[226:227], v[216:217], v[12:13] op_sel_hi:[1,0,1]
	v_pk_fma_f32 v[14:15], v[226:227], v[216:217], v[14:15] op_sel:[0,1,0]
	v_pk_fma_f32 v[0:1], v[228:229], v[202:203], v[0:1] op_sel_hi:[1,0,1]
	v_pk_fma_f32 v[2:3], v[228:229], v[202:203], v[2:3] op_sel:[0,1,0]
	v_pk_fma_f32 v[4:5], v[228:229], v[204:205], v[4:5] op_sel_hi:[1,0,1]
	v_pk_fma_f32 v[6:7], v[228:229], v[204:205], v[6:7] op_sel:[0,1,0]
	v_pk_fma_f32 v[8:9], v[228:229], v[206:207], v[8:9] op_sel_hi:[1,0,1]
	v_pk_fma_f32 v[10:11], v[228:229], v[206:207], v[10:11] op_sel:[0,1,0]
	v_pk_fma_f32 v[12:13], v[228:229], v[208:209], v[12:13] op_sel_hi:[1,0,1]
	v_pk_fma_f32 v[14:15], v[228:229], v[208:209], v[14:15] op_sel:[0,1,0]
	v_pk_mul_f32 v[116:117], v[0:1], v[218:219] op_sel_hi:[1,0]
	v_pk_fma_f32 v[116:117], v[2:3], v[218:219], v[116:117] op_sel:[0,1,0]
	v_pk_fma_f32 v[116:117], v[4:5], v[220:221], v[116:117] op_sel_hi:[1,0,1]
	v_pk_fma_f32 v[116:117], v[6:7], v[220:221], v[116:117] op_sel:[0,1,0]
	v_pk_fma_f32 v[116:117], v[8:9], v[222:223], v[116:117] op_sel_hi:[1,0,1]
	v_pk_fma_f32 v[116:117], v[10:11], v[222:223], v[116:117] op_sel:[0,1,0]
	v_pk_fma_f32 v[116:117], v[12:13], v[224:225], v[116:117] op_sel_hi:[1,0,1]
	v_pk_fma_f32 v[116:117], v[14:15], v[224:225], v[116:117] op_sel:[0,1,0]
	ds_read_b128 v[186:189], v20 offset:16896
	ds_read_b128 v[190:193], v20 offset:16912
	v_add_f32_dpp v240, v116, v116 quad_perm:[1,0,3,2] row_mask:0xf bank_mask:0xf bound_ctrl:1
	v_add_f32_dpp v241, v117, v117 quad_perm:[1,0,3,2] row_mask:0xf bank_mask:0xf bound_ctrl:1
	ds_read_b128 v[194:197], v20 offset:17152
	v_add_f32_dpp v240, v240, v240 quad_perm:[2,3,0,1] row_mask:0xf bank_mask:0xf bound_ctrl:1
	v_add_f32_dpp v241, v241, v241 quad_perm:[2,3,0,1] row_mask:0xf bank_mask:0xf bound_ctrl:1
	ds_read_b128 v[198:201], v20 offset:17168
	v_add_f32_dpp v240, v240, v240 row_half_mirror row_mask:0xf bank_mask:0xf bound_ctrl:1
	v_add_f32_dpp v241, v241, v241 row_half_mirror row_mask:0xf bank_mask:0xf bound_ctrl:1
	ds_read_b128 v[202:205], v20 offset:17408
	ds_read_b128 v[206:209], v20 offset:17424
	ds_read_b128 v[210:213], v20 offset:17664
	ds_read_b128 v[214:217], v20 offset:17680
	ds_read_b128 v[218:221], v20 offset:17920
	ds_read_b128 v[222:225], v20 offset:17936
	ds_read_b64 v[226:227], v22 offset:18176
	ds_write_b64 v21, v[240:241] offset:2304
	s_waitcnt lgkmcnt(12)
; DEV float reduce8_dpp(float v) { v += DPPF(v, 0xB1); v += DPPF(v, 0x4E); v += DPPF(v, 0x141); return v; }
;     ...
;                     const float* bs = base0 + tok * 384;
;                     const f32x4 a0 = *(const f32x4*)bs, a1 = *(const f32x4*)(bs + 4);
;                     const f32x4 w0 = *(const f32x4*)(bs + 64), w1 = *(const f32x4*)(bs + 68);
;                     const f32x4 b0 = *(const f32x4*)(bs + 128), b1 = *(const f32x4*)(bs + 132);
;                     const f32x4 k0 = *(const f32x4*)(bs + 192), k1 = *(const f32x4*)(bs + 196);
;                     const f32x4 r0 = *(const f32x4*)(bs + 256), r1 = *(const f32x4*)(bs + 260);
;                     const f32x2 vv = *(const f32x2*)(op + (size_t)(buf * 32 + tok) * 384 + 320 + 2 * vp);
;                     const f32x2 av[4] = {(f32x2){a0[0], a0[1]}, (f32x2){a0[2], a0[3]}, (f32x2){a1[0], a1[1]}, (f32x2){a1[2], a1[3]}};
;                     const f32x2 wv[4] = {(f32x2){w0[0], w0[1]}, (f32x2){w0[2], w0[3]}, (f32x2){w1[0], w1[1]}, (f32x2){w1[2], w1[3]}};
;                     const f32x2 bv[4] = {(f32x2){b0[0], b0[1]}, (f32x2){b0[2], b0[3]}, (f32x2){b1[0], b1[1]}, (f32x2){b1[2], b1[3]}};
;                     const f32x2 kv[4] = {(f32x2){k0[0], k0[1]}, (f32x2){k0[2], k0[3]}, (f32x2){k1[0], k1[1]}, (f32x2){k1[2], k1[3]}};
;                     const f32x2 rv[4] = {(f32x2){r0[0], r0[1]}, (f32x2){r0[2], r0[3]}, (f32x2){r1[0], r1[1]}, (f32x2){r1[2], r1[3]}};
;                     float yo[2];
; #pragma unroll
;                     for (int i = 0; i < 2; ++i) {
;                         f32x2 sa2 = st[i][0] * av[0]; sa2 += st[i][1] * av[1]; sa2 += st[i][2] * av[2]; sa2 += st[i][3] * av[3];
;                         const float sa = reduce8_dpp(sa2[0] + sa2[1]);
;                         const float vi = vv[i];
;                         f32x2 y2 = (f32x2){0.f, 0.f};
; #pragma unroll
;                         for (int j = 0; j < 4; ++j) { st[i][j] = st[i][j] * wv[j] + sa * bv[j] + vi * kv[j]; y2 += st[i][j] * rv[j]; }
;                         yo[i] = reduce8_dpp(y2[0] + y2[1]);
;                     }
;                     if (kq == 0) *(f32x2*)(yb + tok * 64) = (f32x2){yo[0], yo[1]};
	v_pk_mul_f32 v[16:17], v[0:1], v[24:25] op_sel_hi:[1,0]
	v_pk_fma_f32 v[16:17], v[2:3], v[24:25], v[16:17] op_sel:[0,1,0]
	v_pk_fma_f32 v[16:17], v[4:5], v[26:27], v[16:17] op_sel_hi:[1,0,1]
	v_pk_fma_f32 v[16:17], v[6:7], v[26:27], v[16:17] op_sel:[0,1,0]
	v_pk_fma_f32 v[16:17], v[8:9], v[28:29], v[16:17] op_sel_hi:[1,0,1]
	v_pk_fma_f32 v[16:17], v[10:11], v[28:29], v[16:17] op_sel:[0,1,0]
	v_pk_fma_f32 v[16:17], v[12:13], v[30:31], v[16:17] op_sel_hi:[1,0,1]
	v_pk_fma_f32 v[16:17], v[14:15], v[30:31], v[16:17] op_sel:[0,1,0]
	v_pk_mul_f32 v[0:1], v[0:1], v[32:33] op_sel_hi:[1,0]
	v_pk_mul_f32 v[2:3], v[2:3], v[32:33] op_sel:[0,1]
	v_add_f32_dpp v16, v16, v16 quad_perm:[1,0,3,2] row_mask:0xf bank_mask:0xf bound_ctrl:1
	v_add_f32_dpp v17, v17, v17 quad_perm:[1,0,3,2] row_mask:0xf bank_mask:0xf bound_ctrl:1
	v_pk_mul_f32 v[4:5], v[4:5], v[34:35] op_sel_hi:[1,0]
	v_pk_mul_f32 v[6:7], v[6:7], v[34:35] op_sel:[0,1]
	v_add_f32_dpp v16, v16, v16 quad_perm:[2,3,0,1] row_mask:0xf bank_mask:0xf bound_ctrl:1
	v_add_f32_dpp v17, v17, v17 quad_perm:[2,3,0,1] row_mask:0xf bank_mask:0xf bound_ctrl:1
	v_pk_mul_f32 v[8:9], v[8:9], v[36:37] op_sel_hi:[1,0]
	v_pk_mul_f32 v[10:11], v[10:11], v[36:37] op_sel:[0,1]
	v_add_f32_dpp v228, v16, v16 row_half_mirror row_mask:0xf bank_mask:0xf bound_ctrl:1
	v_add_f32_dpp v229, v17, v17 row_half_mirror row_mask:0xf bank_mask:0xf bound_ctrl:1
	v_pk_mul_f32 v[12:13], v[12:13], v[38:39] op_sel_hi:[1,0]
	v_pk_mul_f32 v[14:15], v[14:15], v[38:39] op_sel:[0,1]
	v_pk_fma_f32 v[0:1], v[64:65], v[48:49], v[0:1] op_sel_hi:[1,0,1]
	v_pk_fma_f32 v[2:3], v[64:65], v[48:49], v[2:3] op_sel:[0,1,0]
	v_pk_fma_f32 v[4:5], v[64:65], v[50:51], v[4:5] op_sel_hi:[1,0,1]
	v_pk_fma_f32 v[6:7], v[64:65], v[50:51], v[6:7] op_sel:[0,1,0]
	v_pk_fma_f32 v[8:9], v[64:65], v[52:53], v[8:9] op_sel_hi:[1,0,1]
	v_pk_fma_f32 v[10:11], v[64:65], v[52:53], v[10:11] op_sel:[0,1,0]
	v_pk_fma_f32 v[12:13], v[64:65], v[54:55], v[12:13] op_sel_hi:[1,0,1]
	v_pk_fma_f32 v[14:15], v[64:65], v[54:55], v[14:15] op_sel:[0,1,0]
	v_pk_fma_f32 v[0:1], v[228:229], v[40:41], v[0:1] op_sel_hi:[1,0,1]
	v_pk_fma_f32 v[2:3], v[228:229], v[40:41], v[2:3] op_sel:[0,1,0]
	v_pk_fma_f32 v[4:5], v[228:229], v[42:43], v[4:5] op_sel_hi:[1,0,1]
	v_pk_fma_f32 v[6:7], v[228:229], v[42:43], v[6:7] op_sel:[0,1,0]
	v_pk_fma_f32 v[8:9], v[228:229], v[44:45], v[8:9] op_sel_hi:[1,0,1]
	v_pk_fma_f32 v[10:11], v[228:229], v[44:45], v[10:11] op_sel:[0,1,0]
	v_pk_fma_f32 v[12:13], v[228:229], v[46:47], v[12:13] op_sel_hi:[1,0,1]
	v_pk_fma_f32 v[14:15], v[228:229], v[46:47], v[14:15] op_sel:[0,1,0]
	v_pk_mul_f32 v[116:117], v[0:1], v[56:57] op_sel_hi:[1,0]
	v_pk_fma_f32 v[116:117], v[2:3], v[56:57], v[116:117] op_sel:[0,1,0]
	v_pk_fma_f32 v[116:117], v[4:5], v[58:59], v[116:117] op_sel_hi:[1,0,1]
	v_pk_fma_f32 v[116:117], v[6:7], v[58:59], v[116:117] op_sel:[0,1,0]
	v_pk_fma_f32 v[116:117], v[8:9], v[60:61], v[116:117] op_sel_hi:[1,0,1]
	v_pk_fma_f32 v[116:117], v[10:11], v[60:61], v[116:117] op_sel:[0,1,0]
	v_pk_fma_f32 v[116:117], v[12:13], v[62:63], v[116:117] op_sel_hi:[1,0,1]
	v_pk_fma_f32 v[116:117], v[14:15], v[62:63], v[116:117] op_sel:[0,1,0]
	ds_read_b128 v[24:27], v20 offset:18432
	ds_read_b128 v[28:31], v20 offset:18448
	v_add_f32_dpp v240, v116, v116 quad_perm:[1,0,3,2] row_mask:0xf bank_mask:0xf bound_ctrl:1
	v_add_f32_dpp v241, v117, v117 quad_perm:[1,0,3,2] row_mask:0xf bank_mask:0xf bound_ctrl:1
	ds_read_b128 v[32:35], v20 offset:18688
	v_add_f32_dpp v240, v240, v240 quad_perm:[2,3,0,1] row_mask:0xf bank_mask:0xf bound_ctrl:1
	v_add_f32_dpp v241, v241, v241 quad_perm:[2,3,0,1] row_mask:0xf bank_mask:0xf bound_ctrl:1
	ds_read_b128 v[36:39], v20 offset:18704
	v_add_f32_dpp v240, v240, v240 row_half_mirror row_mask:0xf bank_mask:0xf bound_ctrl:1
	v_add_f32_dpp v241, v241, v241 row_half_mirror row_mask:0xf bank_mask:0xf bound_ctrl:1
	ds_read_b128 v[40:43], v20 offset:18944
	ds_read_b128 v[44:47], v20 offset:18960
	ds_read_b128 v[48:51], v20 offset:19200
	ds_read_b128 v[52:55], v20 offset:19216
	ds_read_b128 v[56:59], v20 offset:19456
	ds_read_b128 v[60:63], v20 offset:19472
	ds_read_b64 v[64:65], v22 offset:19712
	ds_write_b64 v21, v[240:241] offset:2560
	s_waitcnt lgkmcnt(12)
	v_pk_mul_f32 v[16:17], v[0:1], v[186:187] op_sel_hi:[1,0]
	v_pk_fma_f32 v[16:17], v[2:3], v[186:187], v[16:17] op_sel:[0,1,0]
	v_pk_fma_f32 v[16:17], v[4:5], v[188:189], v[16:17] op_sel_hi:[1,0,1]
	v_pk_fma_f32 v[16:17], v[6:7], v[188:189], v[16:17] op_sel:[0,1,0]
	v_pk_fma_f32 v[16:17], v[8:9], v[190:191], v[16:17] op_sel_hi:[1,0,1]
	v_pk_fma_f32 v[16:17], v[10:11], v[190:191], v[16:17] op_sel:[0,1,0]
	v_pk_fma_f32 v[16:17], v[12:13], v[192:193], v[16:17] op_sel_hi:[1,0,1]
	v_pk_fma_f32 v[16:17], v[14:15], v[192:193], v[16:17] op_sel:[0,1,0]
	v_pk_mul_f32 v[0:1], v[0:1], v[194:195] op_sel_hi:[1,0]
	v_pk_mul_f32 v[2:3], v[2:3], v[194:195] op_sel:[0,1]
	v_add_f32_dpp v16, v16, v16 quad_perm:[1,0,3,2] row_mask:0xf bank_mask:0xf bound_ctrl:1
	v_add_f32_dpp v17, v17, v17 quad_perm:[1,0,3,2] row_mask:0xf bank_mask:0xf bound_ctrl:1
	v_pk_mul_f32 v[4:5], v[4:5], v[196:197] op_sel_hi:[1,0]
	v_pk_mul_f32 v[6:7], v[6:7], v[196:197] op_sel:[0,1]
	v_add_f32_dpp v16, v16, v16 quad_perm:[2,3,0,1] row_mask:0xf bank_mask:0xf bound_ctrl:1
	v_add_f32_dpp v17, v17, v17 quad_perm:[2,3,0,1] row_mask:0xf bank_mask:0xf bound_ctrl:1
	v_pk_mul_f32 v[8:9], v[8:9], v[198:199] op_sel_hi:[1,0]
	v_pk_mul_f32 v[10:11], v[10:11], v[198:199] op_sel:[0,1]
	v_add_f32_dpp v228, v16, v16 row_half_mirror row_mask:0xf bank_mask:0xf bound_ctrl:1
	v_add_f32_dpp v229, v17, v17 row_half_mirror row_mask:0xf bank_mask:0xf bound_ctrl:1
; DEV float reduce8_dpp(float v) { v += DPPF(v, 0xB1); v += DPPF(v, 0x4E); v += DPPF(v, 0x141); return v; }
;     ...
;                     const float* bs = base0 + tok * 384;
;                     const f32x4 a0 = *(const f32x4*)bs, a1 = *(const f32x4*)(bs + 4);
;                     const f32x4 w0 = *(const f32x4*)(bs + 64), w1 = *(const f32x4*)(bs + 68);
;                     const f32x4 b0 = *(const f32x4*)(bs + 128), b1 = *(const f32x4*)(bs + 132);
;                     const f32x4 k0 = *(const f32x4*)(bs + 192), k1 = *(const f32x4*)(bs + 196);
;                     const f32x4 r0 = *(const f32x4*)(bs + 256), r1 = *(const f32x4*)(bs + 260);
;                     const f32x2 vv = *(const f32x2*)(op + (size_t)(buf * 32 + tok) * 384 + 320 + 2 * vp);
;                     const f32x2 av[4] = {(f32x2){a0[0], a0[1]}, (f32x2){a0[2], a0[3]}, (f32x2){a1[0], a1[1]}, (f32x2){a1[2], a1[3]}};
;                     const f32x2 wv[4] = {(f32x2){w0[0], w0[1]}, (f32x2){w0[2], w0[3]}, (f32x2){w1[0], w1[1]}, (f32x2){w1[2], w1[3]}};
;                     const f32x2 bv[4] = {(f32x2){b0[0], b0[1]}, (f32x2){b0[2], b0[3]}, (f32x2){b1[0], b1[1]}, (f32x2){b1[2], b1[3]}};
;                     const f32x2 kv[4] = {(f32x2){k0[0], k0[1]}, (f32x2){k0[2], k0[3]}, (f32x2){k1[0], k1[1]}, (f32x2){k1[2], k1[3]}};
;                     const f32x2 rv[4] = {(f32x2){r0[0], r0[1]}, (f32x2){r0[2], r0[3]}, (f32x2){r1[0], r1[1]}, (f32x2){r1[2], r1[3]}};
;                     float yo[2];
; #pragma unroll
;                     for (int i = 0; i < 2; ++i) {
;                         f32x2 sa2 = st[i][0] * av[0]; sa2 += st[i][1] * av[1]; sa2 += st[i][2] * av[2]; sa2 += st[i][3] * av[3];
;                         const float sa = reduce8_dpp(sa2[0] + sa2[1]);
;                         const float vi = vv[i];
;                         f32x2 y2 = (f32x2){0.f, 0.f};
; #pragma unroll
;                         for (int j = 0; j < 4; ++j) { st[i][j] = st[i][j] * wv[j] + sa * bv[j] + vi * kv[j]; y2 += st[i][j] * rv[j]; }
;                         yo[i] = reduce8_dpp(y2[0] + y2[1]);
;                     }
;                     if (kq == 0) *(f32x2*)(yb + tok * 64) = (f32x2){yo[0], yo[1]};
	v_pk_mul_f32 v[12:13], v[12:13], v[200:201] op_sel_hi:[1,0]
	v_pk_mul_f32 v[14:15], v[14:15], v[200:201] op_sel:[0,1]
	v_pk_fma_f32 v[0:1], v[226:227], v[210:211], v[0:1] op_sel_hi:[1,0,1]
	v_pk_fma_f32 v[2:3], v[226:227], v[210:211], v[2:3] op_sel:[0,1,0]
	v_pk_fma_f32 v[4:5], v[226:227], v[212:213], v[4:5] op_sel_hi:[1,0,1]
	v_pk_fma_f32 v[6:7], v[226:227], v[212:213], v[6:7] op_sel:[0,1,0]
	v_pk_fma_f32 v[8:9], v[226:227], v[214:215], v[8:9] op_sel_hi:[1,0,1]
	v_pk_fma_f32 v[10:11], v[226:227], v[214:215], v[10:11] op_sel:[0,1,0]
	v_pk_fma_f32 v[12:13], v[226:227], v[216:217], v[12:13] op_sel_hi:[1,0,1]
	v_pk_fma_f32 v[14:15], v[226:227], v[216:217], v[14:15] op_sel:[0,1,0]
	v_pk_fma_f32 v[0:1], v[228:229], v[202:203], v[0:1] op_sel_hi:[1,0,1]
	v_pk_fma_f32 v[2:3], v[228:229], v[202:203], v[2:3] op_sel:[0,1,0]
	v_pk_fma_f32 v[4:5], v[228:229], v[204:205], v[4:5] op_sel_hi:[1,0,1]
	v_pk_fma_f32 v[6:7], v[228:229], v[204:205], v[6:7] op_sel:[0,1,0]
	v_pk_fma_f32 v[8:9], v[228:229], v[206:207], v[8:9] op_sel_hi:[1,0,1]
	v_pk_fma_f32 v[10:11], v[228:229], v[206:207], v[10:11] op_sel:[0,1,0]
	v_pk_fma_f32 v[12:13], v[228:229], v[208:209], v[12:13] op_sel_hi:[1,0,1]
	v_pk_fma_f32 v[14:15], v[228:229], v[208:209], v[14:15] op_sel:[0,1,0]
	v_pk_mul_f32 v[116:117], v[0:1], v[218:219] op_sel_hi:[1,0]
	v_pk_fma_f32 v[116:117], v[2:3], v[218:219], v[116:117] op_sel:[0,1,0]
	v_pk_fma_f32 v[116:117], v[4:5], v[220:221], v[116:117] op_sel_hi:[1,0,1]
	v_pk_fma_f32 v[116:117], v[6:7], v[220:221], v[116:117] op_sel:[0,1,0]
	v_pk_fma_f32 v[116:117], v[8:9], v[222:223], v[116:117] op_sel_hi:[1,0,1]
	v_pk_fma_f32 v[116:117], v[10:11], v[222:223], v[116:117] op_sel:[0,1,0]
	v_pk_fma_f32 v[116:117], v[12:13], v[224:225], v[116:117] op_sel_hi:[1,0,1]
	v_pk_fma_f32 v[116:117], v[14:15], v[224:225], v[116:117] op_sel:[0,1,0]
	ds_read_b128 v[186:189], v20 offset:19968
	ds_read_b128 v[190:193], v20 offset:19984
	v_add_f32_dpp v240, v116, v116 quad_perm:[1,0,3,2] row_mask:0xf bank_mask:0xf bound_ctrl:1
	v_add_f32_dpp v241, v117, v117 quad_perm:[1,0,3,2] row_mask:0xf bank_mask:0xf bound_ctrl:1
	ds_read_b128 v[194:197], v20 offset:20224
	v_add_f32_dpp v240, v240, v240 quad_perm:[2,3,0,1] row_mask:0xf bank_mask:0xf bound_ctrl:1
	v_add_f32_dpp v241, v241, v241 quad_perm:[2,3,0,1] row_mask:0xf bank_mask:0xf bound_ctrl:1
	ds_read_b128 v[198:201], v20 offset:20240
	v_add_f32_dpp v240, v240, v240 row_half_mirror row_mask:0xf bank_mask:0xf bound_ctrl:1
	v_add_f32_dpp v241, v241, v241 row_half_mirror row_mask:0xf bank_mask:0xf bound_ctrl:1
	ds_read_b128 v[202:205], v20 offset:20480
	ds_read_b128 v[206:209], v20 offset:20496
	ds_read_b128 v[210:213], v20 offset:20736
	ds_read_b128 v[214:217], v20 offset:20752
	ds_read_b128 v[218:221], v20 offset:20992
	ds_read_b128 v[222:225], v20 offset:21008
	ds_read_b64 v[226:227], v22 offset:21248
	ds_write_b64 v21, v[240:241] offset:2816
	s_waitcnt lgkmcnt(12)
	v_pk_mul_f32 v[16:17], v[0:1], v[24:25] op_sel_hi:[1,0]
	v_pk_fma_f32 v[16:17], v[2:3], v[24:25], v[16:17] op_sel:[0,1,0]
	v_pk_fma_f32 v[16:17], v[4:5], v[26:27], v[16:17] op_sel_hi:[1,0,1]
	v_pk_fma_f32 v[16:17], v[6:7], v[26:27], v[16:17] op_sel:[0,1,0]
	v_pk_fma_f32 v[16:17], v[8:9], v[28:29], v[16:17] op_sel_hi:[1,0,1]
	v_pk_fma_f32 v[16:17], v[10:11], v[28:29], v[16:17] op_sel:[0,1,0]
	v_pk_fma_f32 v[16:17], v[12:13], v[30:31], v[16:17] op_sel_hi:[1,0,1]
	v_pk_fma_f32 v[16:17], v[14:15], v[30:31], v[16:17] op_sel:[0,1,0]
	v_pk_mul_f32 v[0:1], v[0:1], v[32:33] op_sel_hi:[1,0]
	v_pk_mul_f32 v[2:3], v[2:3], v[32:33] op_sel:[0,1]
	v_add_f32_dpp v16, v16, v16 quad_perm:[1,0,3,2] row_mask:0xf bank_mask:0xf bound_ctrl:1
	v_add_f32_dpp v17, v17, v17 quad_perm:[1,0,3,2] row_mask:0xf bank_mask:0xf bound_ctrl:1
	v_pk_mul_f32 v[4:5], v[4:5], v[34:35] op_sel_hi:[1,0]
	v_pk_mul_f32 v[6:7], v[6:7], v[34:35] op_sel:[0,1]
	v_add_f32_dpp v16, v16, v16 quad_perm:[2,3,0,1] row_mask:0xf bank_mask:0xf bound_ctrl:1
	v_add_f32_dpp v17, v17, v17 quad_perm:[2,3,0,1] row_mask:0xf bank_mask:0xf bound_ctrl:1
	v_pk_mul_f32 v[8:9], v[8:9], v[36:37] op_sel_hi:[1,0]
	v_pk_mul_f32 v[10:11], v[10:11], v[36:37] op_sel:[0,1]
	v_add_f32_dpp v228, v16, v16 row_half_mirror row_mask:0xf bank_mask:0xf bound_ctrl:1
	v_add_f32_dpp v229, v17, v17 row_half_mirror row_mask:0xf bank_mask:0xf bound_ctrl:1
	v_pk_mul_f32 v[12:13], v[12:13], v[38:39] op_sel_hi:[1,0]
	v_pk_mul_f32 v[14:15], v[14:15], v[38:39] op_sel:[0,1]
	v_pk_fma_f32 v[0:1], v[64:65], v[48:49], v[0:1] op_sel_hi:[1,0,1]
	v_pk_fma_f32 v[2:3], v[64:65], v[48:49], v[2:3] op_sel:[0,1,0]
	v_pk_fma_f32 v[4:5], v[64:65], v[50:51], v[4:5] op_sel_hi:[1,0,1]
	v_pk_fma_f32 v[6:7], v[64:65], v[50:51], v[6:7] op_sel:[0,1,0]
	v_pk_fma_f32 v[8:9], v[64:65], v[52:53], v[8:9] op_sel_hi:[1,0,1]
	v_pk_fma_f32 v[10:11], v[64:65], v[52:53], v[10:11] op_sel:[0,1,0]
	v_pk_fma_f32 v[12:13], v[64:65], v[54:55], v[12:13] op_sel_hi:[1,0,1]
	v_pk_fma_f32 v[14:15], v[64:65], v[54:55], v[14:15] op_sel:[0,1,0]
	v_pk_fma_f32 v[0:1], v[228:229], v[40:41], v[0:1] op_sel_hi:[1,0,1]
	v_pk_fma_f32 v[2:3], v[228:229], v[40:41], v[2:3] op_sel:[0,1,0]
	v_pk_fma_f32 v[4:5], v[228:229], v[42:43], v[4:5] op_sel_hi:[1,0,1]
	v_pk_fma_f32 v[6:7], v[228:229], v[42:43], v[6:7] op_sel:[0,1,0]
	v_pk_fma_f32 v[8:9], v[228:229], v[44:45], v[8:9] op_sel_hi:[1,0,1]
	v_pk_fma_f32 v[10:11], v[228:229], v[44:45], v[10:11] op_sel:[0,1,0]
	v_pk_fma_f32 v[12:13], v[228:229], v[46:47], v[12:13] op_sel_hi:[1,0,1]
	v_pk_fma_f32 v[14:15], v[228:229], v[46:47], v[14:15] op_sel:[0,1,0]
	v_pk_mul_f32 v[116:117], v[0:1], v[56:57] op_sel_hi:[1,0]
	v_pk_fma_f32 v[116:117], v[2:3], v[56:57], v[116:117] op_sel:[0,1,0]
; DEV float reduce8_dpp(float v) { v += DPPF(v, 0xB1); v += DPPF(v, 0x4E); v += DPPF(v, 0x141); return v; }
;     ...
;                     const float* bs = base0 + tok * 384;
;                     const f32x4 a0 = *(const f32x4*)bs, a1 = *(const f32x4*)(bs + 4);
;                     const f32x4 w0 = *(const f32x4*)(bs + 64), w1 = *(const f32x4*)(bs + 68);
;                     const f32x4 b0 = *(const f32x4*)(bs + 128), b1 = *(const f32x4*)(bs + 132);
;                     const f32x4 k0 = *(const f32x4*)(bs + 192), k1 = *(const f32x4*)(bs + 196);
;                     const f32x4 r0 = *(const f32x4*)(bs + 256), r1 = *(const f32x4*)(bs + 260);
;                     const f32x2 vv = *(const f32x2*)(op + (size_t)(buf * 32 + tok) * 384 + 320 + 2 * vp);
;                     const f32x2 av[4] = {(f32x2){a0[0], a0[1]}, (f32x2){a0[2], a0[3]}, (f32x2){a1[0], a1[1]}, (f32x2){a1[2], a1[3]}};
;                     const f32x2 wv[4] = {(f32x2){w0[0], w0[1]}, (f32x2){w0[2], w0[3]}, (f32x2){w1[0], w1[1]}, (f32x2){w1[2], w1[3]}};
;                     const f32x2 bv[4] = {(f32x2){b0[0], b0[1]}, (f32x2){b0[2], b0[3]}, (f32x2){b1[0], b1[1]}, (f32x2){b1[2], b1[3]}};
;                     const f32x2 kv[4] = {(f32x2){k0[0], k0[1]}, (f32x2){k0[2], k0[3]}, (f32x2){k1[0], k1[1]}, (f32x2){k1[2], k1[3]}};
;                     const f32x2 rv[4] = {(f32x2){r0[0], r0[1]}, (f32x2){r0[2], r0[3]}, (f32x2){r1[0], r1[1]}, (f32x2){r1[2], r1[3]}};
;                     float yo[2];
; #pragma unroll
;                     for (int i = 0; i < 2; ++i) {
;                         f32x2 sa2 = st[i][0] * av[0]; sa2 += st[i][1] * av[1]; sa2 += st[i][2] * av[2]; sa2 += st[i][3] * av[3];
;                         const float sa = reduce8_dpp(sa2[0] + sa2[1]);
;                         const float vi = vv[i];
;                         f32x2 y2 = (f32x2){0.f, 0.f};
; #pragma unroll
;                         for (int j = 0; j < 4; ++j) { st[i][j] = st[i][j] * wv[j] + sa * bv[j] + vi * kv[j]; y2 += st[i][j] * rv[j]; }
;                         yo[i] = reduce8_dpp(y2[0] + y2[1]);
;                     }
;                     if (kq == 0) *(f32x2*)(yb + tok * 64) = (f32x2){yo[0], yo[1]};
	v_pk_fma_f32 v[116:117], v[4:5], v[58:59], v[116:117] op_sel_hi:[1,0,1]
	v_pk_fma_f32 v[116:117], v[6:7], v[58:59], v[116:117] op_sel:[0,1,0]
	v_pk_fma_f32 v[116:117], v[8:9], v[60:61], v[116:117] op_sel_hi:[1,0,1]
	v_pk_fma_f32 v[116:117], v[10:11], v[60:61], v[116:117] op_sel:[0,1,0]
	v_pk_fma_f32 v[116:117], v[12:13], v[62:63], v[116:117] op_sel_hi:[1,0,1]
	v_pk_fma_f32 v[116:117], v[14:15], v[62:63], v[116:117] op_sel:[0,1,0]
	ds_read_b128 v[24:27], v20 offset:21504
	ds_read_b128 v[28:31], v20 offset:21520
	v_add_f32_dpp v240, v116, v116 quad_perm:[1,0,3,2] row_mask:0xf bank_mask:0xf bound_ctrl:1
	v_add_f32_dpp v241, v117, v117 quad_perm:[1,0,3,2] row_mask:0xf bank_mask:0xf bound_ctrl:1
	ds_read_b128 v[32:35], v20 offset:21760
	v_add_f32_dpp v240, v240, v240 quad_perm:[2,3,0,1] row_mask:0xf bank_mask:0xf bound_ctrl:1
	v_add_f32_dpp v241, v241, v241 quad_perm:[2,3,0,1] row_mask:0xf bank_mask:0xf bound_ctrl:1
	ds_read_b128 v[36:39], v20 offset:21776
	v_add_f32_dpp v240, v240, v240 row_half_mirror row_mask:0xf bank_mask:0xf bound_ctrl:1
	v_add_f32_dpp v241, v241, v241 row_half_mirror row_mask:0xf bank_mask:0xf bound_ctrl:1
	ds_read_b128 v[40:43], v20 offset:22016
	ds_read_b128 v[44:47], v20 offset:22032
	ds_read_b128 v[48:51], v20 offset:22272
	ds_read_b128 v[52:55], v20 offset:22288
	ds_read_b128 v[56:59], v20 offset:22528
	ds_read_b128 v[60:63], v20 offset:22544
	ds_read_b64 v[64:65], v22 offset:22784
	ds_write_b64 v21, v[240:241] offset:3072
	s_waitcnt lgkmcnt(12)
	v_pk_mul_f32 v[16:17], v[0:1], v[186:187] op_sel_hi:[1,0]
	v_pk_fma_f32 v[16:17], v[2:3], v[186:187], v[16:17] op_sel:[0,1,0]
	v_pk_fma_f32 v[16:17], v[4:5], v[188:189], v[16:17] op_sel_hi:[1,0,1]
	v_pk_fma_f32 v[16:17], v[6:7], v[188:189], v[16:17] op_sel:[0,1,0]
	v_pk_fma_f32 v[16:17], v[8:9], v[190:191], v[16:17] op_sel_hi:[1,0,1]
	v_pk_fma_f32 v[16:17], v[10:11], v[190:191], v[16:17] op_sel:[0,1,0]
	v_pk_fma_f32 v[16:17], v[12:13], v[192:193], v[16:17] op_sel_hi:[1,0,1]
	v_pk_fma_f32 v[16:17], v[14:15], v[192:193], v[16:17] op_sel:[0,1,0]
	v_pk_mul_f32 v[0:1], v[0:1], v[194:195] op_sel_hi:[1,0]
	v_pk_mul_f32 v[2:3], v[2:3], v[194:195] op_sel:[0,1]
	v_add_f32_dpp v16, v16, v16 quad_perm:[1,0,3,2] row_mask:0xf bank_mask:0xf bound_ctrl:1
	v_add_f32_dpp v17, v17, v17 quad_perm:[1,0,3,2] row_mask:0xf bank_mask:0xf bound_ctrl:1
	v_pk_mul_f32 v[4:5], v[4:5], v[196:197] op_sel_hi:[1,0]
	v_pk_mul_f32 v[6:7], v[6:7], v[196:197] op_sel:[0,1]
	v_add_f32_dpp v16, v16, v16 quad_perm:[2,3,0,1] row_mask:0xf bank_mask:0xf bound_ctrl:1
	v_add_f32_dpp v17, v17, v17 quad_perm:[2,3,0,1] row_mask:0xf bank_mask:0xf bound_ctrl:1
	v_pk_mul_f32 v[8:9], v[8:9], v[198:199] op_sel_hi:[1,0]
	v_pk_mul_f32 v[10:11], v[10:11], v[198:199] op_sel:[0,1]
	v_add_f32_dpp v228, v16, v16 row_half_mirror row_mask:0xf bank_mask:0xf bound_ctrl:1
	v_add_f32_dpp v229, v17, v17 row_half_mirror row_mask:0xf bank_mask:0xf bound_ctrl:1
	v_pk_mul_f32 v[12:13], v[12:13], v[200:201] op_sel_hi:[1,0]
	v_pk_mul_f32 v[14:15], v[14:15], v[200:201] op_sel:[0,1]
	v_pk_fma_f32 v[0:1], v[226:227], v[210:211], v[0:1] op_sel_hi:[1,0,1]
	v_pk_fma_f32 v[2:3], v[226:227], v[210:211], v[2:3] op_sel:[0,1,0]
	v_pk_fma_f32 v[4:5], v[226:227], v[212:213], v[4:5] op_sel_hi:[1,0,1]
	v_pk_fma_f32 v[6:7], v[226:227], v[212:213], v[6:7] op_sel:[0,1,0]
	v_pk_fma_f32 v[8:9], v[226:227], v[214:215], v[8:9] op_sel_hi:[1,0,1]
	v_pk_fma_f32 v[10:11], v[226:227], v[214:215], v[10:11] op_sel:[0,1,0]
	v_pk_fma_f32 v[12:13], v[226:227], v[216:217], v[12:13] op_sel_hi:[1,0,1]
	v_pk_fma_f32 v[14:15], v[226:227], v[216:217], v[14:15] op_sel:[0,1,0]
	v_pk_fma_f32 v[0:1], v[228:229], v[202:203], v[0:1] op_sel_hi:[1,0,1]
	v_pk_fma_f32 v[2:3], v[228:229], v[202:203], v[2:3] op_sel:[0,1,0]
	v_pk_fma_f32 v[4:5], v[228:229], v[204:205], v[4:5] op_sel_hi:[1,0,1]
	v_pk_fma_f32 v[6:7], v[228:229], v[204:205], v[6:7] op_sel:[0,1,0]
	v_pk_fma_f32 v[8:9], v[228:229], v[206:207], v[8:9] op_sel_hi:[1,0,1]
	v_pk_fma_f32 v[10:11], v[228:229], v[206:207], v[10:11] op_sel:[0,1,0]
	v_pk_fma_f32 v[12:13], v[228:229], v[208:209], v[12:13] op_sel_hi:[1,0,1]
	v_pk_fma_f32 v[14:15], v[228:229], v[208:209], v[14:15] op_sel:[0,1,0]
	v_pk_mul_f32 v[116:117], v[0:1], v[218:219] op_sel_hi:[1,0]
	v_pk_fma_f32 v[116:117], v[2:3], v[218:219], v[116:117] op_sel:[0,1,0]
	v_pk_fma_f32 v[116:117], v[4:5], v[220:221], v[116:117] op_sel_hi:[1,0,1]
	v_pk_fma_f32 v[116:117], v[6:7], v[220:221], v[116:117] op_sel:[0,1,0]
	v_pk_fma_f32 v[116:117], v[8:9], v[222:223], v[116:117] op_sel_hi:[1,0,1]
	v_pk_fma_f32 v[116:117], v[10:11], v[222:223], v[116:117] op_sel:[0,1,0]
	v_pk_fma_f32 v[116:117], v[12:13], v[224:225], v[116:117] op_sel_hi:[1,0,1]
	v_pk_fma_f32 v[116:117], v[14:15], v[224:225], v[116:117] op_sel:[0,1,0]
	ds_read_b128 v[186:189], v20 offset:23040
	ds_read_b128 v[190:193], v20 offset:23056
	v_add_f32_dpp v240, v116, v116 quad_perm:[1,0,3,2] row_mask:0xf bank_mask:0xf bound_ctrl:1
	v_add_f32_dpp v241, v117, v117 quad_perm:[1,0,3,2] row_mask:0xf bank_mask:0xf bound_ctrl:1
	ds_read_b128 v[194:197], v20 offset:23296
	v_add_f32_dpp v240, v240, v240 quad_perm:[2,3,0,1] row_mask:0xf bank_mask:0xf bound_ctrl:1
	v_add_f32_dpp v241, v241, v241 quad_perm:[2,3,0,1] row_mask:0xf bank_mask:0xf bound_ctrl:1
	ds_read_b128 v[198:201], v20 offset:23312
	v_add_f32_dpp v240, v240, v240 row_half_mirror row_mask:0xf bank_mask:0xf bound_ctrl:1
	v_add_f32_dpp v241, v241, v241 row_half_mirror row_mask:0xf bank_mask:0xf bound_ctrl:1
	ds_read_b128 v[202:205], v20 offset:23552
	ds_read_b128 v[206:209], v20 offset:23568
	ds_read_b128 v[210:213], v20 offset:23808
	ds_read_b128 v[214:217], v20 offset:23824
	ds_read_b128 v[218:221], v20 offset:24064
	ds_read_b128 v[222:225], v20 offset:24080
	ds_read_b64 v[226:227], v22 offset:24320
	ds_write_b64 v21, v[240:241] offset:3328
	s_waitcnt lgkmcnt(12)
; DEV float reduce8_dpp(float v) { v += DPPF(v, 0xB1); v += DPPF(v, 0x4E); v += DPPF(v, 0x141); return v; }
;     ...
;                     const float* bs = base0 + tok * 384;
;                     const f32x4 a0 = *(const f32x4*)bs, a1 = *(const f32x4*)(bs + 4);
;                     const f32x4 w0 = *(const f32x4*)(bs + 64), w1 = *(const f32x4*)(bs + 68);
;                     const f32x4 b0 = *(const f32x4*)(bs + 128), b1 = *(const f32x4*)(bs + 132);
;                     const f32x4 k0 = *(const f32x4*)(bs + 192), k1 = *(const f32x4*)(bs + 196);
;                     const f32x4 r0 = *(const f32x4*)(bs + 256), r1 = *(const f32x4*)(bs + 260);
;                     const f32x2 vv = *(const f32x2*)(op + (size_t)(buf * 32 + tok) * 384 + 320 + 2 * vp);
;                     const f32x2 av[4] = {(f32x2){a0[0], a0[1]}, (f32x2){a0[2], a0[3]}, (f32x2){a1[0], a1[1]}, (f32x2){a1[2], a1[3]}};
;                     const f32x2 wv[4] = {(f32x2){w0[0], w0[1]}, (f32x2){w0[2], w0[3]}, (f32x2){w1[0], w1[1]}, (f32x2){w1[2], w1[3]}};
;                     const f32x2 bv[4] = {(f32x2){b0[0], b0[1]}, (f32x2){b0[2], b0[3]}, (f32x2){b1[0], b1[1]}, (f32x2){b1[2], b1[3]}};
;                     const f32x2 kv[4] = {(f32x2){k0[0], k0[1]}, (f32x2){k0[2], k0[3]}, (f32x2){k1[0], k1[1]}, (f32x2){k1[2], k1[3]}};
;                     const f32x2 rv[4] = {(f32x2){r0[0], r0[1]}, (f32x2){r0[2], r0[3]}, (f32x2){r1[0], r1[1]}, (f32x2){r1[2], r1[3]}};
;                     float yo[2];
; #pragma unroll
;                     for (int i = 0; i < 2; ++i) {
;                         f32x2 sa2 = st[i][0] * av[0]; sa2 += st[i][1] * av[1]; sa2 += st[i][2] * av[2]; sa2 += st[i][3] * av[3];
;                         const float sa = reduce8_dpp(sa2[0] + sa2[1]);
;                         const float vi = vv[i];
;                         f32x2 y2 = (f32x2){0.f, 0.f};
; #pragma unroll
;                         for (int j = 0; j < 4; ++j) { st[i][j] = st[i][j] * wv[j] + sa * bv[j] + vi * kv[j]; y2 += st[i][j] * rv[j]; }
;                         yo[i] = reduce8_dpp(y2[0] + y2[1]);
;                     }
;                     if (kq == 0) *(f32x2*)(yb + tok * 64) = (f32x2){yo[0], yo[1]};
	v_pk_mul_f32 v[16:17], v[0:1], v[24:25] op_sel_hi:[1,0]
	v_pk_fma_f32 v[16:17], v[2:3], v[24:25], v[16:17] op_sel:[0,1,0]
	v_pk_fma_f32 v[16:17], v[4:5], v[26:27], v[16:17] op_sel_hi:[1,0,1]
	v_pk_fma_f32 v[16:17], v[6:7], v[26:27], v[16:17] op_sel:[0,1,0]
	v_pk_fma_f32 v[16:17], v[8:9], v[28:29], v[16:17] op_sel_hi:[1,0,1]
	v_pk_fma_f32 v[16:17], v[10:11], v[28:29], v[16:17] op_sel:[0,1,0]
	v_pk_fma_f32 v[16:17], v[12:13], v[30:31], v[16:17] op_sel_hi:[1,0,1]
	v_pk_fma_f32 v[16:17], v[14:15], v[30:31], v[16:17] op_sel:[0,1,0]
	v_pk_mul_f32 v[0:1], v[0:1], v[32:33] op_sel_hi:[1,0]
	v_pk_mul_f32 v[2:3], v[2:3], v[32:33] op_sel:[0,1]
	v_add_f32_dpp v16, v16, v16 quad_perm:[1,0,3,2] row_mask:0xf bank_mask:0xf bound_ctrl:1
	v_add_f32_dpp v17, v17, v17 quad_perm:[1,0,3,2] row_mask:0xf bank_mask:0xf bound_ctrl:1
	v_pk_mul_f32 v[4:5], v[4:5], v[34:35] op_sel_hi:[1,0]
	v_pk_mul_f32 v[6:7], v[6:7], v[34:35] op_sel:[0,1]
	v_add_f32_dpp v16, v16, v16 quad_perm:[2,3,0,1] row_mask:0xf bank_mask:0xf bound_ctrl:1
	v_add_f32_dpp v17, v17, v17 quad_perm:[2,3,0,1] row_mask:0xf bank_mask:0xf bound_ctrl:1
	v_pk_mul_f32 v[8:9], v[8:9], v[36:37] op_sel_hi:[1,0]
	v_pk_mul_f32 v[10:11], v[10:11], v[36:37] op_sel:[0,1]
	v_add_f32_dpp v228, v16, v16 row_half_mirror row_mask:0xf bank_mask:0xf bound_ctrl:1
	v_add_f32_dpp v229, v17, v17 row_half_mirror row_mask:0xf bank_mask:0xf bound_ctrl:1
	v_pk_mul_f32 v[12:13], v[12:13], v[38:39] op_sel_hi:[1,0]
	v_pk_mul_f32 v[14:15], v[14:15], v[38:39] op_sel:[0,1]
	v_pk_fma_f32 v[0:1], v[64:65], v[48:49], v[0:1] op_sel_hi:[1,0,1]
	v_pk_fma_f32 v[2:3], v[64:65], v[48:49], v[2:3] op_sel:[0,1,0]
	v_pk_fma_f32 v[4:5], v[64:65], v[50:51], v[4:5] op_sel_hi:[1,0,1]
	v_pk_fma_f32 v[6:7], v[64:65], v[50:51], v[6:7] op_sel:[0,1,0]
	v_pk_fma_f32 v[8:9], v[64:65], v[52:53], v[8:9] op_sel_hi:[1,0,1]
	v_pk_fma_f32 v[10:11], v[64:65], v[52:53], v[10:11] op_sel:[0,1,0]
	v_pk_fma_f32 v[12:13], v[64:65], v[54:55], v[12:13] op_sel_hi:[1,0,1]
	v_pk_fma_f32 v[14:15], v[64:65], v[54:55], v[14:15] op_sel:[0,1,0]
	v_pk_fma_f32 v[0:1], v[228:229], v[40:41], v[0:1] op_sel_hi:[1,0,1]
	v_pk_fma_f32 v[2:3], v[228:229], v[40:41], v[2:3] op_sel:[0,1,0]
	v_pk_fma_f32 v[4:5], v[228:229], v[42:43], v[4:5] op_sel_hi:[1,0,1]
	v_pk_fma_f32 v[6:7], v[228:229], v[42:43], v[6:7] op_sel:[0,1,0]
	v_pk_fma_f32 v[8:9], v[228:229], v[44:45], v[8:9] op_sel_hi:[1,0,1]
	v_pk_fma_f32 v[10:11], v[228:229], v[44:45], v[10:11] op_sel:[0,1,0]
	v_pk_fma_f32 v[12:13], v[228:229], v[46:47], v[12:13] op_sel_hi:[1,0,1]
	v_pk_fma_f32 v[14:15], v[228:229], v[46:47], v[14:15] op_sel:[0,1,0]
	v_pk_mul_f32 v[116:117], v[0:1], v[56:57] op_sel_hi:[1,0]
	v_pk_fma_f32 v[116:117], v[2:3], v[56:57], v[116:117] op_sel:[0,1,0]
	v_pk_fma_f32 v[116:117], v[4:5], v[58:59], v[116:117] op_sel_hi:[1,0,1]
	v_pk_fma_f32 v[116:117], v[6:7], v[58:59], v[116:117] op_sel:[0,1,0]
	v_pk_fma_f32 v[116:117], v[8:9], v[60:61], v[116:117] op_sel_hi:[1,0,1]
	v_pk_fma_f32 v[116:117], v[10:11], v[60:61], v[116:117] op_sel:[0,1,0]
	v_pk_fma_f32 v[116:117], v[12:13], v[62:63], v[116:117] op_sel_hi:[1,0,1]
	v_pk_fma_f32 v[116:117], v[14:15], v[62:63], v[116:117] op_sel:[0,1,0]
	ds_read_b128 v[24:27], v20 offset:24576
	ds_read_b128 v[28:31], v20 offset:24592
	v_add_f32_dpp v240, v116, v116 quad_perm:[1,0,3,2] row_mask:0xf bank_mask:0xf bound_ctrl:1
	v_add_f32_dpp v241, v117, v117 quad_perm:[1,0,3,2] row_mask:0xf bank_mask:0xf bound_ctrl:1
	ds_read_b128 v[32:35], v20 offset:24832
	v_add_f32_dpp v240, v240, v240 quad_perm:[2,3,0,1] row_mask:0xf bank_mask:0xf bound_ctrl:1
	v_add_f32_dpp v241, v241, v241 quad_perm:[2,3,0,1] row_mask:0xf bank_mask:0xf bound_ctrl:1
	ds_read_b128 v[36:39], v20 offset:24848
	v_add_f32_dpp v240, v240, v240 row_half_mirror row_mask:0xf bank_mask:0xf bound_ctrl:1
	v_add_f32_dpp v241, v241, v241 row_half_mirror row_mask:0xf bank_mask:0xf bound_ctrl:1
	ds_read_b128 v[40:43], v20 offset:25088
	ds_read_b128 v[44:47], v20 offset:25104
	ds_read_b128 v[48:51], v20 offset:25344
	ds_read_b128 v[52:55], v20 offset:25360
	ds_read_b128 v[56:59], v20 offset:25600
	ds_read_b128 v[60:63], v20 offset:25616
	ds_read_b64 v[64:65], v22 offset:25856
	ds_write_b64 v21, v[240:241] offset:3584
	s_waitcnt lgkmcnt(12)
	v_pk_mul_f32 v[16:17], v[0:1], v[186:187] op_sel_hi:[1,0]
	v_pk_fma_f32 v[16:17], v[2:3], v[186:187], v[16:17] op_sel:[0,1,0]
	v_pk_fma_f32 v[16:17], v[4:5], v[188:189], v[16:17] op_sel_hi:[1,0,1]
	v_pk_fma_f32 v[16:17], v[6:7], v[188:189], v[16:17] op_sel:[0,1,0]
	v_pk_fma_f32 v[16:17], v[8:9], v[190:191], v[16:17] op_sel_hi:[1,0,1]
	v_pk_fma_f32 v[16:17], v[10:11], v[190:191], v[16:17] op_sel:[0,1,0]
	v_pk_fma_f32 v[16:17], v[12:13], v[192:193], v[16:17] op_sel_hi:[1,0,1]
	v_pk_fma_f32 v[16:17], v[14:15], v[192:193], v[16:17] op_sel:[0,1,0]
	v_pk_mul_f32 v[0:1], v[0:1], v[194:195] op_sel_hi:[1,0]
	v_pk_mul_f32 v[2:3], v[2:3], v[194:195] op_sel:[0,1]
	v_add_f32_dpp v16, v16, v16 quad_perm:[1,0,3,2] row_mask:0xf bank_mask:0xf bound_ctrl:1
	v_add_f32_dpp v17, v17, v17 quad_perm:[1,0,3,2] row_mask:0xf bank_mask:0xf bound_ctrl:1
	v_pk_mul_f32 v[4:5], v[4:5], v[196:197] op_sel_hi:[1,0]
	v_pk_mul_f32 v[6:7], v[6:7], v[196:197] op_sel:[0,1]
	v_add_f32_dpp v16, v16, v16 quad_perm:[2,3,0,1] row_mask:0xf bank_mask:0xf bound_ctrl:1
	v_add_f32_dpp v17, v17, v17 quad_perm:[2,3,0,1] row_mask:0xf bank_mask:0xf bound_ctrl:1
	v_pk_mul_f32 v[8:9], v[8:9], v[198:199] op_sel_hi:[1,0]
	v_pk_mul_f32 v[10:11], v[10:11], v[198:199] op_sel:[0,1]
	v_add_f32_dpp v228, v16, v16 row_half_mirror row_mask:0xf bank_mask:0xf bound_ctrl:1
	v_add_f32_dpp v229, v17, v17 row_half_mirror row_mask:0xf bank_mask:0xf bound_ctrl:1
; DEV float reduce8_dpp(float v) { v += DPPF(v, 0xB1); v += DPPF(v, 0x4E); v += DPPF(v, 0x141); return v; }
;     ...
;                     const float* bs = base0 + tok * 384;
;                     const f32x4 a0 = *(const f32x4*)bs, a1 = *(const f32x4*)(bs + 4);
;                     const f32x4 w0 = *(const f32x4*)(bs + 64), w1 = *(const f32x4*)(bs + 68);
;                     const f32x4 b0 = *(const f32x4*)(bs + 128), b1 = *(const f32x4*)(bs + 132);
;                     const f32x4 k0 = *(const f32x4*)(bs + 192), k1 = *(const f32x4*)(bs + 196);
;                     const f32x4 r0 = *(const f32x4*)(bs + 256), r1 = *(const f32x4*)(bs + 260);
;                     const f32x2 vv = *(const f32x2*)(op + (size_t)(buf * 32 + tok) * 384 + 320 + 2 * vp);
;                     const f32x2 av[4] = {(f32x2){a0[0], a0[1]}, (f32x2){a0[2], a0[3]}, (f32x2){a1[0], a1[1]}, (f32x2){a1[2], a1[3]}};
;                     const f32x2 wv[4] = {(f32x2){w0[0], w0[1]}, (f32x2){w0[2], w0[3]}, (f32x2){w1[0], w1[1]}, (f32x2){w1[2], w1[3]}};
;                     const f32x2 bv[4] = {(f32x2){b0[0], b0[1]}, (f32x2){b0[2], b0[3]}, (f32x2){b1[0], b1[1]}, (f32x2){b1[2], b1[3]}};
;                     const f32x2 kv[4] = {(f32x2){k0[0], k0[1]}, (f32x2){k0[2], k0[3]}, (f32x2){k1[0], k1[1]}, (f32x2){k1[2], k1[3]}};
;                     const f32x2 rv[4] = {(f32x2){r0[0], r0[1]}, (f32x2){r0[2], r0[3]}, (f32x2){r1[0], r1[1]}, (f32x2){r1[2], r1[3]}};
;                     float yo[2];
; #pragma unroll
;                     for (int i = 0; i < 2; ++i) {
;                         f32x2 sa2 = st[i][0] * av[0]; sa2 += st[i][1] * av[1]; sa2 += st[i][2] * av[2]; sa2 += st[i][3] * av[3];
;                         const float sa = reduce8_dpp(sa2[0] + sa2[1]);
;                         const float vi = vv[i];
;                         f32x2 y2 = (f32x2){0.f, 0.f};
; #pragma unroll
;                         for (int j = 0; j < 4; ++j) { st[i][j] = st[i][j] * wv[j] + sa * bv[j] + vi * kv[j]; y2 += st[i][j] * rv[j]; }
;                         yo[i] = reduce8_dpp(y2[0] + y2[1]);
;                     }
;                     if (kq == 0) *(f32x2*)(yb + tok * 64) = (f32x2){yo[0], yo[1]};
	v_pk_mul_f32 v[12:13], v[12:13], v[200:201] op_sel_hi:[1,0]
	v_pk_mul_f32 v[14:15], v[14:15], v[200:201] op_sel:[0,1]
	v_pk_fma_f32 v[0:1], v[226:227], v[210:211], v[0:1] op_sel_hi:[1,0,1]
	v_pk_fma_f32 v[2:3], v[226:227], v[210:211], v[2:3] op_sel:[0,1,0]
	v_pk_fma_f32 v[4:5], v[226:227], v[212:213], v[4:5] op_sel_hi:[1,0,1]
	v_pk_fma_f32 v[6:7], v[226:227], v[212:213], v[6:7] op_sel:[0,1,0]
	v_pk_fma_f32 v[8:9], v[226:227], v[214:215], v[8:9] op_sel_hi:[1,0,1]
	v_pk_fma_f32 v[10:11], v[226:227], v[214:215], v[10:11] op_sel:[0,1,0]
	v_pk_fma_f32 v[12:13], v[226:227], v[216:217], v[12:13] op_sel_hi:[1,0,1]
	v_pk_fma_f32 v[14:15], v[226:227], v[216:217], v[14:15] op_sel:[0,1,0]
	v_pk_fma_f32 v[0:1], v[228:229], v[202:203], v[0:1] op_sel_hi:[1,0,1]
	v_pk_fma_f32 v[2:3], v[228:229], v[202:203], v[2:3] op_sel:[0,1,0]
	v_pk_fma_f32 v[4:5], v[228:229], v[204:205], v[4:5] op_sel_hi:[1,0,1]
	v_pk_fma_f32 v[6:7], v[228:229], v[204:205], v[6:7] op_sel:[0,1,0]
	v_pk_fma_f32 v[8:9], v[228:229], v[206:207], v[8:9] op_sel_hi:[1,0,1]
	v_pk_fma_f32 v[10:11], v[228:229], v[206:207], v[10:11] op_sel:[0,1,0]
	v_pk_fma_f32 v[12:13], v[228:229], v[208:209], v[12:13] op_sel_hi:[1,0,1]
	v_pk_fma_f32 v[14:15], v[228:229], v[208:209], v[14:15] op_sel:[0,1,0]
	v_pk_mul_f32 v[116:117], v[0:1], v[218:219] op_sel_hi:[1,0]
	v_pk_fma_f32 v[116:117], v[2:3], v[218:219], v[116:117] op_sel:[0,1,0]
	v_pk_fma_f32 v[116:117], v[4:5], v[220:221], v[116:117] op_sel_hi:[1,0,1]
	v_pk_fma_f32 v[116:117], v[6:7], v[220:221], v[116:117] op_sel:[0,1,0]
	v_pk_fma_f32 v[116:117], v[8:9], v[222:223], v[116:117] op_sel_hi:[1,0,1]
	v_pk_fma_f32 v[116:117], v[10:11], v[222:223], v[116:117] op_sel:[0,1,0]
	v_pk_fma_f32 v[116:117], v[12:13], v[224:225], v[116:117] op_sel_hi:[1,0,1]
	v_pk_fma_f32 v[116:117], v[14:15], v[224:225], v[116:117] op_sel:[0,1,0]
	ds_read_b128 v[186:189], v20 offset:26112
	ds_read_b128 v[190:193], v20 offset:26128
	v_add_f32_dpp v240, v116, v116 quad_perm:[1,0,3,2] row_mask:0xf bank_mask:0xf bound_ctrl:1
	v_add_f32_dpp v241, v117, v117 quad_perm:[1,0,3,2] row_mask:0xf bank_mask:0xf bound_ctrl:1
	ds_read_b128 v[194:197], v20 offset:26368
	v_add_f32_dpp v240, v240, v240 quad_perm:[2,3,0,1] row_mask:0xf bank_mask:0xf bound_ctrl:1
	v_add_f32_dpp v241, v241, v241 quad_perm:[2,3,0,1] row_mask:0xf bank_mask:0xf bound_ctrl:1
	ds_read_b128 v[198:201], v20 offset:26384
	v_add_f32_dpp v240, v240, v240 row_half_mirror row_mask:0xf bank_mask:0xf bound_ctrl:1
	v_add_f32_dpp v241, v241, v241 row_half_mirror row_mask:0xf bank_mask:0xf bound_ctrl:1
	ds_read_b128 v[202:205], v20 offset:26624
	ds_read_b128 v[206:209], v20 offset:26640
	ds_read_b128 v[210:213], v20 offset:26880
	ds_read_b128 v[214:217], v20 offset:26896
	ds_read_b128 v[218:221], v20 offset:27136
	ds_read_b128 v[222:225], v20 offset:27152
	ds_read_b64 v[226:227], v22 offset:27392
	ds_write_b64 v21, v[240:241] offset:3840
	s_waitcnt lgkmcnt(12)
	v_pk_mul_f32 v[16:17], v[0:1], v[24:25] op_sel_hi:[1,0]
	v_pk_fma_f32 v[16:17], v[2:3], v[24:25], v[16:17] op_sel:[0,1,0]
	v_pk_fma_f32 v[16:17], v[4:5], v[26:27], v[16:17] op_sel_hi:[1,0,1]
	v_pk_fma_f32 v[16:17], v[6:7], v[26:27], v[16:17] op_sel:[0,1,0]
	v_pk_fma_f32 v[16:17], v[8:9], v[28:29], v[16:17] op_sel_hi:[1,0,1]
	v_pk_fma_f32 v[16:17], v[10:11], v[28:29], v[16:17] op_sel:[0,1,0]
	v_pk_fma_f32 v[16:17], v[12:13], v[30:31], v[16:17] op_sel_hi:[1,0,1]
	v_pk_fma_f32 v[16:17], v[14:15], v[30:31], v[16:17] op_sel:[0,1,0]
	v_pk_mul_f32 v[0:1], v[0:1], v[32:33] op_sel_hi:[1,0]
	v_pk_mul_f32 v[2:3], v[2:3], v[32:33] op_sel:[0,1]
	v_add_f32_dpp v16, v16, v16 quad_perm:[1,0,3,2] row_mask:0xf bank_mask:0xf bound_ctrl:1
	v_add_f32_dpp v17, v17, v17 quad_perm:[1,0,3,2] row_mask:0xf bank_mask:0xf bound_ctrl:1
	v_pk_mul_f32 v[4:5], v[4:5], v[34:35] op_sel_hi:[1,0]
	v_pk_mul_f32 v[6:7], v[6:7], v[34:35] op_sel:[0,1]
	v_add_f32_dpp v16, v16, v16 quad_perm:[2,3,0,1] row_mask:0xf bank_mask:0xf bound_ctrl:1
	v_add_f32_dpp v17, v17, v17 quad_perm:[2,3,0,1] row_mask:0xf bank_mask:0xf bound_ctrl:1
	v_pk_mul_f32 v[8:9], v[8:9], v[36:37] op_sel_hi:[1,0]
	v_pk_mul_f32 v[10:11], v[10:11], v[36:37] op_sel:[0,1]
	v_add_f32_dpp v228, v16, v16 row_half_mirror row_mask:0xf bank_mask:0xf bound_ctrl:1
	v_add_f32_dpp v229, v17, v17 row_half_mirror row_mask:0xf bank_mask:0xf bound_ctrl:1
	v_pk_mul_f32 v[12:13], v[12:13], v[38:39] op_sel_hi:[1,0]
	v_pk_mul_f32 v[14:15], v[14:15], v[38:39] op_sel:[0,1]
	v_pk_fma_f32 v[0:1], v[64:65], v[48:49], v[0:1] op_sel_hi:[1,0,1]
	v_pk_fma_f32 v[2:3], v[64:65], v[48:49], v[2:3] op_sel:[0,1,0]
	v_pk_fma_f32 v[4:5], v[64:65], v[50:51], v[4:5] op_sel_hi:[1,0,1]
	v_pk_fma_f32 v[6:7], v[64:65], v[50:51], v[6:7] op_sel:[0,1,0]
	v_pk_fma_f32 v[8:9], v[64:65], v[52:53], v[8:9] op_sel_hi:[1,0,1]
	v_pk_fma_f32 v[10:11], v[64:65], v[52:53], v[10:11] op_sel:[0,1,0]
	v_pk_fma_f32 v[12:13], v[64:65], v[54:55], v[12:13] op_sel_hi:[1,0,1]
	v_pk_fma_f32 v[14:15], v[64:65], v[54:55], v[14:15] op_sel:[0,1,0]
	v_pk_fma_f32 v[0:1], v[228:229], v[40:41], v[0:1] op_sel_hi:[1,0,1]
	v_pk_fma_f32 v[2:3], v[228:229], v[40:41], v[2:3] op_sel:[0,1,0]
	v_pk_fma_f32 v[4:5], v[228:229], v[42:43], v[4:5] op_sel_hi:[1,0,1]
	v_pk_fma_f32 v[6:7], v[228:229], v[42:43], v[6:7] op_sel:[0,1,0]
	v_pk_fma_f32 v[8:9], v[228:229], v[44:45], v[8:9] op_sel_hi:[1,0,1]
	v_pk_fma_f32 v[10:11], v[228:229], v[44:45], v[10:11] op_sel:[0,1,0]
	v_pk_fma_f32 v[12:13], v[228:229], v[46:47], v[12:13] op_sel_hi:[1,0,1]
	v_pk_fma_f32 v[14:15], v[228:229], v[46:47], v[14:15] op_sel:[0,1,0]
	v_pk_mul_f32 v[116:117], v[0:1], v[56:57] op_sel_hi:[1,0]
	v_pk_fma_f32 v[116:117], v[2:3], v[56:57], v[116:117] op_sel:[0,1,0]
; DEV float reduce8_dpp(float v) { v += DPPF(v, 0xB1); v += DPPF(v, 0x4E); v += DPPF(v, 0x141); return v; }
;     ...
;                     const float* bs = base0 + tok * 384;
;                     const f32x4 a0 = *(const f32x4*)bs, a1 = *(const f32x4*)(bs + 4);
;                     const f32x4 w0 = *(const f32x4*)(bs + 64), w1 = *(const f32x4*)(bs + 68);
;                     const f32x4 b0 = *(const f32x4*)(bs + 128), b1 = *(const f32x4*)(bs + 132);
;                     const f32x4 k0 = *(const f32x4*)(bs + 192), k1 = *(const f32x4*)(bs + 196);
;                     const f32x4 r0 = *(const f32x4*)(bs + 256), r1 = *(const f32x4*)(bs + 260);
;                     const f32x2 vv = *(const f32x2*)(op + (size_t)(buf * 32 + tok) * 384 + 320 + 2 * vp);
;                     const f32x2 av[4] = {(f32x2){a0[0], a0[1]}, (f32x2){a0[2], a0[3]}, (f32x2){a1[0], a1[1]}, (f32x2){a1[2], a1[3]}};
;                     const f32x2 wv[4] = {(f32x2){w0[0], w0[1]}, (f32x2){w0[2], w0[3]}, (f32x2){w1[0], w1[1]}, (f32x2){w1[2], w1[3]}};
;                     const f32x2 bv[4] = {(f32x2){b0[0], b0[1]}, (f32x2){b0[2], b0[3]}, (f32x2){b1[0], b1[1]}, (f32x2){b1[2], b1[3]}};
;                     const f32x2 kv[4] = {(f32x2){k0[0], k0[1]}, (f32x2){k0[2], k0[3]}, (f32x2){k1[0], k1[1]}, (f32x2){k1[2], k1[3]}};
;                     const f32x2 rv[4] = {(f32x2){r0[0], r0[1]}, (f32x2){r0[2], r0[3]}, (f32x2){r1[0], r1[1]}, (f32x2){r1[2], r1[3]}};
;                     float yo[2];
; #pragma unroll
;                     for (int i = 0; i < 2; ++i) {
;                         f32x2 sa2 = st[i][0] * av[0]; sa2 += st[i][1] * av[1]; sa2 += st[i][2] * av[2]; sa2 += st[i][3] * av[3];
;                         const float sa = reduce8_dpp(sa2[0] + sa2[1]);
;                         const float vi = vv[i];
;                         f32x2 y2 = (f32x2){0.f, 0.f};
; #pragma unroll
;                         for (int j = 0; j < 4; ++j) { st[i][j] = st[i][j] * wv[j] + sa * bv[j] + vi * kv[j]; y2 += st[i][j] * rv[j]; }
;                         yo[i] = reduce8_dpp(y2[0] + y2[1]);
;                     }
;                     if (kq == 0) *(f32x2*)(yb + tok * 64) = (f32x2){yo[0], yo[1]};
	v_pk_fma_f32 v[116:117], v[4:5], v[58:59], v[116:117] op_sel_hi:[1,0,1]
	v_pk_fma_f32 v[116:117], v[6:7], v[58:59], v[116:117] op_sel:[0,1,0]
	v_pk_fma_f32 v[116:117], v[8:9], v[60:61], v[116:117] op_sel_hi:[1,0,1]
	v_pk_fma_f32 v[116:117], v[10:11], v[60:61], v[116:117] op_sel:[0,1,0]
	v_pk_fma_f32 v[116:117], v[12:13], v[62:63], v[116:117] op_sel_hi:[1,0,1]
	v_pk_fma_f32 v[116:117], v[14:15], v[62:63], v[116:117] op_sel:[0,1,0]
	ds_read_b128 v[24:27], v20 offset:27648
	ds_read_b128 v[28:31], v20 offset:27664
	v_add_f32_dpp v240, v116, v116 quad_perm:[1,0,3,2] row_mask:0xf bank_mask:0xf bound_ctrl:1
	v_add_f32_dpp v241, v117, v117 quad_perm:[1,0,3,2] row_mask:0xf bank_mask:0xf bound_ctrl:1
	ds_read_b128 v[32:35], v20 offset:27904
	v_add_f32_dpp v240, v240, v240 quad_perm:[2,3,0,1] row_mask:0xf bank_mask:0xf bound_ctrl:1
	v_add_f32_dpp v241, v241, v241 quad_perm:[2,3,0,1] row_mask:0xf bank_mask:0xf bound_ctrl:1
	ds_read_b128 v[36:39], v20 offset:27920
	v_add_f32_dpp v240, v240, v240 row_half_mirror row_mask:0xf bank_mask:0xf bound_ctrl:1
	v_add_f32_dpp v241, v241, v241 row_half_mirror row_mask:0xf bank_mask:0xf bound_ctrl:1
	ds_read_b128 v[40:43], v20 offset:28160
	ds_read_b128 v[44:47], v20 offset:28176
	ds_read_b128 v[48:51], v20 offset:28416
	ds_read_b128 v[52:55], v20 offset:28432
	ds_read_b128 v[56:59], v20 offset:28672
	ds_read_b128 v[60:63], v20 offset:28688
	ds_read_b64 v[64:65], v22 offset:28928
	ds_write_b64 v21, v[240:241] offset:4096
	s_waitcnt lgkmcnt(12)
	v_pk_mul_f32 v[16:17], v[0:1], v[186:187] op_sel_hi:[1,0]
	v_pk_fma_f32 v[16:17], v[2:3], v[186:187], v[16:17] op_sel:[0,1,0]
	v_pk_fma_f32 v[16:17], v[4:5], v[188:189], v[16:17] op_sel_hi:[1,0,1]
	v_pk_fma_f32 v[16:17], v[6:7], v[188:189], v[16:17] op_sel:[0,1,0]
	v_pk_fma_f32 v[16:17], v[8:9], v[190:191], v[16:17] op_sel_hi:[1,0,1]
	v_pk_fma_f32 v[16:17], v[10:11], v[190:191], v[16:17] op_sel:[0,1,0]
	v_pk_fma_f32 v[16:17], v[12:13], v[192:193], v[16:17] op_sel_hi:[1,0,1]
	v_pk_fma_f32 v[16:17], v[14:15], v[192:193], v[16:17] op_sel:[0,1,0]
	v_pk_mul_f32 v[0:1], v[0:1], v[194:195] op_sel_hi:[1,0]
	v_pk_mul_f32 v[2:3], v[2:3], v[194:195] op_sel:[0,1]
	v_add_f32_dpp v16, v16, v16 quad_perm:[1,0,3,2] row_mask:0xf bank_mask:0xf bound_ctrl:1
	v_add_f32_dpp v17, v17, v17 quad_perm:[1,0,3,2] row_mask:0xf bank_mask:0xf bound_ctrl:1
	v_pk_mul_f32 v[4:5], v[4:5], v[196:197] op_sel_hi:[1,0]
	v_pk_mul_f32 v[6:7], v[6:7], v[196:197] op_sel:[0,1]
	v_add_f32_dpp v16, v16, v16 quad_perm:[2,3,0,1] row_mask:0xf bank_mask:0xf bound_ctrl:1
	v_add_f32_dpp v17, v17, v17 quad_perm:[2,3,0,1] row_mask:0xf bank_mask:0xf bound_ctrl:1
	v_pk_mul_f32 v[8:9], v[8:9], v[198:199] op_sel_hi:[1,0]
	v_pk_mul_f32 v[10:11], v[10:11], v[198:199] op_sel:[0,1]
	v_add_f32_dpp v228, v16, v16 row_half_mirror row_mask:0xf bank_mask:0xf bound_ctrl:1
	v_add_f32_dpp v229, v17, v17 row_half_mirror row_mask:0xf bank_mask:0xf bound_ctrl:1
	v_pk_mul_f32 v[12:13], v[12:13], v[200:201] op_sel_hi:[1,0]
	v_pk_mul_f32 v[14:15], v[14:15], v[200:201] op_sel:[0,1]
	v_pk_fma_f32 v[0:1], v[226:227], v[210:211], v[0:1] op_sel_hi:[1,0,1]
	v_pk_fma_f32 v[2:3], v[226:227], v[210:211], v[2:3] op_sel:[0,1,0]
	v_pk_fma_f32 v[4:5], v[226:227], v[212:213], v[4:5] op_sel_hi:[1,0,1]
	v_pk_fma_f32 v[6:7], v[226:227], v[212:213], v[6:7] op_sel:[0,1,0]
	v_pk_fma_f32 v[8:9], v[226:227], v[214:215], v[8:9] op_sel_hi:[1,0,1]
	v_pk_fma_f32 v[10:11], v[226:227], v[214:215], v[10:11] op_sel:[0,1,0]
	v_pk_fma_f32 v[12:13], v[226:227], v[216:217], v[12:13] op_sel_hi:[1,0,1]
	v_pk_fma_f32 v[14:15], v[226:227], v[216:217], v[14:15] op_sel:[0,1,0]
	v_pk_fma_f32 v[0:1], v[228:229], v[202:203], v[0:1] op_sel_hi:[1,0,1]
	v_pk_fma_f32 v[2:3], v[228:229], v[202:203], v[2:3] op_sel:[0,1,0]
	v_pk_fma_f32 v[4:5], v[228:229], v[204:205], v[4:5] op_sel_hi:[1,0,1]
	v_pk_fma_f32 v[6:7], v[228:229], v[204:205], v[6:7] op_sel:[0,1,0]
	v_pk_fma_f32 v[8:9], v[228:229], v[206:207], v[8:9] op_sel_hi:[1,0,1]
	v_pk_fma_f32 v[10:11], v[228:229], v[206:207], v[10:11] op_sel:[0,1,0]
	v_pk_fma_f32 v[12:13], v[228:229], v[208:209], v[12:13] op_sel_hi:[1,0,1]
	v_pk_fma_f32 v[14:15], v[228:229], v[208:209], v[14:15] op_sel:[0,1,0]
	v_pk_mul_f32 v[116:117], v[0:1], v[218:219] op_sel_hi:[1,0]
	v_pk_fma_f32 v[116:117], v[2:3], v[218:219], v[116:117] op_sel:[0,1,0]
	v_pk_fma_f32 v[116:117], v[4:5], v[220:221], v[116:117] op_sel_hi:[1,0,1]
	v_pk_fma_f32 v[116:117], v[6:7], v[220:221], v[116:117] op_sel:[0,1,0]
	v_pk_fma_f32 v[116:117], v[8:9], v[222:223], v[116:117] op_sel_hi:[1,0,1]
	v_pk_fma_f32 v[116:117], v[10:11], v[222:223], v[116:117] op_sel:[0,1,0]
	v_pk_fma_f32 v[116:117], v[12:13], v[224:225], v[116:117] op_sel_hi:[1,0,1]
	v_pk_fma_f32 v[116:117], v[14:15], v[224:225], v[116:117] op_sel:[0,1,0]
	ds_read_b128 v[186:189], v20 offset:29184
	ds_read_b128 v[190:193], v20 offset:29200
	v_add_f32_dpp v240, v116, v116 quad_perm:[1,0,3,2] row_mask:0xf bank_mask:0xf bound_ctrl:1
	v_add_f32_dpp v241, v117, v117 quad_perm:[1,0,3,2] row_mask:0xf bank_mask:0xf bound_ctrl:1
	ds_read_b128 v[194:197], v20 offset:29440
	v_add_f32_dpp v240, v240, v240 quad_perm:[2,3,0,1] row_mask:0xf bank_mask:0xf bound_ctrl:1
	v_add_f32_dpp v241, v241, v241 quad_perm:[2,3,0,1] row_mask:0xf bank_mask:0xf bound_ctrl:1
	ds_read_b128 v[198:201], v20 offset:29456
	v_add_f32_dpp v240, v240, v240 row_half_mirror row_mask:0xf bank_mask:0xf bound_ctrl:1
	v_add_f32_dpp v241, v241, v241 row_half_mirror row_mask:0xf bank_mask:0xf bound_ctrl:1
	ds_read_b128 v[202:205], v20 offset:29696
	ds_read_b128 v[206:209], v20 offset:29712
	ds_read_b128 v[210:213], v20 offset:29952
	ds_read_b128 v[214:217], v20 offset:29968
	ds_read_b128 v[218:221], v20 offset:30208
	ds_read_b128 v[222:225], v20 offset:30224
	ds_read_b64 v[226:227], v22 offset:30464
	ds_write_b64 v21, v[240:241] offset:4352
	s_waitcnt lgkmcnt(12)
; DEV float reduce8_dpp(float v) { v += DPPF(v, 0xB1); v += DPPF(v, 0x4E); v += DPPF(v, 0x141); return v; }
;     ...
;                     const float* bs = base0 + tok * 384;
;                     const f32x4 a0 = *(const f32x4*)bs, a1 = *(const f32x4*)(bs + 4);
;                     const f32x4 w0 = *(const f32x4*)(bs + 64), w1 = *(const f32x4*)(bs + 68);
;                     const f32x4 b0 = *(const f32x4*)(bs + 128), b1 = *(const f32x4*)(bs + 132);
;                     const f32x4 k0 = *(const f32x4*)(bs + 192), k1 = *(const f32x4*)(bs + 196);
;                     const f32x4 r0 = *(const f32x4*)(bs + 256), r1 = *(const f32x4*)(bs + 260);
;                     const f32x2 vv = *(const f32x2*)(op + (size_t)(buf * 32 + tok) * 384 + 320 + 2 * vp);
;                     const f32x2 av[4] = {(f32x2){a0[0], a0[1]}, (f32x2){a0[2], a0[3]}, (f32x2){a1[0], a1[1]}, (f32x2){a1[2], a1[3]}};
;                     const f32x2 wv[4] = {(f32x2){w0[0], w0[1]}, (f32x2){w0[2], w0[3]}, (f32x2){w1[0], w1[1]}, (f32x2){w1[2], w1[3]}};
;                     const f32x2 bv[4] = {(f32x2){b0[0], b0[1]}, (f32x2){b0[2], b0[3]}, (f32x2){b1[0], b1[1]}, (f32x2){b1[2], b1[3]}};
;                     const f32x2 kv[4] = {(f32x2){k0[0], k0[1]}, (f32x2){k0[2], k0[3]}, (f32x2){k1[0], k1[1]}, (f32x2){k1[2], k1[3]}};
;                     const f32x2 rv[4] = {(f32x2){r0[0], r0[1]}, (f32x2){r0[2], r0[3]}, (f32x2){r1[0], r1[1]}, (f32x2){r1[2], r1[3]}};
;                     float yo[2];
; #pragma unroll
;                     for (int i = 0; i < 2; ++i) {
;                         f32x2 sa2 = st[i][0] * av[0]; sa2 += st[i][1] * av[1]; sa2 += st[i][2] * av[2]; sa2 += st[i][3] * av[3];
;                         const float sa = reduce8_dpp(sa2[0] + sa2[1]);
;                         const float vi = vv[i];
;                         f32x2 y2 = (f32x2){0.f, 0.f};
; #pragma unroll
;                         for (int j = 0; j < 4; ++j) { st[i][j] = st[i][j] * wv[j] + sa * bv[j] + vi * kv[j]; y2 += st[i][j] * rv[j]; }
;                         yo[i] = reduce8_dpp(y2[0] + y2[1]);
;                     }
;                     if (kq == 0) *(f32x2*)(yb + tok * 64) = (f32x2){yo[0], yo[1]};
	v_pk_mul_f32 v[16:17], v[0:1], v[24:25] op_sel_hi:[1,0]
	v_pk_fma_f32 v[16:17], v[2:3], v[24:25], v[16:17] op_sel:[0,1,0]
	v_pk_fma_f32 v[16:17], v[4:5], v[26:27], v[16:17] op_sel_hi:[1,0,1]
	v_pk_fma_f32 v[16:17], v[6:7], v[26:27], v[16:17] op_sel:[0,1,0]
	v_pk_fma_f32 v[16:17], v[8:9], v[28:29], v[16:17] op_sel_hi:[1,0,1]
	v_pk_fma_f32 v[16:17], v[10:11], v[28:29], v[16:17] op_sel:[0,1,0]
	v_pk_fma_f32 v[16:17], v[12:13], v[30:31], v[16:17] op_sel_hi:[1,0,1]
	v_pk_fma_f32 v[16:17], v[14:15], v[30:31], v[16:17] op_sel:[0,1,0]
	v_pk_mul_f32 v[0:1], v[0:1], v[32:33] op_sel_hi:[1,0]
	v_pk_mul_f32 v[2:3], v[2:3], v[32:33] op_sel:[0,1]
	v_add_f32_dpp v16, v16, v16 quad_perm:[1,0,3,2] row_mask:0xf bank_mask:0xf bound_ctrl:1
	v_add_f32_dpp v17, v17, v17 quad_perm:[1,0,3,2] row_mask:0xf bank_mask:0xf bound_ctrl:1
	v_pk_mul_f32 v[4:5], v[4:5], v[34:35] op_sel_hi:[1,0]
	v_pk_mul_f32 v[6:7], v[6:7], v[34:35] op_sel:[0,1]
	v_add_f32_dpp v16, v16, v16 quad_perm:[2,3,0,1] row_mask:0xf bank_mask:0xf bound_ctrl:1
	v_add_f32_dpp v17, v17, v17 quad_perm:[2,3,0,1] row_mask:0xf bank_mask:0xf bound_ctrl:1
	v_pk_mul_f32 v[8:9], v[8:9], v[36:37] op_sel_hi:[1,0]
	v_pk_mul_f32 v[10:11], v[10:11], v[36:37] op_sel:[0,1]
	v_add_f32_dpp v228, v16, v16 row_half_mirror row_mask:0xf bank_mask:0xf bound_ctrl:1
	v_add_f32_dpp v229, v17, v17 row_half_mirror row_mask:0xf bank_mask:0xf bound_ctrl:1
	v_pk_mul_f32 v[12:13], v[12:13], v[38:39] op_sel_hi:[1,0]
	v_pk_mul_f32 v[14:15], v[14:15], v[38:39] op_sel:[0,1]
	v_pk_fma_f32 v[0:1], v[64:65], v[48:49], v[0:1] op_sel_hi:[1,0,1]
	v_pk_fma_f32 v[2:3], v[64:65], v[48:49], v[2:3] op_sel:[0,1,0]
	v_pk_fma_f32 v[4:5], v[64:65], v[50:51], v[4:5] op_sel_hi:[1,0,1]
	v_pk_fma_f32 v[6:7], v[64:65], v[50:51], v[6:7] op_sel:[0,1,0]
	v_pk_fma_f32 v[8:9], v[64:65], v[52:53], v[8:9] op_sel_hi:[1,0,1]
	v_pk_fma_f32 v[10:11], v[64:65], v[52:53], v[10:11] op_sel:[0,1,0]
	v_pk_fma_f32 v[12:13], v[64:65], v[54:55], v[12:13] op_sel_hi:[1,0,1]
	v_pk_fma_f32 v[14:15], v[64:65], v[54:55], v[14:15] op_sel:[0,1,0]
	v_pk_fma_f32 v[0:1], v[228:229], v[40:41], v[0:1] op_sel_hi:[1,0,1]
	v_pk_fma_f32 v[2:3], v[228:229], v[40:41], v[2:3] op_sel:[0,1,0]
	v_pk_fma_f32 v[4:5], v[228:229], v[42:43], v[4:5] op_sel_hi:[1,0,1]
	v_pk_fma_f32 v[6:7], v[228:229], v[42:43], v[6:7] op_sel:[0,1,0]
	v_pk_fma_f32 v[8:9], v[228:229], v[44:45], v[8:9] op_sel_hi:[1,0,1]
	v_pk_fma_f32 v[10:11], v[228:229], v[44:45], v[10:11] op_sel:[0,1,0]
	v_pk_fma_f32 v[12:13], v[228:229], v[46:47], v[12:13] op_sel_hi:[1,0,1]
	v_pk_fma_f32 v[14:15], v[228:229], v[46:47], v[14:15] op_sel:[0,1,0]
	v_pk_mul_f32 v[116:117], v[0:1], v[56:57] op_sel_hi:[1,0]
	v_pk_fma_f32 v[116:117], v[2:3], v[56:57], v[116:117] op_sel:[0,1,0]
	v_pk_fma_f32 v[116:117], v[4:5], v[58:59], v[116:117] op_sel_hi:[1,0,1]
	v_pk_fma_f32 v[116:117], v[6:7], v[58:59], v[116:117] op_sel:[0,1,0]
	v_pk_fma_f32 v[116:117], v[8:9], v[60:61], v[116:117] op_sel_hi:[1,0,1]
	v_pk_fma_f32 v[116:117], v[10:11], v[60:61], v[116:117] op_sel:[0,1,0]
	v_pk_fma_f32 v[116:117], v[12:13], v[62:63], v[116:117] op_sel_hi:[1,0,1]
	v_pk_fma_f32 v[116:117], v[14:15], v[62:63], v[116:117] op_sel:[0,1,0]
	ds_read_b128 v[24:27], v20 offset:30720
	ds_read_b128 v[28:31], v20 offset:30736
	v_add_f32_dpp v240, v116, v116 quad_perm:[1,0,3,2] row_mask:0xf bank_mask:0xf bound_ctrl:1
	v_add_f32_dpp v241, v117, v117 quad_perm:[1,0,3,2] row_mask:0xf bank_mask:0xf bound_ctrl:1
	ds_read_b128 v[32:35], v20 offset:30976
	v_add_f32_dpp v240, v240, v240 quad_perm:[2,3,0,1] row_mask:0xf bank_mask:0xf bound_ctrl:1
	v_add_f32_dpp v241, v241, v241 quad_perm:[2,3,0,1] row_mask:0xf bank_mask:0xf bound_ctrl:1
	ds_read_b128 v[36:39], v20 offset:30992
	v_add_f32_dpp v240, v240, v240 row_half_mirror row_mask:0xf bank_mask:0xf bound_ctrl:1
	v_add_f32_dpp v241, v241, v241 row_half_mirror row_mask:0xf bank_mask:0xf bound_ctrl:1
	ds_read_b128 v[40:43], v20 offset:31232
	ds_read_b128 v[44:47], v20 offset:31248
	ds_read_b128 v[48:51], v20 offset:31488
	ds_read_b128 v[52:55], v20 offset:31504
	ds_read_b128 v[56:59], v20 offset:31744
	ds_read_b128 v[60:63], v20 offset:31760
	ds_read_b64 v[64:65], v22 offset:32000
	ds_write_b64 v21, v[240:241] offset:4608
	s_waitcnt lgkmcnt(12)
	v_pk_mul_f32 v[16:17], v[0:1], v[186:187] op_sel_hi:[1,0]
	v_pk_fma_f32 v[16:17], v[2:3], v[186:187], v[16:17] op_sel:[0,1,0]
	v_pk_fma_f32 v[16:17], v[4:5], v[188:189], v[16:17] op_sel_hi:[1,0,1]
	v_pk_fma_f32 v[16:17], v[6:7], v[188:189], v[16:17] op_sel:[0,1,0]
	v_pk_fma_f32 v[16:17], v[8:9], v[190:191], v[16:17] op_sel_hi:[1,0,1]
	v_pk_fma_f32 v[16:17], v[10:11], v[190:191], v[16:17] op_sel:[0,1,0]
	v_pk_fma_f32 v[16:17], v[12:13], v[192:193], v[16:17] op_sel_hi:[1,0,1]
	v_pk_fma_f32 v[16:17], v[14:15], v[192:193], v[16:17] op_sel:[0,1,0]
	v_pk_mul_f32 v[0:1], v[0:1], v[194:195] op_sel_hi:[1,0]
	v_pk_mul_f32 v[2:3], v[2:3], v[194:195] op_sel:[0,1]
	v_add_f32_dpp v16, v16, v16 quad_perm:[1,0,3,2] row_mask:0xf bank_mask:0xf bound_ctrl:1
	v_add_f32_dpp v17, v17, v17 quad_perm:[1,0,3,2] row_mask:0xf bank_mask:0xf bound_ctrl:1
	v_pk_mul_f32 v[4:5], v[4:5], v[196:197] op_sel_hi:[1,0]
	v_pk_mul_f32 v[6:7], v[6:7], v[196:197] op_sel:[0,1]
	v_add_f32_dpp v16, v16, v16 quad_perm:[2,3,0,1] row_mask:0xf bank_mask:0xf bound_ctrl:1
	v_add_f32_dpp v17, v17, v17 quad_perm:[2,3,0,1] row_mask:0xf bank_mask:0xf bound_ctrl:1
	v_pk_mul_f32 v[8:9], v[8:9], v[198:199] op_sel_hi:[1,0]
	v_pk_mul_f32 v[10:11], v[10:11], v[198:199] op_sel:[0,1]
	v_add_f32_dpp v228, v16, v16 row_half_mirror row_mask:0xf bank_mask:0xf bound_ctrl:1
	v_add_f32_dpp v229, v17, v17 row_half_mirror row_mask:0xf bank_mask:0xf bound_ctrl:1
; DEV float reduce8_dpp(float v) { v += DPPF(v, 0xB1); v += DPPF(v, 0x4E); v += DPPF(v, 0x141); return v; }
;     ...
;                     const float* bs = base0 + tok * 384;
;                     const f32x4 a0 = *(const f32x4*)bs, a1 = *(const f32x4*)(bs + 4);
;                     const f32x4 w0 = *(const f32x4*)(bs + 64), w1 = *(const f32x4*)(bs + 68);
;                     const f32x4 b0 = *(const f32x4*)(bs + 128), b1 = *(const f32x4*)(bs + 132);
;                     const f32x4 k0 = *(const f32x4*)(bs + 192), k1 = *(const f32x4*)(bs + 196);
;                     const f32x4 r0 = *(const f32x4*)(bs + 256), r1 = *(const f32x4*)(bs + 260);
;                     const f32x2 vv = *(const f32x2*)(op + (size_t)(buf * 32 + tok) * 384 + 320 + 2 * vp);
;                     const f32x2 av[4] = {(f32x2){a0[0], a0[1]}, (f32x2){a0[2], a0[3]}, (f32x2){a1[0], a1[1]}, (f32x2){a1[2], a1[3]}};
;                     const f32x2 wv[4] = {(f32x2){w0[0], w0[1]}, (f32x2){w0[2], w0[3]}, (f32x2){w1[0], w1[1]}, (f32x2){w1[2], w1[3]}};
;                     const f32x2 bv[4] = {(f32x2){b0[0], b0[1]}, (f32x2){b0[2], b0[3]}, (f32x2){b1[0], b1[1]}, (f32x2){b1[2], b1[3]}};
;                     const f32x2 kv[4] = {(f32x2){k0[0], k0[1]}, (f32x2){k0[2], k0[3]}, (f32x2){k1[0], k1[1]}, (f32x2){k1[2], k1[3]}};
;                     const f32x2 rv[4] = {(f32x2){r0[0], r0[1]}, (f32x2){r0[2], r0[3]}, (f32x2){r1[0], r1[1]}, (f32x2){r1[2], r1[3]}};
;                     float yo[2];
; #pragma unroll
;                     for (int i = 0; i < 2; ++i) {
;                         f32x2 sa2 = st[i][0] * av[0]; sa2 += st[i][1] * av[1]; sa2 += st[i][2] * av[2]; sa2 += st[i][3] * av[3];
;                         const float sa = reduce8_dpp(sa2[0] + sa2[1]);
;                         const float vi = vv[i];
;                         f32x2 y2 = (f32x2){0.f, 0.f};
; #pragma unroll
;                         for (int j = 0; j < 4; ++j) { st[i][j] = st[i][j] * wv[j] + sa * bv[j] + vi * kv[j]; y2 += st[i][j] * rv[j]; }
;                         yo[i] = reduce8_dpp(y2[0] + y2[1]);
;                     }
;                     if (kq == 0) *(f32x2*)(yb + tok * 64) = (f32x2){yo[0], yo[1]};
	v_pk_mul_f32 v[12:13], v[12:13], v[200:201] op_sel_hi:[1,0]
	v_pk_mul_f32 v[14:15], v[14:15], v[200:201] op_sel:[0,1]
	v_pk_fma_f32 v[0:1], v[226:227], v[210:211], v[0:1] op_sel_hi:[1,0,1]
	v_pk_fma_f32 v[2:3], v[226:227], v[210:211], v[2:3] op_sel:[0,1,0]
	v_pk_fma_f32 v[4:5], v[226:227], v[212:213], v[4:5] op_sel_hi:[1,0,1]
	v_pk_fma_f32 v[6:7], v[226:227], v[212:213], v[6:7] op_sel:[0,1,0]
	v_pk_fma_f32 v[8:9], v[226:227], v[214:215], v[8:9] op_sel_hi:[1,0,1]
	v_pk_fma_f32 v[10:11], v[226:227], v[214:215], v[10:11] op_sel:[0,1,0]
	v_pk_fma_f32 v[12:13], v[226:227], v[216:217], v[12:13] op_sel_hi:[1,0,1]
	v_pk_fma_f32 v[14:15], v[226:227], v[216:217], v[14:15] op_sel:[0,1,0]
	v_pk_fma_f32 v[0:1], v[228:229], v[202:203], v[0:1] op_sel_hi:[1,0,1]
	v_pk_fma_f32 v[2:3], v[228:229], v[202:203], v[2:3] op_sel:[0,1,0]
	v_pk_fma_f32 v[4:5], v[228:229], v[204:205], v[4:5] op_sel_hi:[1,0,1]
	v_pk_fma_f32 v[6:7], v[228:229], v[204:205], v[6:7] op_sel:[0,1,0]
	v_pk_fma_f32 v[8:9], v[228:229], v[206:207], v[8:9] op_sel_hi:[1,0,1]
	v_pk_fma_f32 v[10:11], v[228:229], v[206:207], v[10:11] op_sel:[0,1,0]
	v_pk_fma_f32 v[12:13], v[228:229], v[208:209], v[12:13] op_sel_hi:[1,0,1]
	v_pk_fma_f32 v[14:15], v[228:229], v[208:209], v[14:15] op_sel:[0,1,0]
	v_pk_mul_f32 v[116:117], v[0:1], v[218:219] op_sel_hi:[1,0]
	v_pk_fma_f32 v[116:117], v[2:3], v[218:219], v[116:117] op_sel:[0,1,0]
	v_pk_fma_f32 v[116:117], v[4:5], v[220:221], v[116:117] op_sel_hi:[1,0,1]
	v_pk_fma_f32 v[116:117], v[6:7], v[220:221], v[116:117] op_sel:[0,1,0]
	v_pk_fma_f32 v[116:117], v[8:9], v[222:223], v[116:117] op_sel_hi:[1,0,1]
	v_pk_fma_f32 v[116:117], v[10:11], v[222:223], v[116:117] op_sel:[0,1,0]
	v_pk_fma_f32 v[116:117], v[12:13], v[224:225], v[116:117] op_sel_hi:[1,0,1]
	v_pk_fma_f32 v[116:117], v[14:15], v[224:225], v[116:117] op_sel:[0,1,0]
	ds_read_b128 v[186:189], v20 offset:32256
	ds_read_b128 v[190:193], v20 offset:32272
	v_add_f32_dpp v240, v116, v116 quad_perm:[1,0,3,2] row_mask:0xf bank_mask:0xf bound_ctrl:1
	v_add_f32_dpp v241, v117, v117 quad_perm:[1,0,3,2] row_mask:0xf bank_mask:0xf bound_ctrl:1
	ds_read_b128 v[194:197], v20 offset:32512
	v_add_f32_dpp v240, v240, v240 quad_perm:[2,3,0,1] row_mask:0xf bank_mask:0xf bound_ctrl:1
	v_add_f32_dpp v241, v241, v241 quad_perm:[2,3,0,1] row_mask:0xf bank_mask:0xf bound_ctrl:1
	ds_read_b128 v[198:201], v20 offset:32528
	v_add_f32_dpp v240, v240, v240 row_half_mirror row_mask:0xf bank_mask:0xf bound_ctrl:1
	v_add_f32_dpp v241, v241, v241 row_half_mirror row_mask:0xf bank_mask:0xf bound_ctrl:1
	ds_read_b128 v[202:205], v20 offset:32768
	ds_read_b128 v[206:209], v20 offset:32784
	ds_read_b128 v[210:213], v20 offset:33024
	ds_read_b128 v[214:217], v20 offset:33040
	ds_read_b128 v[218:221], v20 offset:33280
	ds_read_b128 v[222:225], v20 offset:33296
	ds_read_b64 v[226:227], v22 offset:33536
	ds_write_b64 v21, v[240:241] offset:4864
	s_waitcnt lgkmcnt(12)
	v_pk_mul_f32 v[16:17], v[0:1], v[24:25] op_sel_hi:[1,0]
	v_pk_fma_f32 v[16:17], v[2:3], v[24:25], v[16:17] op_sel:[0,1,0]
	v_pk_fma_f32 v[16:17], v[4:5], v[26:27], v[16:17] op_sel_hi:[1,0,1]
	v_pk_fma_f32 v[16:17], v[6:7], v[26:27], v[16:17] op_sel:[0,1,0]
	v_pk_fma_f32 v[16:17], v[8:9], v[28:29], v[16:17] op_sel_hi:[1,0,1]
	v_pk_fma_f32 v[16:17], v[10:11], v[28:29], v[16:17] op_sel:[0,1,0]
	v_pk_fma_f32 v[16:17], v[12:13], v[30:31], v[16:17] op_sel_hi:[1,0,1]
	v_pk_fma_f32 v[16:17], v[14:15], v[30:31], v[16:17] op_sel:[0,1,0]
	v_pk_mul_f32 v[0:1], v[0:1], v[32:33] op_sel_hi:[1,0]
	v_pk_mul_f32 v[2:3], v[2:3], v[32:33] op_sel:[0,1]
	v_add_f32_dpp v16, v16, v16 quad_perm:[1,0,3,2] row_mask:0xf bank_mask:0xf bound_ctrl:1
	v_add_f32_dpp v17, v17, v17 quad_perm:[1,0,3,2] row_mask:0xf bank_mask:0xf bound_ctrl:1
	v_pk_mul_f32 v[4:5], v[4:5], v[34:35] op_sel_hi:[1,0]
	v_pk_mul_f32 v[6:7], v[6:7], v[34:35] op_sel:[0,1]
	v_add_f32_dpp v16, v16, v16 quad_perm:[2,3,0,1] row_mask:0xf bank_mask:0xf bound_ctrl:1
	v_add_f32_dpp v17, v17, v17 quad_perm:[2,3,0,1] row_mask:0xf bank_mask:0xf bound_ctrl:1
	v_pk_mul_f32 v[8:9], v[8:9], v[36:37] op_sel_hi:[1,0]
	v_pk_mul_f32 v[10:11], v[10:11], v[36:37] op_sel:[0,1]
	v_add_f32_dpp v228, v16, v16 row_half_mirror row_mask:0xf bank_mask:0xf bound_ctrl:1
	v_add_f32_dpp v229, v17, v17 row_half_mirror row_mask:0xf bank_mask:0xf bound_ctrl:1
	v_pk_mul_f32 v[12:13], v[12:13], v[38:39] op_sel_hi:[1,0]
	v_pk_mul_f32 v[14:15], v[14:15], v[38:39] op_sel:[0,1]
	v_pk_fma_f32 v[0:1], v[64:65], v[48:49], v[0:1] op_sel_hi:[1,0,1]
	v_pk_fma_f32 v[2:3], v[64:65], v[48:49], v[2:3] op_sel:[0,1,0]
	v_pk_fma_f32 v[4:5], v[64:65], v[50:51], v[4:5] op_sel_hi:[1,0,1]
	v_pk_fma_f32 v[6:7], v[64:65], v[50:51], v[6:7] op_sel:[0,1,0]
	v_pk_fma_f32 v[8:9], v[64:65], v[52:53], v[8:9] op_sel_hi:[1,0,1]
	v_pk_fma_f32 v[10:11], v[64:65], v[52:53], v[10:11] op_sel:[0,1,0]
	v_pk_fma_f32 v[12:13], v[64:65], v[54:55], v[12:13] op_sel_hi:[1,0,1]
	v_pk_fma_f32 v[14:15], v[64:65], v[54:55], v[14:15] op_sel:[0,1,0]
	v_pk_fma_f32 v[0:1], v[228:229], v[40:41], v[0:1] op_sel_hi:[1,0,1]
	v_pk_fma_f32 v[2:3], v[228:229], v[40:41], v[2:3] op_sel:[0,1,0]
	v_pk_fma_f32 v[4:5], v[228:229], v[42:43], v[4:5] op_sel_hi:[1,0,1]
	v_pk_fma_f32 v[6:7], v[228:229], v[42:43], v[6:7] op_sel:[0,1,0]
	v_pk_fma_f32 v[8:9], v[228:229], v[44:45], v[8:9] op_sel_hi:[1,0,1]
	v_pk_fma_f32 v[10:11], v[228:229], v[44:45], v[10:11] op_sel:[0,1,0]
	v_pk_fma_f32 v[12:13], v[228:229], v[46:47], v[12:13] op_sel_hi:[1,0,1]
	v_pk_fma_f32 v[14:15], v[228:229], v[46:47], v[14:15] op_sel:[0,1,0]
	v_pk_mul_f32 v[116:117], v[0:1], v[56:57] op_sel_hi:[1,0]
	v_pk_fma_f32 v[116:117], v[2:3], v[56:57], v[116:117] op_sel:[0,1,0]
; DEV float reduce8_dpp(float v) { v += DPPF(v, 0xB1); v += DPPF(v, 0x4E); v += DPPF(v, 0x141); return v; }
;     ...
; #pragma unroll 32
;                 for (int tok = 0; tok < 32; ++tok) {
;                     const float* bs = base0 + tok * 384;
;                     const f32x4 a0 = *(const f32x4*)bs, a1 = *(const f32x4*)(bs + 4);
;                     const f32x4 w0 = *(const f32x4*)(bs + 64), w1 = *(const f32x4*)(bs + 68);
;                     const f32x4 b0 = *(const f32x4*)(bs + 128), b1 = *(const f32x4*)(bs + 132);
;                     const f32x4 k0 = *(const f32x4*)(bs + 192), k1 = *(const f32x4*)(bs + 196);
;                     const f32x4 r0 = *(const f32x4*)(bs + 256), r1 = *(const f32x4*)(bs + 260);
;                     const f32x2 vv = *(const f32x2*)(op + (size_t)(buf * 32 + tok) * 384 + 320 + 2 * vp);
;                     const f32x2 av[4] = {(f32x2){a0[0], a0[1]}, (f32x2){a0[2], a0[3]}, (f32x2){a1[0], a1[1]}, (f32x2){a1[2], a1[3]}};
;                     const f32x2 wv[4] = {(f32x2){w0[0], w0[1]}, (f32x2){w0[2], w0[3]}, (f32x2){w1[0], w1[1]}, (f32x2){w1[2], w1[3]}};
;                     const f32x2 bv[4] = {(f32x2){b0[0], b0[1]}, (f32x2){b0[2], b0[3]}, (f32x2){b1[0], b1[1]}, (f32x2){b1[2], b1[3]}};
;                     const f32x2 kv[4] = {(f32x2){k0[0], k0[1]}, (f32x2){k0[2], k0[3]}, (f32x2){k1[0], k1[1]}, (f32x2){k1[2], k1[3]}};
;                     const f32x2 rv[4] = {(f32x2){r0[0], r0[1]}, (f32x2){r0[2], r0[3]}, (f32x2){r1[0], r1[1]}, (f32x2){r1[2], r1[3]}};
;                     float yo[2];
; #pragma unroll
;                     for (int i = 0; i < 2; ++i) {
;                         f32x2 sa2 = st[i][0] * av[0]; sa2 += st[i][1] * av[1]; sa2 += st[i][2] * av[2]; sa2 += st[i][3] * av[3];
;                         const float sa = reduce8_dpp(sa2[0] + sa2[1]);
;                         const float vi = vv[i];
;                         f32x2 y2 = (f32x2){0.f, 0.f};
; #pragma unroll
;                         for (int j = 0; j < 4; ++j) { st[i][j] = st[i][j] * wv[j] + sa * bv[j] + vi * kv[j]; y2 += st[i][j] * rv[j]; }
;                         yo[i] = reduce8_dpp(y2[0] + y2[1]);
;                     }
;                     if (kq == 0) *(f32x2*)(yb + tok * 64) = (f32x2){yo[0], yo[1]};
;                 }
	v_pk_fma_f32 v[116:117], v[4:5], v[58:59], v[116:117] op_sel_hi:[1,0,1]
	v_pk_fma_f32 v[116:117], v[6:7], v[58:59], v[116:117] op_sel:[0,1,0]
	v_pk_fma_f32 v[116:117], v[8:9], v[60:61], v[116:117] op_sel_hi:[1,0,1]
	v_pk_fma_f32 v[116:117], v[10:11], v[60:61], v[116:117] op_sel:[0,1,0]
	v_pk_fma_f32 v[116:117], v[12:13], v[62:63], v[116:117] op_sel_hi:[1,0,1]
	v_pk_fma_f32 v[116:117], v[14:15], v[62:63], v[116:117] op_sel:[0,1,0]
	ds_read_b128 v[24:27], v20 offset:33792
	ds_read_b128 v[28:31], v20 offset:33808
	v_add_f32_dpp v240, v116, v116 quad_perm:[1,0,3,2] row_mask:0xf bank_mask:0xf bound_ctrl:1
	v_add_f32_dpp v241, v117, v117 quad_perm:[1,0,3,2] row_mask:0xf bank_mask:0xf bound_ctrl:1
	ds_read_b128 v[32:35], v20 offset:34048
	v_add_f32_dpp v240, v240, v240 quad_perm:[2,3,0,1] row_mask:0xf bank_mask:0xf bound_ctrl:1
	v_add_f32_dpp v241, v241, v241 quad_perm:[2,3,0,1] row_mask:0xf bank_mask:0xf bound_ctrl:1
	ds_read_b128 v[36:39], v20 offset:34064
	v_add_f32_dpp v240, v240, v240 row_half_mirror row_mask:0xf bank_mask:0xf bound_ctrl:1
	v_add_f32_dpp v241, v241, v241 row_half_mirror row_mask:0xf bank_mask:0xf bound_ctrl:1
	ds_read_b128 v[40:43], v20 offset:34304
	ds_read_b128 v[44:47], v20 offset:34320
	ds_read_b128 v[48:51], v20 offset:34560
	ds_read_b128 v[52:55], v20 offset:34576
	ds_read_b128 v[56:59], v20 offset:34816
	ds_read_b128 v[60:63], v20 offset:34832
	ds_read_b64 v[64:65], v22 offset:35072
	ds_write_b64 v21, v[240:241] offset:5120
	s_waitcnt lgkmcnt(12)
	v_pk_mul_f32 v[16:17], v[0:1], v[186:187] op_sel_hi:[1,0]
	v_pk_fma_f32 v[16:17], v[2:3], v[186:187], v[16:17] op_sel:[0,1,0]
	v_pk_fma_f32 v[16:17], v[4:5], v[188:189], v[16:17] op_sel_hi:[1,0,1]
	v_pk_fma_f32 v[16:17], v[6:7], v[188:189], v[16:17] op_sel:[0,1,0]
	v_pk_fma_f32 v[16:17], v[8:9], v[190:191], v[16:17] op_sel_hi:[1,0,1]
	v_pk_fma_f32 v[16:17], v[10:11], v[190:191], v[16:17] op_sel:[0,1,0]
	v_pk_fma_f32 v[16:17], v[12:13], v[192:193], v[16:17] op_sel_hi:[1,0,1]
	v_pk_fma_f32 v[16:17], v[14:15], v[192:193], v[16:17] op_sel:[0,1,0]
	v_pk_mul_f32 v[0:1], v[0:1], v[194:195] op_sel_hi:[1,0]
	v_pk_mul_f32 v[2:3], v[2:3], v[194:195] op_sel:[0,1]
	v_add_f32_dpp v16, v16, v16 quad_perm:[1,0,3,2] row_mask:0xf bank_mask:0xf bound_ctrl:1
	v_add_f32_dpp v17, v17, v17 quad_perm:[1,0,3,2] row_mask:0xf bank_mask:0xf bound_ctrl:1
	v_pk_mul_f32 v[4:5], v[4:5], v[196:197] op_sel_hi:[1,0]
	v_pk_mul_f32 v[6:7], v[6:7], v[196:197] op_sel:[0,1]
	v_add_f32_dpp v16, v16, v16 quad_perm:[2,3,0,1] row_mask:0xf bank_mask:0xf bound_ctrl:1
	v_add_f32_dpp v17, v17, v17 quad_perm:[2,3,0,1] row_mask:0xf bank_mask:0xf bound_ctrl:1
	v_pk_mul_f32 v[8:9], v[8:9], v[198:199] op_sel_hi:[1,0]
	v_pk_mul_f32 v[10:11], v[10:11], v[198:199] op_sel:[0,1]
	v_add_f32_dpp v228, v16, v16 row_half_mirror row_mask:0xf bank_mask:0xf bound_ctrl:1
	v_add_f32_dpp v229, v17, v17 row_half_mirror row_mask:0xf bank_mask:0xf bound_ctrl:1
	v_pk_mul_f32 v[12:13], v[12:13], v[200:201] op_sel_hi:[1,0]
	v_pk_mul_f32 v[14:15], v[14:15], v[200:201] op_sel:[0,1]
	v_pk_fma_f32 v[0:1], v[226:227], v[210:211], v[0:1] op_sel_hi:[1,0,1]
	v_pk_fma_f32 v[2:3], v[226:227], v[210:211], v[2:3] op_sel:[0,1,0]
	v_pk_fma_f32 v[4:5], v[226:227], v[212:213], v[4:5] op_sel_hi:[1,0,1]
	v_pk_fma_f32 v[6:7], v[226:227], v[212:213], v[6:7] op_sel:[0,1,0]
	v_pk_fma_f32 v[8:9], v[226:227], v[214:215], v[8:9] op_sel_hi:[1,0,1]
	v_pk_fma_f32 v[10:11], v[226:227], v[214:215], v[10:11] op_sel:[0,1,0]
	v_pk_fma_f32 v[12:13], v[226:227], v[216:217], v[12:13] op_sel_hi:[1,0,1]
	v_pk_fma_f32 v[14:15], v[226:227], v[216:217], v[14:15] op_sel:[0,1,0]
	v_pk_fma_f32 v[0:1], v[228:229], v[202:203], v[0:1] op_sel_hi:[1,0,1]
	v_pk_fma_f32 v[2:3], v[228:229], v[202:203], v[2:3] op_sel:[0,1,0]
	v_pk_fma_f32 v[4:5], v[228:229], v[204:205], v[4:5] op_sel_hi:[1,0,1]
	v_pk_fma_f32 v[6:7], v[228:229], v[204:205], v[6:7] op_sel:[0,1,0]
	v_pk_fma_f32 v[8:9], v[228:229], v[206:207], v[8:9] op_sel_hi:[1,0,1]
	v_pk_fma_f32 v[10:11], v[228:229], v[206:207], v[10:11] op_sel:[0,1,0]
	v_pk_fma_f32 v[12:13], v[228:229], v[208:209], v[12:13] op_sel_hi:[1,0,1]
	v_pk_fma_f32 v[14:15], v[228:229], v[208:209], v[14:15] op_sel:[0,1,0]
	v_pk_mul_f32 v[116:117], v[0:1], v[218:219] op_sel_hi:[1,0]
	v_pk_fma_f32 v[116:117], v[2:3], v[218:219], v[116:117] op_sel:[0,1,0]
	v_pk_fma_f32 v[116:117], v[4:5], v[220:221], v[116:117] op_sel_hi:[1,0,1]
	v_pk_fma_f32 v[116:117], v[6:7], v[220:221], v[116:117] op_sel:[0,1,0]
	v_pk_fma_f32 v[116:117], v[8:9], v[222:223], v[116:117] op_sel_hi:[1,0,1]
	v_pk_fma_f32 v[116:117], v[10:11], v[222:223], v[116:117] op_sel:[0,1,0]
	v_pk_fma_f32 v[116:117], v[12:13], v[224:225], v[116:117] op_sel_hi:[1,0,1]
	v_pk_fma_f32 v[116:117], v[14:15], v[224:225], v[116:117] op_sel:[0,1,0]
	ds_read_b128 v[186:189], v20 offset:35328
	ds_read_b128 v[190:193], v20 offset:35344
	v_add_f32_dpp v240, v116, v116 quad_perm:[1,0,3,2] row_mask:0xf bank_mask:0xf bound_ctrl:1
	v_add_f32_dpp v241, v117, v117 quad_perm:[1,0,3,2] row_mask:0xf bank_mask:0xf bound_ctrl:1
	ds_read_b128 v[194:197], v20 offset:35584
	v_add_f32_dpp v240, v240, v240 quad_perm:[2,3,0,1] row_mask:0xf bank_mask:0xf bound_ctrl:1
	v_add_f32_dpp v241, v241, v241 quad_perm:[2,3,0,1] row_mask:0xf bank_mask:0xf bound_ctrl:1
	ds_read_b128 v[198:201], v20 offset:35600
	v_add_f32_dpp v240, v240, v240 row_half_mirror row_mask:0xf bank_mask:0xf bound_ctrl:1
	v_add_f32_dpp v241, v241, v241 row_half_mirror row_mask:0xf bank_mask:0xf bound_ctrl:1
	ds_read_b128 v[202:205], v20 offset:35840
	ds_read_b128 v[206:209], v20 offset:35856
	ds_read_b128 v[210:213], v20 offset:36096
	ds_read_b128 v[214:217], v20 offset:36112
	ds_read_b128 v[218:221], v20 offset:36352
	ds_read_b128 v[222:225], v20 offset:36368
	ds_read_b64 v[226:227], v22 offset:36608
	ds_write_b64 v21, v[240:241] offset:5376
	s_waitcnt lgkmcnt(12)
; DEV float reduce8_dpp(float v) { v += DPPF(v, 0xB1); v += DPPF(v, 0x4E); v += DPPF(v, 0x141); return v; }
;     ...
; #pragma unroll 32
;                 for (int tok = 0; tok < 32; ++tok) {
;                     const float* bs = base0 + tok * 384;
;                     const f32x4 a0 = *(const f32x4*)bs, a1 = *(const f32x4*)(bs + 4);
;                     const f32x4 w0 = *(const f32x4*)(bs + 64), w1 = *(const f32x4*)(bs + 68);
;                     const f32x4 b0 = *(const f32x4*)(bs + 128), b1 = *(const f32x4*)(bs + 132);
;                     const f32x4 k0 = *(const f32x4*)(bs + 192), k1 = *(const f32x4*)(bs + 196);
;                     const f32x4 r0 = *(const f32x4*)(bs + 256), r1 = *(const f32x4*)(bs + 260);
;                     const f32x2 vv = *(const f32x2*)(op + (size_t)(buf * 32 + tok) * 384 + 320 + 2 * vp);
;                     const f32x2 av[4] = {(f32x2){a0[0], a0[1]}, (f32x2){a0[2], a0[3]}, (f32x2){a1[0], a1[1]}, (f32x2){a1[2], a1[3]}};
;                     const f32x2 wv[4] = {(f32x2){w0[0], w0[1]}, (f32x2){w0[2], w0[3]}, (f32x2){w1[0], w1[1]}, (f32x2){w1[2], w1[3]}};
;                     const f32x2 bv[4] = {(f32x2){b0[0], b0[1]}, (f32x2){b0[2], b0[3]}, (f32x2){b1[0], b1[1]}, (f32x2){b1[2], b1[3]}};
;                     const f32x2 kv[4] = {(f32x2){k0[0], k0[1]}, (f32x2){k0[2], k0[3]}, (f32x2){k1[0], k1[1]}, (f32x2){k1[2], k1[3]}};
;                     const f32x2 rv[4] = {(f32x2){r0[0], r0[1]}, (f32x2){r0[2], r0[3]}, (f32x2){r1[0], r1[1]}, (f32x2){r1[2], r1[3]}};
;                     float yo[2];
; #pragma unroll
;                     for (int i = 0; i < 2; ++i) {
;                         f32x2 sa2 = st[i][0] * av[0]; sa2 += st[i][1] * av[1]; sa2 += st[i][2] * av[2]; sa2 += st[i][3] * av[3];
;                         const float sa = reduce8_dpp(sa2[0] + sa2[1]);
;                         const float vi = vv[i];
;                         f32x2 y2 = (f32x2){0.f, 0.f};
; #pragma unroll
;                         for (int j = 0; j < 4; ++j) { st[i][j] = st[i][j] * wv[j] + sa * bv[j] + vi * kv[j]; y2 += st[i][j] * rv[j]; }
;                         yo[i] = reduce8_dpp(y2[0] + y2[1]);
;                     }
;                     if (kq == 0) *(f32x2*)(yb + tok * 64) = (f32x2){yo[0], yo[1]};
;                 }
	v_pk_mul_f32 v[16:17], v[0:1], v[24:25] op_sel_hi:[1,0]
	v_pk_fma_f32 v[16:17], v[2:3], v[24:25], v[16:17] op_sel:[0,1,0]
	v_pk_fma_f32 v[16:17], v[4:5], v[26:27], v[16:17] op_sel_hi:[1,0,1]
	v_pk_fma_f32 v[16:17], v[6:7], v[26:27], v[16:17] op_sel:[0,1,0]
	v_pk_fma_f32 v[16:17], v[8:9], v[28:29], v[16:17] op_sel_hi:[1,0,1]
	v_pk_fma_f32 v[16:17], v[10:11], v[28:29], v[16:17] op_sel:[0,1,0]
	v_pk_fma_f32 v[16:17], v[12:13], v[30:31], v[16:17] op_sel_hi:[1,0,1]
	v_pk_fma_f32 v[16:17], v[14:15], v[30:31], v[16:17] op_sel:[0,1,0]
	v_pk_mul_f32 v[0:1], v[0:1], v[32:33] op_sel_hi:[1,0]
	v_pk_mul_f32 v[2:3], v[2:3], v[32:33] op_sel:[0,1]
	v_add_f32_dpp v16, v16, v16 quad_perm:[1,0,3,2] row_mask:0xf bank_mask:0xf bound_ctrl:1
	v_add_f32_dpp v17, v17, v17 quad_perm:[1,0,3,2] row_mask:0xf bank_mask:0xf bound_ctrl:1
	v_pk_mul_f32 v[4:5], v[4:5], v[34:35] op_sel_hi:[1,0]
	v_pk_mul_f32 v[6:7], v[6:7], v[34:35] op_sel:[0,1]
	v_add_f32_dpp v16, v16, v16 quad_perm:[2,3,0,1] row_mask:0xf bank_mask:0xf bound_ctrl:1
	v_add_f32_dpp v17, v17, v17 quad_perm:[2,3,0,1] row_mask:0xf bank_mask:0xf bound_ctrl:1
	v_pk_mul_f32 v[8:9], v[8:9], v[36:37] op_sel_hi:[1,0]
	v_pk_mul_f32 v[10:11], v[10:11], v[36:37] op_sel:[0,1]
	v_add_f32_dpp v228, v16, v16 row_half_mirror row_mask:0xf bank_mask:0xf bound_ctrl:1
	v_add_f32_dpp v229, v17, v17 row_half_mirror row_mask:0xf bank_mask:0xf bound_ctrl:1
	v_pk_mul_f32 v[12:13], v[12:13], v[38:39] op_sel_hi:[1,0]
	v_pk_mul_f32 v[14:15], v[14:15], v[38:39] op_sel:[0,1]
	v_pk_fma_f32 v[0:1], v[64:65], v[48:49], v[0:1] op_sel_hi:[1,0,1]
	v_pk_fma_f32 v[2:3], v[64:65], v[48:49], v[2:3] op_sel:[0,1,0]
	v_pk_fma_f32 v[4:5], v[64:65], v[50:51], v[4:5] op_sel_hi:[1,0,1]
	v_pk_fma_f32 v[6:7], v[64:65], v[50:51], v[6:7] op_sel:[0,1,0]
	v_pk_fma_f32 v[8:9], v[64:65], v[52:53], v[8:9] op_sel_hi:[1,0,1]
	v_pk_fma_f32 v[10:11], v[64:65], v[52:53], v[10:11] op_sel:[0,1,0]
	v_pk_fma_f32 v[12:13], v[64:65], v[54:55], v[12:13] op_sel_hi:[1,0,1]
	v_pk_fma_f32 v[14:15], v[64:65], v[54:55], v[14:15] op_sel:[0,1,0]
	v_pk_fma_f32 v[0:1], v[228:229], v[40:41], v[0:1] op_sel_hi:[1,0,1]
	v_pk_fma_f32 v[2:3], v[228:229], v[40:41], v[2:3] op_sel:[0,1,0]
	v_pk_fma_f32 v[4:5], v[228:229], v[42:43], v[4:5] op_sel_hi:[1,0,1]
	v_pk_fma_f32 v[6:7], v[228:229], v[42:43], v[6:7] op_sel:[0,1,0]
	v_pk_fma_f32 v[8:9], v[228:229], v[44:45], v[8:9] op_sel_hi:[1,0,1]
	v_pk_fma_f32 v[10:11], v[228:229], v[44:45], v[10:11] op_sel:[0,1,0]
	v_pk_fma_f32 v[12:13], v[228:229], v[46:47], v[12:13] op_sel_hi:[1,0,1]
	v_pk_fma_f32 v[14:15], v[228:229], v[46:47], v[14:15] op_sel:[0,1,0]
	v_pk_mul_f32 v[116:117], v[0:1], v[56:57] op_sel_hi:[1,0]
	v_pk_fma_f32 v[116:117], v[2:3], v[56:57], v[116:117] op_sel:[0,1,0]
	v_pk_fma_f32 v[116:117], v[4:5], v[58:59], v[116:117] op_sel_hi:[1,0,1]
	v_pk_fma_f32 v[116:117], v[6:7], v[58:59], v[116:117] op_sel:[0,1,0]
	v_pk_fma_f32 v[116:117], v[8:9], v[60:61], v[116:117] op_sel_hi:[1,0,1]
	v_pk_fma_f32 v[116:117], v[10:11], v[60:61], v[116:117] op_sel:[0,1,0]
	v_pk_fma_f32 v[116:117], v[12:13], v[62:63], v[116:117] op_sel_hi:[1,0,1]
	v_pk_fma_f32 v[116:117], v[14:15], v[62:63], v[116:117] op_sel:[0,1,0]
	ds_read_b128 v[24:27], v20 offset:36864
	ds_read_b128 v[28:31], v20 offset:36880
	v_add_f32_dpp v240, v116, v116 quad_perm:[1,0,3,2] row_mask:0xf bank_mask:0xf bound_ctrl:1
	v_add_f32_dpp v241, v117, v117 quad_perm:[1,0,3,2] row_mask:0xf bank_mask:0xf bound_ctrl:1
	ds_read_b128 v[32:35], v20 offset:37120
	v_add_f32_dpp v240, v240, v240 quad_perm:[2,3,0,1] row_mask:0xf bank_mask:0xf bound_ctrl:1
	v_add_f32_dpp v241, v241, v241 quad_perm:[2,3,0,1] row_mask:0xf bank_mask:0xf bound_ctrl:1
	ds_read_b128 v[36:39], v20 offset:37136
	v_add_f32_dpp v240, v240, v240 row_half_mirror row_mask:0xf bank_mask:0xf bound_ctrl:1
	v_add_f32_dpp v241, v241, v241 row_half_mirror row_mask:0xf bank_mask:0xf bound_ctrl:1
	ds_read_b128 v[40:43], v20 offset:37376
	ds_read_b128 v[44:47], v20 offset:37392
	ds_read_b128 v[48:51], v20 offset:37632
	ds_read_b128 v[52:55], v20 offset:37648
	ds_read_b128 v[56:59], v20 offset:37888
	ds_read_b128 v[60:63], v20 offset:37904
	ds_read_b64 v[64:65], v22 offset:38144
	ds_write_b64 v21, v[240:241] offset:5632
	s_waitcnt lgkmcnt(12)
	v_pk_mul_f32 v[16:17], v[0:1], v[186:187] op_sel_hi:[1,0]
	v_pk_fma_f32 v[16:17], v[2:3], v[186:187], v[16:17] op_sel:[0,1,0]
	v_pk_fma_f32 v[16:17], v[4:5], v[188:189], v[16:17] op_sel_hi:[1,0,1]
	v_pk_fma_f32 v[16:17], v[6:7], v[188:189], v[16:17] op_sel:[0,1,0]
	v_pk_fma_f32 v[16:17], v[8:9], v[190:191], v[16:17] op_sel_hi:[1,0,1]
	v_pk_fma_f32 v[16:17], v[10:11], v[190:191], v[16:17] op_sel:[0,1,0]
	v_pk_fma_f32 v[16:17], v[12:13], v[192:193], v[16:17] op_sel_hi:[1,0,1]
	v_pk_fma_f32 v[16:17], v[14:15], v[192:193], v[16:17] op_sel:[0,1,0]
	v_pk_mul_f32 v[0:1], v[0:1], v[194:195] op_sel_hi:[1,0]
	v_pk_mul_f32 v[2:3], v[2:3], v[194:195] op_sel:[0,1]
	v_add_f32_dpp v16, v16, v16 quad_perm:[1,0,3,2] row_mask:0xf bank_mask:0xf bound_ctrl:1
	v_add_f32_dpp v17, v17, v17 quad_perm:[1,0,3,2] row_mask:0xf bank_mask:0xf bound_ctrl:1
	v_pk_mul_f32 v[4:5], v[4:5], v[196:197] op_sel_hi:[1,0]
	v_pk_mul_f32 v[6:7], v[6:7], v[196:197] op_sel:[0,1]
	v_add_f32_dpp v16, v16, v16 quad_perm:[2,3,0,1] row_mask:0xf bank_mask:0xf bound_ctrl:1
	v_add_f32_dpp v17, v17, v17 quad_perm:[2,3,0,1] row_mask:0xf bank_mask:0xf bound_ctrl:1
	v_pk_mul_f32 v[8:9], v[8:9], v[198:199] op_sel_hi:[1,0]
	v_pk_mul_f32 v[10:11], v[10:11], v[198:199] op_sel:[0,1]
	v_add_f32_dpp v228, v16, v16 row_half_mirror row_mask:0xf bank_mask:0xf bound_ctrl:1
	v_add_f32_dpp v229, v17, v17 row_half_mirror row_mask:0xf bank_mask:0xf bound_ctrl:1
; DEV float reduce8_dpp(float v) { v += DPPF(v, 0xB1); v += DPPF(v, 0x4E); v += DPPF(v, 0x141); return v; }
;     ...
; #pragma unroll 32
;                 for (int tok = 0; tok < 32; ++tok) {
;                     const float* bs = base0 + tok * 384;
;                     const f32x4 a0 = *(const f32x4*)bs, a1 = *(const f32x4*)(bs + 4);
;                     const f32x4 w0 = *(const f32x4*)(bs + 64), w1 = *(const f32x4*)(bs + 68);
;                     const f32x4 b0 = *(const f32x4*)(bs + 128), b1 = *(const f32x4*)(bs + 132);
;                     const f32x4 k0 = *(const f32x4*)(bs + 192), k1 = *(const f32x4*)(bs + 196);
;                     const f32x4 r0 = *(const f32x4*)(bs + 256), r1 = *(const f32x4*)(bs + 260);
;                     const f32x2 vv = *(const f32x2*)(op + (size_t)(buf * 32 + tok) * 384 + 320 + 2 * vp);
;                     const f32x2 av[4] = {(f32x2){a0[0], a0[1]}, (f32x2){a0[2], a0[3]}, (f32x2){a1[0], a1[1]}, (f32x2){a1[2], a1[3]}};
;                     const f32x2 wv[4] = {(f32x2){w0[0], w0[1]}, (f32x2){w0[2], w0[3]}, (f32x2){w1[0], w1[1]}, (f32x2){w1[2], w1[3]}};
;                     const f32x2 bv[4] = {(f32x2){b0[0], b0[1]}, (f32x2){b0[2], b0[3]}, (f32x2){b1[0], b1[1]}, (f32x2){b1[2], b1[3]}};
;                     const f32x2 kv[4] = {(f32x2){k0[0], k0[1]}, (f32x2){k0[2], k0[3]}, (f32x2){k1[0], k1[1]}, (f32x2){k1[2], k1[3]}};
;                     const f32x2 rv[4] = {(f32x2){r0[0], r0[1]}, (f32x2){r0[2], r0[3]}, (f32x2){r1[0], r1[1]}, (f32x2){r1[2], r1[3]}};
;                     float yo[2];
; #pragma unroll
;                     for (int i = 0; i < 2; ++i) {
;                         f32x2 sa2 = st[i][0] * av[0]; sa2 += st[i][1] * av[1]; sa2 += st[i][2] * av[2]; sa2 += st[i][3] * av[3];
;                         const float sa = reduce8_dpp(sa2[0] + sa2[1]);
;                         const float vi = vv[i];
;                         f32x2 y2 = (f32x2){0.f, 0.f};
; #pragma unroll
;                         for (int j = 0; j < 4; ++j) { st[i][j] = st[i][j] * wv[j] + sa * bv[j] + vi * kv[j]; y2 += st[i][j] * rv[j]; }
;                         yo[i] = reduce8_dpp(y2[0] + y2[1]);
;                     }
;                     if (kq == 0) *(f32x2*)(yb + tok * 64) = (f32x2){yo[0], yo[1]};
;                 }
	v_pk_mul_f32 v[12:13], v[12:13], v[200:201] op_sel_hi:[1,0]
	v_pk_mul_f32 v[14:15], v[14:15], v[200:201] op_sel:[0,1]
	v_pk_fma_f32 v[0:1], v[226:227], v[210:211], v[0:1] op_sel_hi:[1,0,1]
	v_pk_fma_f32 v[2:3], v[226:227], v[210:211], v[2:3] op_sel:[0,1,0]
	v_pk_fma_f32 v[4:5], v[226:227], v[212:213], v[4:5] op_sel_hi:[1,0,1]
	v_pk_fma_f32 v[6:7], v[226:227], v[212:213], v[6:7] op_sel:[0,1,0]
	v_pk_fma_f32 v[8:9], v[226:227], v[214:215], v[8:9] op_sel_hi:[1,0,1]
	v_pk_fma_f32 v[10:11], v[226:227], v[214:215], v[10:11] op_sel:[0,1,0]
	v_pk_fma_f32 v[12:13], v[226:227], v[216:217], v[12:13] op_sel_hi:[1,0,1]
	v_pk_fma_f32 v[14:15], v[226:227], v[216:217], v[14:15] op_sel:[0,1,0]
	v_pk_fma_f32 v[0:1], v[228:229], v[202:203], v[0:1] op_sel_hi:[1,0,1]
	v_pk_fma_f32 v[2:3], v[228:229], v[202:203], v[2:3] op_sel:[0,1,0]
	v_pk_fma_f32 v[4:5], v[228:229], v[204:205], v[4:5] op_sel_hi:[1,0,1]
	v_pk_fma_f32 v[6:7], v[228:229], v[204:205], v[6:7] op_sel:[0,1,0]
	v_pk_fma_f32 v[8:9], v[228:229], v[206:207], v[8:9] op_sel_hi:[1,0,1]
	v_pk_fma_f32 v[10:11], v[228:229], v[206:207], v[10:11] op_sel:[0,1,0]
	v_pk_fma_f32 v[12:13], v[228:229], v[208:209], v[12:13] op_sel_hi:[1,0,1]
	v_pk_fma_f32 v[14:15], v[228:229], v[208:209], v[14:15] op_sel:[0,1,0]
	v_pk_mul_f32 v[116:117], v[0:1], v[218:219] op_sel_hi:[1,0]
	v_pk_fma_f32 v[116:117], v[2:3], v[218:219], v[116:117] op_sel:[0,1,0]
	v_pk_fma_f32 v[116:117], v[4:5], v[220:221], v[116:117] op_sel_hi:[1,0,1]
	v_pk_fma_f32 v[116:117], v[6:7], v[220:221], v[116:117] op_sel:[0,1,0]
	v_pk_fma_f32 v[116:117], v[8:9], v[222:223], v[116:117] op_sel_hi:[1,0,1]
	v_pk_fma_f32 v[116:117], v[10:11], v[222:223], v[116:117] op_sel:[0,1,0]
	v_pk_fma_f32 v[116:117], v[12:13], v[224:225], v[116:117] op_sel_hi:[1,0,1]
	v_pk_fma_f32 v[116:117], v[14:15], v[224:225], v[116:117] op_sel:[0,1,0]
	ds_read_b128 v[186:189], v20 offset:38400
	ds_read_b128 v[190:193], v20 offset:38416
	v_add_f32_dpp v240, v116, v116 quad_perm:[1,0,3,2] row_mask:0xf bank_mask:0xf bound_ctrl:1
	v_add_f32_dpp v241, v117, v117 quad_perm:[1,0,3,2] row_mask:0xf bank_mask:0xf bound_ctrl:1
	ds_read_b128 v[194:197], v20 offset:38656
	v_add_f32_dpp v240, v240, v240 quad_perm:[2,3,0,1] row_mask:0xf bank_mask:0xf bound_ctrl:1
	v_add_f32_dpp v241, v241, v241 quad_perm:[2,3,0,1] row_mask:0xf bank_mask:0xf bound_ctrl:1
	ds_read_b128 v[198:201], v20 offset:38672
	v_add_f32_dpp v240, v240, v240 row_half_mirror row_mask:0xf bank_mask:0xf bound_ctrl:1
	v_add_f32_dpp v241, v241, v241 row_half_mirror row_mask:0xf bank_mask:0xf bound_ctrl:1
	ds_read_b128 v[202:205], v20 offset:38912
	ds_read_b128 v[206:209], v20 offset:38928
	ds_read_b128 v[210:213], v20 offset:39168
	ds_read_b128 v[214:217], v20 offset:39184
	ds_read_b128 v[218:221], v20 offset:39424
	ds_read_b128 v[222:225], v20 offset:39440
	ds_read_b64 v[226:227], v22 offset:39680
	ds_write_b64 v21, v[240:241] offset:5888
	s_waitcnt lgkmcnt(12)
	v_pk_mul_f32 v[16:17], v[0:1], v[24:25] op_sel_hi:[1,0]
	v_pk_fma_f32 v[16:17], v[2:3], v[24:25], v[16:17] op_sel:[0,1,0]
	v_pk_fma_f32 v[16:17], v[4:5], v[26:27], v[16:17] op_sel_hi:[1,0,1]
	v_pk_fma_f32 v[16:17], v[6:7], v[26:27], v[16:17] op_sel:[0,1,0]
	v_pk_fma_f32 v[16:17], v[8:9], v[28:29], v[16:17] op_sel_hi:[1,0,1]
	v_pk_fma_f32 v[16:17], v[10:11], v[28:29], v[16:17] op_sel:[0,1,0]
	v_pk_fma_f32 v[16:17], v[12:13], v[30:31], v[16:17] op_sel_hi:[1,0,1]
	v_pk_fma_f32 v[16:17], v[14:15], v[30:31], v[16:17] op_sel:[0,1,0]
	v_pk_mul_f32 v[0:1], v[0:1], v[32:33] op_sel_hi:[1,0]
	v_pk_mul_f32 v[2:3], v[2:3], v[32:33] op_sel:[0,1]
	v_add_f32_dpp v16, v16, v16 quad_perm:[1,0,3,2] row_mask:0xf bank_mask:0xf bound_ctrl:1
	v_add_f32_dpp v17, v17, v17 quad_perm:[1,0,3,2] row_mask:0xf bank_mask:0xf bound_ctrl:1
	v_pk_mul_f32 v[4:5], v[4:5], v[34:35] op_sel_hi:[1,0]
	v_pk_mul_f32 v[6:7], v[6:7], v[34:35] op_sel:[0,1]
	v_add_f32_dpp v16, v16, v16 quad_perm:[2,3,0,1] row_mask:0xf bank_mask:0xf bound_ctrl:1
	v_add_f32_dpp v17, v17, v17 quad_perm:[2,3,0,1] row_mask:0xf bank_mask:0xf bound_ctrl:1
	v_pk_mul_f32 v[8:9], v[8:9], v[36:37] op_sel_hi:[1,0]
	v_pk_mul_f32 v[10:11], v[10:11], v[36:37] op_sel:[0,1]
	v_add_f32_dpp v228, v16, v16 row_half_mirror row_mask:0xf bank_mask:0xf bound_ctrl:1
	v_add_f32_dpp v229, v17, v17 row_half_mirror row_mask:0xf bank_mask:0xf bound_ctrl:1
	v_pk_mul_f32 v[12:13], v[12:13], v[38:39] op_sel_hi:[1,0]
	v_pk_mul_f32 v[14:15], v[14:15], v[38:39] op_sel:[0,1]
	v_pk_fma_f32 v[0:1], v[64:65], v[48:49], v[0:1] op_sel_hi:[1,0,1]
	v_pk_fma_f32 v[2:3], v[64:65], v[48:49], v[2:3] op_sel:[0,1,0]
	v_pk_fma_f32 v[4:5], v[64:65], v[50:51], v[4:5] op_sel_hi:[1,0,1]
	v_pk_fma_f32 v[6:7], v[64:65], v[50:51], v[6:7] op_sel:[0,1,0]
	v_pk_fma_f32 v[8:9], v[64:65], v[52:53], v[8:9] op_sel_hi:[1,0,1]
	v_pk_fma_f32 v[10:11], v[64:65], v[52:53], v[10:11] op_sel:[0,1,0]
	v_pk_fma_f32 v[12:13], v[64:65], v[54:55], v[12:13] op_sel_hi:[1,0,1]
	v_pk_fma_f32 v[14:15], v[64:65], v[54:55], v[14:15] op_sel:[0,1,0]
	v_pk_fma_f32 v[0:1], v[228:229], v[40:41], v[0:1] op_sel_hi:[1,0,1]
	v_pk_fma_f32 v[2:3], v[228:229], v[40:41], v[2:3] op_sel:[0,1,0]
	v_pk_fma_f32 v[4:5], v[228:229], v[42:43], v[4:5] op_sel_hi:[1,0,1]
	v_pk_fma_f32 v[6:7], v[228:229], v[42:43], v[6:7] op_sel:[0,1,0]
	v_pk_fma_f32 v[8:9], v[228:229], v[44:45], v[8:9] op_sel_hi:[1,0,1]
	v_pk_fma_f32 v[10:11], v[228:229], v[44:45], v[10:11] op_sel:[0,1,0]
	v_pk_fma_f32 v[12:13], v[228:229], v[46:47], v[12:13] op_sel_hi:[1,0,1]
	v_pk_fma_f32 v[14:15], v[228:229], v[46:47], v[14:15] op_sel:[0,1,0]
	v_pk_mul_f32 v[116:117], v[0:1], v[56:57] op_sel_hi:[1,0]
	v_pk_fma_f32 v[116:117], v[2:3], v[56:57], v[116:117] op_sel:[0,1,0]
; DEV float reduce8_dpp(float v) { v += DPPF(v, 0xB1); v += DPPF(v, 0x4E); v += DPPF(v, 0x141); return v; }
;     ...
; #pragma unroll 32
;                 for (int tok = 0; tok < 32; ++tok) {
;                     const float* bs = base0 + tok * 384;
;                     const f32x4 a0 = *(const f32x4*)bs, a1 = *(const f32x4*)(bs + 4);
;                     const f32x4 w0 = *(const f32x4*)(bs + 64), w1 = *(const f32x4*)(bs + 68);
;                     const f32x4 b0 = *(const f32x4*)(bs + 128), b1 = *(const f32x4*)(bs + 132);
;                     const f32x4 k0 = *(const f32x4*)(bs + 192), k1 = *(const f32x4*)(bs + 196);
;                     const f32x4 r0 = *(const f32x4*)(bs + 256), r1 = *(const f32x4*)(bs + 260);
;                     const f32x2 vv = *(const f32x2*)(op + (size_t)(buf * 32 + tok) * 384 + 320 + 2 * vp);
;                     const f32x2 av[4] = {(f32x2){a0[0], a0[1]}, (f32x2){a0[2], a0[3]}, (f32x2){a1[0], a1[1]}, (f32x2){a1[2], a1[3]}};
;                     const f32x2 wv[4] = {(f32x2){w0[0], w0[1]}, (f32x2){w0[2], w0[3]}, (f32x2){w1[0], w1[1]}, (f32x2){w1[2], w1[3]}};
;                     const f32x2 bv[4] = {(f32x2){b0[0], b0[1]}, (f32x2){b0[2], b0[3]}, (f32x2){b1[0], b1[1]}, (f32x2){b1[2], b1[3]}};
;                     const f32x2 kv[4] = {(f32x2){k0[0], k0[1]}, (f32x2){k0[2], k0[3]}, (f32x2){k1[0], k1[1]}, (f32x2){k1[2], k1[3]}};
;                     const f32x2 rv[4] = {(f32x2){r0[0], r0[1]}, (f32x2){r0[2], r0[3]}, (f32x2){r1[0], r1[1]}, (f32x2){r1[2], r1[3]}};
;                     float yo[2];
; #pragma unroll
;                     for (int i = 0; i < 2; ++i) {
;                         f32x2 sa2 = st[i][0] * av[0]; sa2 += st[i][1] * av[1]; sa2 += st[i][2] * av[2]; sa2 += st[i][3] * av[3];
;                         const float sa = reduce8_dpp(sa2[0] + sa2[1]);
;                         const float vi = vv[i];
;                         f32x2 y2 = (f32x2){0.f, 0.f};
; #pragma unroll
;                         for (int j = 0; j < 4; ++j) { st[i][j] = st[i][j] * wv[j] + sa * bv[j] + vi * kv[j]; y2 += st[i][j] * rv[j]; }
;                         yo[i] = reduce8_dpp(y2[0] + y2[1]);
;                     }
;                     if (kq == 0) *(f32x2*)(yb + tok * 64) = (f32x2){yo[0], yo[1]};
;                 }
	v_pk_fma_f32 v[116:117], v[4:5], v[58:59], v[116:117] op_sel_hi:[1,0,1]
	v_pk_fma_f32 v[116:117], v[6:7], v[58:59], v[116:117] op_sel:[0,1,0]
	v_pk_fma_f32 v[116:117], v[8:9], v[60:61], v[116:117] op_sel_hi:[1,0,1]
	v_pk_fma_f32 v[116:117], v[10:11], v[60:61], v[116:117] op_sel:[0,1,0]
	v_pk_fma_f32 v[116:117], v[12:13], v[62:63], v[116:117] op_sel_hi:[1,0,1]
	v_pk_fma_f32 v[116:117], v[14:15], v[62:63], v[116:117] op_sel:[0,1,0]
	ds_read_b128 v[24:27], v20 offset:39936
	ds_read_b128 v[28:31], v20 offset:39952
	v_add_f32_dpp v240, v116, v116 quad_perm:[1,0,3,2] row_mask:0xf bank_mask:0xf bound_ctrl:1
	v_add_f32_dpp v241, v117, v117 quad_perm:[1,0,3,2] row_mask:0xf bank_mask:0xf bound_ctrl:1
	ds_read_b128 v[32:35], v20 offset:40192
	v_add_f32_dpp v240, v240, v240 quad_perm:[2,3,0,1] row_mask:0xf bank_mask:0xf bound_ctrl:1
	v_add_f32_dpp v241, v241, v241 quad_perm:[2,3,0,1] row_mask:0xf bank_mask:0xf bound_ctrl:1
	ds_read_b128 v[36:39], v20 offset:40208
	v_add_f32_dpp v240, v240, v240 row_half_mirror row_mask:0xf bank_mask:0xf bound_ctrl:1
	v_add_f32_dpp v241, v241, v241 row_half_mirror row_mask:0xf bank_mask:0xf bound_ctrl:1
	ds_read_b128 v[40:43], v20 offset:40448
	ds_read_b128 v[44:47], v20 offset:40464
	ds_read_b128 v[48:51], v20 offset:40704
	ds_read_b128 v[52:55], v20 offset:40720
	ds_read_b128 v[56:59], v20 offset:40960
	ds_read_b128 v[60:63], v20 offset:40976
	ds_read_b64 v[64:65], v22 offset:41216
	ds_write_b64 v21, v[240:241] offset:6144
	s_waitcnt lgkmcnt(12)
	v_pk_mul_f32 v[16:17], v[0:1], v[186:187] op_sel_hi:[1,0]
	v_pk_fma_f32 v[16:17], v[2:3], v[186:187], v[16:17] op_sel:[0,1,0]
	v_pk_fma_f32 v[16:17], v[4:5], v[188:189], v[16:17] op_sel_hi:[1,0,1]
	v_pk_fma_f32 v[16:17], v[6:7], v[188:189], v[16:17] op_sel:[0,1,0]
	v_pk_fma_f32 v[16:17], v[8:9], v[190:191], v[16:17] op_sel_hi:[1,0,1]
	v_pk_fma_f32 v[16:17], v[10:11], v[190:191], v[16:17] op_sel:[0,1,0]
	v_pk_fma_f32 v[16:17], v[12:13], v[192:193], v[16:17] op_sel_hi:[1,0,1]
	v_pk_fma_f32 v[16:17], v[14:15], v[192:193], v[16:17] op_sel:[0,1,0]
	v_pk_mul_f32 v[0:1], v[0:1], v[194:195] op_sel_hi:[1,0]
	v_pk_mul_f32 v[2:3], v[2:3], v[194:195] op_sel:[0,1]
	v_add_f32_dpp v16, v16, v16 quad_perm:[1,0,3,2] row_mask:0xf bank_mask:0xf bound_ctrl:1
	v_add_f32_dpp v17, v17, v17 quad_perm:[1,0,3,2] row_mask:0xf bank_mask:0xf bound_ctrl:1
	v_pk_mul_f32 v[4:5], v[4:5], v[196:197] op_sel_hi:[1,0]
	v_pk_mul_f32 v[6:7], v[6:7], v[196:197] op_sel:[0,1]
	v_add_f32_dpp v16, v16, v16 quad_perm:[2,3,0,1] row_mask:0xf bank_mask:0xf bound_ctrl:1
	v_add_f32_dpp v17, v17, v17 quad_perm:[2,3,0,1] row_mask:0xf bank_mask:0xf bound_ctrl:1
	v_pk_mul_f32 v[8:9], v[8:9], v[198:199] op_sel_hi:[1,0]
	v_pk_mul_f32 v[10:11], v[10:11], v[198:199] op_sel:[0,1]
	v_add_f32_dpp v228, v16, v16 row_half_mirror row_mask:0xf bank_mask:0xf bound_ctrl:1
	v_add_f32_dpp v229, v17, v17 row_half_mirror row_mask:0xf bank_mask:0xf bound_ctrl:1
	v_pk_mul_f32 v[12:13], v[12:13], v[200:201] op_sel_hi:[1,0]
	v_pk_mul_f32 v[14:15], v[14:15], v[200:201] op_sel:[0,1]
	v_pk_fma_f32 v[0:1], v[226:227], v[210:211], v[0:1] op_sel_hi:[1,0,1]
	v_pk_fma_f32 v[2:3], v[226:227], v[210:211], v[2:3] op_sel:[0,1,0]
	v_pk_fma_f32 v[4:5], v[226:227], v[212:213], v[4:5] op_sel_hi:[1,0,1]
	v_pk_fma_f32 v[6:7], v[226:227], v[212:213], v[6:7] op_sel:[0,1,0]
	v_pk_fma_f32 v[8:9], v[226:227], v[214:215], v[8:9] op_sel_hi:[1,0,1]
	v_pk_fma_f32 v[10:11], v[226:227], v[214:215], v[10:11] op_sel:[0,1,0]
	v_pk_fma_f32 v[12:13], v[226:227], v[216:217], v[12:13] op_sel_hi:[1,0,1]
	v_pk_fma_f32 v[14:15], v[226:227], v[216:217], v[14:15] op_sel:[0,1,0]
	v_pk_fma_f32 v[0:1], v[228:229], v[202:203], v[0:1] op_sel_hi:[1,0,1]
	v_pk_fma_f32 v[2:3], v[228:229], v[202:203], v[2:3] op_sel:[0,1,0]
	v_pk_fma_f32 v[4:5], v[228:229], v[204:205], v[4:5] op_sel_hi:[1,0,1]
	v_pk_fma_f32 v[6:7], v[228:229], v[204:205], v[6:7] op_sel:[0,1,0]
	v_pk_fma_f32 v[8:9], v[228:229], v[206:207], v[8:9] op_sel_hi:[1,0,1]
	v_pk_fma_f32 v[10:11], v[228:229], v[206:207], v[10:11] op_sel:[0,1,0]
	v_pk_fma_f32 v[12:13], v[228:229], v[208:209], v[12:13] op_sel_hi:[1,0,1]
	v_pk_fma_f32 v[14:15], v[228:229], v[208:209], v[14:15] op_sel:[0,1,0]
	v_pk_mul_f32 v[116:117], v[0:1], v[218:219] op_sel_hi:[1,0]
	v_pk_fma_f32 v[116:117], v[2:3], v[218:219], v[116:117] op_sel:[0,1,0]
	v_pk_fma_f32 v[116:117], v[4:5], v[220:221], v[116:117] op_sel_hi:[1,0,1]
	v_pk_fma_f32 v[116:117], v[6:7], v[220:221], v[116:117] op_sel:[0,1,0]
	v_pk_fma_f32 v[116:117], v[8:9], v[222:223], v[116:117] op_sel_hi:[1,0,1]
	v_pk_fma_f32 v[116:117], v[10:11], v[222:223], v[116:117] op_sel:[0,1,0]
	v_pk_fma_f32 v[116:117], v[12:13], v[224:225], v[116:117] op_sel_hi:[1,0,1]
	v_pk_fma_f32 v[116:117], v[14:15], v[224:225], v[116:117] op_sel:[0,1,0]
	ds_read_b128 v[186:189], v20 offset:41472
	ds_read_b128 v[190:193], v20 offset:41488
	v_add_f32_dpp v240, v116, v116 quad_perm:[1,0,3,2] row_mask:0xf bank_mask:0xf bound_ctrl:1
	v_add_f32_dpp v241, v117, v117 quad_perm:[1,0,3,2] row_mask:0xf bank_mask:0xf bound_ctrl:1
	ds_read_b128 v[194:197], v20 offset:41728
	v_add_f32_dpp v240, v240, v240 quad_perm:[2,3,0,1] row_mask:0xf bank_mask:0xf bound_ctrl:1
	v_add_f32_dpp v241, v241, v241 quad_perm:[2,3,0,1] row_mask:0xf bank_mask:0xf bound_ctrl:1
	ds_read_b128 v[198:201], v20 offset:41744
	v_add_f32_dpp v240, v240, v240 row_half_mirror row_mask:0xf bank_mask:0xf bound_ctrl:1
	v_add_f32_dpp v241, v241, v241 row_half_mirror row_mask:0xf bank_mask:0xf bound_ctrl:1
	ds_read_b128 v[202:205], v20 offset:41984
	ds_read_b128 v[206:209], v20 offset:42000
	ds_read_b128 v[210:213], v20 offset:42240
	ds_read_b128 v[214:217], v20 offset:42256
	ds_read_b128 v[218:221], v20 offset:42496
	ds_read_b128 v[222:225], v20 offset:42512
	ds_read_b64 v[226:227], v22 offset:42752
	ds_write_b64 v21, v[240:241] offset:6400
	s_waitcnt lgkmcnt(12)
; DEV float reduce8_dpp(float v) { v += DPPF(v, 0xB1); v += DPPF(v, 0x4E); v += DPPF(v, 0x141); return v; }
;     ...
; #pragma unroll 32
;                 for (int tok = 0; tok < 32; ++tok) {
;                     const float* bs = base0 + tok * 384;
;                     const f32x4 a0 = *(const f32x4*)bs, a1 = *(const f32x4*)(bs + 4);
;                     const f32x4 w0 = *(const f32x4*)(bs + 64), w1 = *(const f32x4*)(bs + 68);
;                     const f32x4 b0 = *(const f32x4*)(bs + 128), b1 = *(const f32x4*)(bs + 132);
;                     const f32x4 k0 = *(const f32x4*)(bs + 192), k1 = *(const f32x4*)(bs + 196);
;                     const f32x4 r0 = *(const f32x4*)(bs + 256), r1 = *(const f32x4*)(bs + 260);
;                     const f32x2 vv = *(const f32x2*)(op + (size_t)(buf * 32 + tok) * 384 + 320 + 2 * vp);
;                     const f32x2 av[4] = {(f32x2){a0[0], a0[1]}, (f32x2){a0[2], a0[3]}, (f32x2){a1[0], a1[1]}, (f32x2){a1[2], a1[3]}};
;                     const f32x2 wv[4] = {(f32x2){w0[0], w0[1]}, (f32x2){w0[2], w0[3]}, (f32x2){w1[0], w1[1]}, (f32x2){w1[2], w1[3]}};
;                     const f32x2 bv[4] = {(f32x2){b0[0], b0[1]}, (f32x2){b0[2], b0[3]}, (f32x2){b1[0], b1[1]}, (f32x2){b1[2], b1[3]}};
;                     const f32x2 kv[4] = {(f32x2){k0[0], k0[1]}, (f32x2){k0[2], k0[3]}, (f32x2){k1[0], k1[1]}, (f32x2){k1[2], k1[3]}};
;                     const f32x2 rv[4] = {(f32x2){r0[0], r0[1]}, (f32x2){r0[2], r0[3]}, (f32x2){r1[0], r1[1]}, (f32x2){r1[2], r1[3]}};
;                     float yo[2];
; #pragma unroll
;                     for (int i = 0; i < 2; ++i) {
;                         f32x2 sa2 = st[i][0] * av[0]; sa2 += st[i][1] * av[1]; sa2 += st[i][2] * av[2]; sa2 += st[i][3] * av[3];
;                         const float sa = reduce8_dpp(sa2[0] + sa2[1]);
;                         const float vi = vv[i];
;                         f32x2 y2 = (f32x2){0.f, 0.f};
; #pragma unroll
;                         for (int j = 0; j < 4; ++j) { st[i][j] = st[i][j] * wv[j] + sa * bv[j] + vi * kv[j]; y2 += st[i][j] * rv[j]; }
;                         yo[i] = reduce8_dpp(y2[0] + y2[1]);
;                     }
;                     if (kq == 0) *(f32x2*)(yb + tok * 64) = (f32x2){yo[0], yo[1]};
;                 }
	v_pk_mul_f32 v[16:17], v[0:1], v[24:25] op_sel_hi:[1,0]
	v_pk_fma_f32 v[16:17], v[2:3], v[24:25], v[16:17] op_sel:[0,1,0]
	v_pk_fma_f32 v[16:17], v[4:5], v[26:27], v[16:17] op_sel_hi:[1,0,1]
	v_pk_fma_f32 v[16:17], v[6:7], v[26:27], v[16:17] op_sel:[0,1,0]
	v_pk_fma_f32 v[16:17], v[8:9], v[28:29], v[16:17] op_sel_hi:[1,0,1]
	v_pk_fma_f32 v[16:17], v[10:11], v[28:29], v[16:17] op_sel:[0,1,0]
	v_pk_fma_f32 v[16:17], v[12:13], v[30:31], v[16:17] op_sel_hi:[1,0,1]
	v_pk_fma_f32 v[16:17], v[14:15], v[30:31], v[16:17] op_sel:[0,1,0]
	v_pk_mul_f32 v[0:1], v[0:1], v[32:33] op_sel_hi:[1,0]
	v_pk_mul_f32 v[2:3], v[2:3], v[32:33] op_sel:[0,1]
	v_add_f32_dpp v16, v16, v16 quad_perm:[1,0,3,2] row_mask:0xf bank_mask:0xf bound_ctrl:1
	v_add_f32_dpp v17, v17, v17 quad_perm:[1,0,3,2] row_mask:0xf bank_mask:0xf bound_ctrl:1
	v_pk_mul_f32 v[4:5], v[4:5], v[34:35] op_sel_hi:[1,0]
	v_pk_mul_f32 v[6:7], v[6:7], v[34:35] op_sel:[0,1]
	v_add_f32_dpp v16, v16, v16 quad_perm:[2,3,0,1] row_mask:0xf bank_mask:0xf bound_ctrl:1
	v_add_f32_dpp v17, v17, v17 quad_perm:[2,3,0,1] row_mask:0xf bank_mask:0xf bound_ctrl:1
	v_pk_mul_f32 v[8:9], v[8:9], v[36:37] op_sel_hi:[1,0]
	v_pk_mul_f32 v[10:11], v[10:11], v[36:37] op_sel:[0,1]
	v_add_f32_dpp v228, v16, v16 row_half_mirror row_mask:0xf bank_mask:0xf bound_ctrl:1
	v_add_f32_dpp v229, v17, v17 row_half_mirror row_mask:0xf bank_mask:0xf bound_ctrl:1
	v_pk_mul_f32 v[12:13], v[12:13], v[38:39] op_sel_hi:[1,0]
	v_pk_mul_f32 v[14:15], v[14:15], v[38:39] op_sel:[0,1]
	v_pk_fma_f32 v[0:1], v[64:65], v[48:49], v[0:1] op_sel_hi:[1,0,1]
	v_pk_fma_f32 v[2:3], v[64:65], v[48:49], v[2:3] op_sel:[0,1,0]
	v_pk_fma_f32 v[4:5], v[64:65], v[50:51], v[4:5] op_sel_hi:[1,0,1]
	v_pk_fma_f32 v[6:7], v[64:65], v[50:51], v[6:7] op_sel:[0,1,0]
	v_pk_fma_f32 v[8:9], v[64:65], v[52:53], v[8:9] op_sel_hi:[1,0,1]
	v_pk_fma_f32 v[10:11], v[64:65], v[52:53], v[10:11] op_sel:[0,1,0]
	v_pk_fma_f32 v[12:13], v[64:65], v[54:55], v[12:13] op_sel_hi:[1,0,1]
	v_pk_fma_f32 v[14:15], v[64:65], v[54:55], v[14:15] op_sel:[0,1,0]
	v_pk_fma_f32 v[0:1], v[228:229], v[40:41], v[0:1] op_sel_hi:[1,0,1]
	v_pk_fma_f32 v[2:3], v[228:229], v[40:41], v[2:3] op_sel:[0,1,0]
	v_pk_fma_f32 v[4:5], v[228:229], v[42:43], v[4:5] op_sel_hi:[1,0,1]
	v_pk_fma_f32 v[6:7], v[228:229], v[42:43], v[6:7] op_sel:[0,1,0]
	v_pk_fma_f32 v[8:9], v[228:229], v[44:45], v[8:9] op_sel_hi:[1,0,1]
	v_pk_fma_f32 v[10:11], v[228:229], v[44:45], v[10:11] op_sel:[0,1,0]
	v_pk_fma_f32 v[12:13], v[228:229], v[46:47], v[12:13] op_sel_hi:[1,0,1]
	v_pk_fma_f32 v[14:15], v[228:229], v[46:47], v[14:15] op_sel:[0,1,0]
	v_pk_mul_f32 v[116:117], v[0:1], v[56:57] op_sel_hi:[1,0]
	v_pk_fma_f32 v[116:117], v[2:3], v[56:57], v[116:117] op_sel:[0,1,0]
	v_pk_fma_f32 v[116:117], v[4:5], v[58:59], v[116:117] op_sel_hi:[1,0,1]
	v_pk_fma_f32 v[116:117], v[6:7], v[58:59], v[116:117] op_sel:[0,1,0]
	v_pk_fma_f32 v[116:117], v[8:9], v[60:61], v[116:117] op_sel_hi:[1,0,1]
	v_pk_fma_f32 v[116:117], v[10:11], v[60:61], v[116:117] op_sel:[0,1,0]
	v_pk_fma_f32 v[116:117], v[12:13], v[62:63], v[116:117] op_sel_hi:[1,0,1]
	v_pk_fma_f32 v[116:117], v[14:15], v[62:63], v[116:117] op_sel:[0,1,0]
	ds_read_b128 v[24:27], v20 offset:43008
	ds_read_b128 v[28:31], v20 offset:43024
	v_add_f32_dpp v240, v116, v116 quad_perm:[1,0,3,2] row_mask:0xf bank_mask:0xf bound_ctrl:1
	v_add_f32_dpp v241, v117, v117 quad_perm:[1,0,3,2] row_mask:0xf bank_mask:0xf bound_ctrl:1
	ds_read_b128 v[32:35], v20 offset:43264
	v_add_f32_dpp v240, v240, v240 quad_perm:[2,3,0,1] row_mask:0xf bank_mask:0xf bound_ctrl:1
	v_add_f32_dpp v241, v241, v241 quad_perm:[2,3,0,1] row_mask:0xf bank_mask:0xf bound_ctrl:1
	ds_read_b128 v[36:39], v20 offset:43280
	v_add_f32_dpp v240, v240, v240 row_half_mirror row_mask:0xf bank_mask:0xf bound_ctrl:1
	v_add_f32_dpp v241, v241, v241 row_half_mirror row_mask:0xf bank_mask:0xf bound_ctrl:1
	ds_read_b128 v[40:43], v20 offset:43520
	ds_read_b128 v[44:47], v20 offset:43536
	ds_read_b128 v[48:51], v20 offset:43776
	ds_read_b128 v[52:55], v20 offset:43792
	ds_read_b128 v[56:59], v20 offset:44032
	ds_read_b128 v[60:63], v20 offset:44048
	ds_read_b64 v[64:65], v22 offset:44288
	ds_write_b64 v21, v[240:241] offset:6656
	s_waitcnt lgkmcnt(12)
	v_pk_mul_f32 v[16:17], v[0:1], v[186:187] op_sel_hi:[1,0]
	v_pk_fma_f32 v[16:17], v[2:3], v[186:187], v[16:17] op_sel:[0,1,0]
	v_pk_fma_f32 v[16:17], v[4:5], v[188:189], v[16:17] op_sel_hi:[1,0,1]
	v_pk_fma_f32 v[16:17], v[6:7], v[188:189], v[16:17] op_sel:[0,1,0]
	v_pk_fma_f32 v[16:17], v[8:9], v[190:191], v[16:17] op_sel_hi:[1,0,1]
	v_pk_fma_f32 v[16:17], v[10:11], v[190:191], v[16:17] op_sel:[0,1,0]
	v_pk_fma_f32 v[16:17], v[12:13], v[192:193], v[16:17] op_sel_hi:[1,0,1]
	v_pk_fma_f32 v[16:17], v[14:15], v[192:193], v[16:17] op_sel:[0,1,0]
	v_pk_mul_f32 v[0:1], v[0:1], v[194:195] op_sel_hi:[1,0]
	v_pk_mul_f32 v[2:3], v[2:3], v[194:195] op_sel:[0,1]
	v_add_f32_dpp v16, v16, v16 quad_perm:[1,0,3,2] row_mask:0xf bank_mask:0xf bound_ctrl:1
	v_add_f32_dpp v17, v17, v17 quad_perm:[1,0,3,2] row_mask:0xf bank_mask:0xf bound_ctrl:1
	v_pk_mul_f32 v[4:5], v[4:5], v[196:197] op_sel_hi:[1,0]
	v_pk_mul_f32 v[6:7], v[6:7], v[196:197] op_sel:[0,1]
	v_add_f32_dpp v16, v16, v16 quad_perm:[2,3,0,1] row_mask:0xf bank_mask:0xf bound_ctrl:1
	v_add_f32_dpp v17, v17, v17 quad_perm:[2,3,0,1] row_mask:0xf bank_mask:0xf bound_ctrl:1
	v_pk_mul_f32 v[8:9], v[8:9], v[198:199] op_sel_hi:[1,0]
	v_pk_mul_f32 v[10:11], v[10:11], v[198:199] op_sel:[0,1]
	v_add_f32_dpp v228, v16, v16 row_half_mirror row_mask:0xf bank_mask:0xf bound_ctrl:1
	v_add_f32_dpp v229, v17, v17 row_half_mirror row_mask:0xf bank_mask:0xf bound_ctrl:1
; DEV float reduce8_dpp(float v) { v += DPPF(v, 0xB1); v += DPPF(v, 0x4E); v += DPPF(v, 0x141); return v; }
;     ...
; #pragma unroll 32
;                 for (int tok = 0; tok < 32; ++tok) {
;                     const float* bs = base0 + tok * 384;
;                     const f32x4 a0 = *(const f32x4*)bs, a1 = *(const f32x4*)(bs + 4);
;                     const f32x4 w0 = *(const f32x4*)(bs + 64), w1 = *(const f32x4*)(bs + 68);
;                     const f32x4 b0 = *(const f32x4*)(bs + 128), b1 = *(const f32x4*)(bs + 132);
;                     const f32x4 k0 = *(const f32x4*)(bs + 192), k1 = *(const f32x4*)(bs + 196);
;                     const f32x4 r0 = *(const f32x4*)(bs + 256), r1 = *(const f32x4*)(bs + 260);
;                     const f32x2 vv = *(const f32x2*)(op + (size_t)(buf * 32 + tok) * 384 + 320 + 2 * vp);
;                     const f32x2 av[4] = {(f32x2){a0[0], a0[1]}, (f32x2){a0[2], a0[3]}, (f32x2){a1[0], a1[1]}, (f32x2){a1[2], a1[3]}};
;                     const f32x2 wv[4] = {(f32x2){w0[0], w0[1]}, (f32x2){w0[2], w0[3]}, (f32x2){w1[0], w1[1]}, (f32x2){w1[2], w1[3]}};
;                     const f32x2 bv[4] = {(f32x2){b0[0], b0[1]}, (f32x2){b0[2], b0[3]}, (f32x2){b1[0], b1[1]}, (f32x2){b1[2], b1[3]}};
;                     const f32x2 kv[4] = {(f32x2){k0[0], k0[1]}, (f32x2){k0[2], k0[3]}, (f32x2){k1[0], k1[1]}, (f32x2){k1[2], k1[3]}};
;                     const f32x2 rv[4] = {(f32x2){r0[0], r0[1]}, (f32x2){r0[2], r0[3]}, (f32x2){r1[0], r1[1]}, (f32x2){r1[2], r1[3]}};
;                     float yo[2];
; #pragma unroll
;                     for (int i = 0; i < 2; ++i) {
;                         f32x2 sa2 = st[i][0] * av[0]; sa2 += st[i][1] * av[1]; sa2 += st[i][2] * av[2]; sa2 += st[i][3] * av[3];
;                         const float sa = reduce8_dpp(sa2[0] + sa2[1]);
;                         const float vi = vv[i];
;                         f32x2 y2 = (f32x2){0.f, 0.f};
; #pragma unroll
;                         for (int j = 0; j < 4; ++j) { st[i][j] = st[i][j] * wv[j] + sa * bv[j] + vi * kv[j]; y2 += st[i][j] * rv[j]; }
;                         yo[i] = reduce8_dpp(y2[0] + y2[1]);
;                     }
;                     if (kq == 0) *(f32x2*)(yb + tok * 64) = (f32x2){yo[0], yo[1]};
;                 }
	v_pk_mul_f32 v[12:13], v[12:13], v[200:201] op_sel_hi:[1,0]
	v_pk_mul_f32 v[14:15], v[14:15], v[200:201] op_sel:[0,1]
	v_pk_fma_f32 v[0:1], v[226:227], v[210:211], v[0:1] op_sel_hi:[1,0,1]
	v_pk_fma_f32 v[2:3], v[226:227], v[210:211], v[2:3] op_sel:[0,1,0]
	v_pk_fma_f32 v[4:5], v[226:227], v[212:213], v[4:5] op_sel_hi:[1,0,1]
	v_pk_fma_f32 v[6:7], v[226:227], v[212:213], v[6:7] op_sel:[0,1,0]
	v_pk_fma_f32 v[8:9], v[226:227], v[214:215], v[8:9] op_sel_hi:[1,0,1]
	v_pk_fma_f32 v[10:11], v[226:227], v[214:215], v[10:11] op_sel:[0,1,0]
	v_pk_fma_f32 v[12:13], v[226:227], v[216:217], v[12:13] op_sel_hi:[1,0,1]
	v_pk_fma_f32 v[14:15], v[226:227], v[216:217], v[14:15] op_sel:[0,1,0]
	v_pk_fma_f32 v[0:1], v[228:229], v[202:203], v[0:1] op_sel_hi:[1,0,1]
	v_pk_fma_f32 v[2:3], v[228:229], v[202:203], v[2:3] op_sel:[0,1,0]
	v_pk_fma_f32 v[4:5], v[228:229], v[204:205], v[4:5] op_sel_hi:[1,0,1]
	v_pk_fma_f32 v[6:7], v[228:229], v[204:205], v[6:7] op_sel:[0,1,0]
	v_pk_fma_f32 v[8:9], v[228:229], v[206:207], v[8:9] op_sel_hi:[1,0,1]
	v_pk_fma_f32 v[10:11], v[228:229], v[206:207], v[10:11] op_sel:[0,1,0]
	v_pk_fma_f32 v[12:13], v[228:229], v[208:209], v[12:13] op_sel_hi:[1,0,1]
	v_pk_fma_f32 v[14:15], v[228:229], v[208:209], v[14:15] op_sel:[0,1,0]
	v_pk_mul_f32 v[116:117], v[0:1], v[218:219] op_sel_hi:[1,0]
	v_pk_fma_f32 v[116:117], v[2:3], v[218:219], v[116:117] op_sel:[0,1,0]
	v_pk_fma_f32 v[116:117], v[4:5], v[220:221], v[116:117] op_sel_hi:[1,0,1]
	v_pk_fma_f32 v[116:117], v[6:7], v[220:221], v[116:117] op_sel:[0,1,0]
	v_pk_fma_f32 v[116:117], v[8:9], v[222:223], v[116:117] op_sel_hi:[1,0,1]
	v_pk_fma_f32 v[116:117], v[10:11], v[222:223], v[116:117] op_sel:[0,1,0]
	v_pk_fma_f32 v[116:117], v[12:13], v[224:225], v[116:117] op_sel_hi:[1,0,1]
	v_pk_fma_f32 v[116:117], v[14:15], v[224:225], v[116:117] op_sel:[0,1,0]
	ds_read_b128 v[186:189], v20 offset:44544
	ds_read_b128 v[190:193], v20 offset:44560
	v_add_f32_dpp v240, v116, v116 quad_perm:[1,0,3,2] row_mask:0xf bank_mask:0xf bound_ctrl:1
	v_add_f32_dpp v241, v117, v117 quad_perm:[1,0,3,2] row_mask:0xf bank_mask:0xf bound_ctrl:1
	ds_read_b128 v[194:197], v20 offset:44800
	v_add_f32_dpp v240, v240, v240 quad_perm:[2,3,0,1] row_mask:0xf bank_mask:0xf bound_ctrl:1
	v_add_f32_dpp v241, v241, v241 quad_perm:[2,3,0,1] row_mask:0xf bank_mask:0xf bound_ctrl:1
	ds_read_b128 v[198:201], v20 offset:44816
	v_add_f32_dpp v240, v240, v240 row_half_mirror row_mask:0xf bank_mask:0xf bound_ctrl:1
	v_add_f32_dpp v241, v241, v241 row_half_mirror row_mask:0xf bank_mask:0xf bound_ctrl:1
	ds_read_b128 v[202:205], v20 offset:45056
	ds_read_b128 v[206:209], v20 offset:45072
	ds_read_b128 v[210:213], v20 offset:45312
	ds_read_b128 v[214:217], v20 offset:45328
	ds_read_b128 v[218:221], v20 offset:45568
	ds_read_b128 v[222:225], v20 offset:45584
	ds_read_b64 v[226:227], v22 offset:45824
	ds_write_b64 v21, v[240:241] offset:6912
	s_waitcnt lgkmcnt(12)
	v_pk_mul_f32 v[16:17], v[0:1], v[24:25] op_sel_hi:[1,0]
	v_pk_fma_f32 v[16:17], v[2:3], v[24:25], v[16:17] op_sel:[0,1,0]
	v_pk_fma_f32 v[16:17], v[4:5], v[26:27], v[16:17] op_sel_hi:[1,0,1]
	v_pk_fma_f32 v[16:17], v[6:7], v[26:27], v[16:17] op_sel:[0,1,0]
	v_pk_fma_f32 v[16:17], v[8:9], v[28:29], v[16:17] op_sel_hi:[1,0,1]
	v_pk_fma_f32 v[16:17], v[10:11], v[28:29], v[16:17] op_sel:[0,1,0]
	v_pk_fma_f32 v[16:17], v[12:13], v[30:31], v[16:17] op_sel_hi:[1,0,1]
	v_pk_fma_f32 v[16:17], v[14:15], v[30:31], v[16:17] op_sel:[0,1,0]
	v_pk_mul_f32 v[0:1], v[0:1], v[32:33] op_sel_hi:[1,0]
	v_pk_mul_f32 v[2:3], v[2:3], v[32:33] op_sel:[0,1]
	v_add_f32_dpp v16, v16, v16 quad_perm:[1,0,3,2] row_mask:0xf bank_mask:0xf bound_ctrl:1
	v_add_f32_dpp v17, v17, v17 quad_perm:[1,0,3,2] row_mask:0xf bank_mask:0xf bound_ctrl:1
	v_pk_mul_f32 v[4:5], v[4:5], v[34:35] op_sel_hi:[1,0]
	v_pk_mul_f32 v[6:7], v[6:7], v[34:35] op_sel:[0,1]
	v_add_f32_dpp v16, v16, v16 quad_perm:[2,3,0,1] row_mask:0xf bank_mask:0xf bound_ctrl:1
	v_add_f32_dpp v17, v17, v17 quad_perm:[2,3,0,1] row_mask:0xf bank_mask:0xf bound_ctrl:1
	v_pk_mul_f32 v[8:9], v[8:9], v[36:37] op_sel_hi:[1,0]
	v_pk_mul_f32 v[10:11], v[10:11], v[36:37] op_sel:[0,1]
	v_add_f32_dpp v228, v16, v16 row_half_mirror row_mask:0xf bank_mask:0xf bound_ctrl:1
	v_add_f32_dpp v229, v17, v17 row_half_mirror row_mask:0xf bank_mask:0xf bound_ctrl:1
	v_pk_mul_f32 v[12:13], v[12:13], v[38:39] op_sel_hi:[1,0]
	v_pk_mul_f32 v[14:15], v[14:15], v[38:39] op_sel:[0,1]
	v_pk_fma_f32 v[0:1], v[64:65], v[48:49], v[0:1] op_sel_hi:[1,0,1]
	v_pk_fma_f32 v[2:3], v[64:65], v[48:49], v[2:3] op_sel:[0,1,0]
	v_pk_fma_f32 v[4:5], v[64:65], v[50:51], v[4:5] op_sel_hi:[1,0,1]
	v_pk_fma_f32 v[6:7], v[64:65], v[50:51], v[6:7] op_sel:[0,1,0]
	v_pk_fma_f32 v[8:9], v[64:65], v[52:53], v[8:9] op_sel_hi:[1,0,1]
	v_pk_fma_f32 v[10:11], v[64:65], v[52:53], v[10:11] op_sel:[0,1,0]
	v_pk_fma_f32 v[12:13], v[64:65], v[54:55], v[12:13] op_sel_hi:[1,0,1]
	v_pk_fma_f32 v[14:15], v[64:65], v[54:55], v[14:15] op_sel:[0,1,0]
	v_pk_fma_f32 v[0:1], v[228:229], v[40:41], v[0:1] op_sel_hi:[1,0,1]
	v_pk_fma_f32 v[2:3], v[228:229], v[40:41], v[2:3] op_sel:[0,1,0]
	v_pk_fma_f32 v[4:5], v[228:229], v[42:43], v[4:5] op_sel_hi:[1,0,1]
	v_pk_fma_f32 v[6:7], v[228:229], v[42:43], v[6:7] op_sel:[0,1,0]
	v_pk_fma_f32 v[8:9], v[228:229], v[44:45], v[8:9] op_sel_hi:[1,0,1]
	v_pk_fma_f32 v[10:11], v[228:229], v[44:45], v[10:11] op_sel:[0,1,0]
	v_pk_fma_f32 v[12:13], v[228:229], v[46:47], v[12:13] op_sel_hi:[1,0,1]
	v_pk_fma_f32 v[14:15], v[228:229], v[46:47], v[14:15] op_sel:[0,1,0]
	v_pk_mul_f32 v[116:117], v[0:1], v[56:57] op_sel_hi:[1,0]
	v_pk_fma_f32 v[116:117], v[2:3], v[56:57], v[116:117] op_sel:[0,1,0]
; DEV float reduce8_dpp(float v) { v += DPPF(v, 0xB1); v += DPPF(v, 0x4E); v += DPPF(v, 0x141); return v; }
;     ...
; #pragma unroll 32
;                 for (int tok = 0; tok < 32; ++tok) {
;                     const float* bs = base0 + tok * 384;
;                     const f32x4 a0 = *(const f32x4*)bs, a1 = *(const f32x4*)(bs + 4);
;                     const f32x4 w0 = *(const f32x4*)(bs + 64), w1 = *(const f32x4*)(bs + 68);
;                     const f32x4 b0 = *(const f32x4*)(bs + 128), b1 = *(const f32x4*)(bs + 132);
;                     const f32x4 k0 = *(const f32x4*)(bs + 192), k1 = *(const f32x4*)(bs + 196);
;                     const f32x4 r0 = *(const f32x4*)(bs + 256), r1 = *(const f32x4*)(bs + 260);
;                     const f32x2 vv = *(const f32x2*)(op + (size_t)(buf * 32 + tok) * 384 + 320 + 2 * vp);
;                     const f32x2 av[4] = {(f32x2){a0[0], a0[1]}, (f32x2){a0[2], a0[3]}, (f32x2){a1[0], a1[1]}, (f32x2){a1[2], a1[3]}};
;                     const f32x2 wv[4] = {(f32x2){w0[0], w0[1]}, (f32x2){w0[2], w0[3]}, (f32x2){w1[0], w1[1]}, (f32x2){w1[2], w1[3]}};
;                     const f32x2 bv[4] = {(f32x2){b0[0], b0[1]}, (f32x2){b0[2], b0[3]}, (f32x2){b1[0], b1[1]}, (f32x2){b1[2], b1[3]}};
;                     const f32x2 kv[4] = {(f32x2){k0[0], k0[1]}, (f32x2){k0[2], k0[3]}, (f32x2){k1[0], k1[1]}, (f32x2){k1[2], k1[3]}};
;                     const f32x2 rv[4] = {(f32x2){r0[0], r0[1]}, (f32x2){r0[2], r0[3]}, (f32x2){r1[0], r1[1]}, (f32x2){r1[2], r1[3]}};
;                     float yo[2];
; #pragma unroll
;                     for (int i = 0; i < 2; ++i) {
;                         f32x2 sa2 = st[i][0] * av[0]; sa2 += st[i][1] * av[1]; sa2 += st[i][2] * av[2]; sa2 += st[i][3] * av[3];
;                         const float sa = reduce8_dpp(sa2[0] + sa2[1]);
;                         const float vi = vv[i];
;                         f32x2 y2 = (f32x2){0.f, 0.f};
; #pragma unroll
;                         for (int j = 0; j < 4; ++j) { st[i][j] = st[i][j] * wv[j] + sa * bv[j] + vi * kv[j]; y2 += st[i][j] * rv[j]; }
;                         yo[i] = reduce8_dpp(y2[0] + y2[1]);
;                     }
;                     if (kq == 0) *(f32x2*)(yb + tok * 64) = (f32x2){yo[0], yo[1]};
;                 }
	v_pk_fma_f32 v[116:117], v[4:5], v[58:59], v[116:117] op_sel_hi:[1,0,1]
	v_pk_fma_f32 v[116:117], v[6:7], v[58:59], v[116:117] op_sel:[0,1,0]
	v_pk_fma_f32 v[116:117], v[8:9], v[60:61], v[116:117] op_sel_hi:[1,0,1]
	v_pk_fma_f32 v[116:117], v[10:11], v[60:61], v[116:117] op_sel:[0,1,0]
	v_pk_fma_f32 v[116:117], v[12:13], v[62:63], v[116:117] op_sel_hi:[1,0,1]
	v_pk_fma_f32 v[116:117], v[14:15], v[62:63], v[116:117] op_sel:[0,1,0]
	ds_read_b128 v[24:27], v20 offset:46080
	ds_read_b128 v[28:31], v20 offset:46096
	v_add_f32_dpp v240, v116, v116 quad_perm:[1,0,3,2] row_mask:0xf bank_mask:0xf bound_ctrl:1
	v_add_f32_dpp v241, v117, v117 quad_perm:[1,0,3,2] row_mask:0xf bank_mask:0xf bound_ctrl:1
	ds_read_b128 v[32:35], v20 offset:46336
	v_add_f32_dpp v240, v240, v240 quad_perm:[2,3,0,1] row_mask:0xf bank_mask:0xf bound_ctrl:1
	v_add_f32_dpp v241, v241, v241 quad_perm:[2,3,0,1] row_mask:0xf bank_mask:0xf bound_ctrl:1
	ds_read_b128 v[36:39], v20 offset:46352
	v_add_f32_dpp v240, v240, v240 row_half_mirror row_mask:0xf bank_mask:0xf bound_ctrl:1
	v_add_f32_dpp v241, v241, v241 row_half_mirror row_mask:0xf bank_mask:0xf bound_ctrl:1
	ds_read_b128 v[40:43], v20 offset:46592
	ds_read_b128 v[44:47], v20 offset:46608
	ds_read_b128 v[48:51], v20 offset:46848
	ds_read_b128 v[52:55], v20 offset:46864
	ds_read_b128 v[56:59], v20 offset:47104
	ds_read_b128 v[60:63], v20 offset:47120
	ds_read_b64 v[64:65], v22 offset:47360
	ds_write_b64 v21, v[240:241] offset:7168
	s_waitcnt lgkmcnt(12)
	v_pk_mul_f32 v[16:17], v[0:1], v[186:187] op_sel_hi:[1,0]
	v_pk_fma_f32 v[16:17], v[2:3], v[186:187], v[16:17] op_sel:[0,1,0]
	v_pk_fma_f32 v[16:17], v[4:5], v[188:189], v[16:17] op_sel_hi:[1,0,1]
	v_pk_fma_f32 v[16:17], v[6:7], v[188:189], v[16:17] op_sel:[0,1,0]
	v_pk_fma_f32 v[16:17], v[8:9], v[190:191], v[16:17] op_sel_hi:[1,0,1]
	v_pk_fma_f32 v[16:17], v[10:11], v[190:191], v[16:17] op_sel:[0,1,0]
	v_pk_fma_f32 v[16:17], v[12:13], v[192:193], v[16:17] op_sel_hi:[1,0,1]
	v_pk_fma_f32 v[16:17], v[14:15], v[192:193], v[16:17] op_sel:[0,1,0]
	v_pk_mul_f32 v[0:1], v[0:1], v[194:195] op_sel_hi:[1,0]
	v_pk_mul_f32 v[2:3], v[2:3], v[194:195] op_sel:[0,1]
	v_add_f32_dpp v16, v16, v16 quad_perm:[1,0,3,2] row_mask:0xf bank_mask:0xf bound_ctrl:1
	v_add_f32_dpp v17, v17, v17 quad_perm:[1,0,3,2] row_mask:0xf bank_mask:0xf bound_ctrl:1
	v_pk_mul_f32 v[4:5], v[4:5], v[196:197] op_sel_hi:[1,0]
	v_pk_mul_f32 v[6:7], v[6:7], v[196:197] op_sel:[0,1]
	v_add_f32_dpp v16, v16, v16 quad_perm:[2,3,0,1] row_mask:0xf bank_mask:0xf bound_ctrl:1
	v_add_f32_dpp v17, v17, v17 quad_perm:[2,3,0,1] row_mask:0xf bank_mask:0xf bound_ctrl:1
	v_pk_mul_f32 v[8:9], v[8:9], v[198:199] op_sel_hi:[1,0]
	v_pk_mul_f32 v[10:11], v[10:11], v[198:199] op_sel:[0,1]
	v_add_f32_dpp v228, v16, v16 row_half_mirror row_mask:0xf bank_mask:0xf bound_ctrl:1
	v_add_f32_dpp v229, v17, v17 row_half_mirror row_mask:0xf bank_mask:0xf bound_ctrl:1
	v_pk_mul_f32 v[12:13], v[12:13], v[200:201] op_sel_hi:[1,0]
	v_pk_mul_f32 v[14:15], v[14:15], v[200:201] op_sel:[0,1]
	v_pk_fma_f32 v[0:1], v[226:227], v[210:211], v[0:1] op_sel_hi:[1,0,1]
	v_pk_fma_f32 v[2:3], v[226:227], v[210:211], v[2:3] op_sel:[0,1,0]
	v_pk_fma_f32 v[4:5], v[226:227], v[212:213], v[4:5] op_sel_hi:[1,0,1]
	v_pk_fma_f32 v[6:7], v[226:227], v[212:213], v[6:7] op_sel:[0,1,0]
	v_pk_fma_f32 v[8:9], v[226:227], v[214:215], v[8:9] op_sel_hi:[1,0,1]
	v_pk_fma_f32 v[10:11], v[226:227], v[214:215], v[10:11] op_sel:[0,1,0]
	v_pk_fma_f32 v[12:13], v[226:227], v[216:217], v[12:13] op_sel_hi:[1,0,1]
	v_pk_fma_f32 v[14:15], v[226:227], v[216:217], v[14:15] op_sel:[0,1,0]
	v_pk_fma_f32 v[0:1], v[228:229], v[202:203], v[0:1] op_sel_hi:[1,0,1]
	v_pk_fma_f32 v[2:3], v[228:229], v[202:203], v[2:3] op_sel:[0,1,0]
	v_pk_fma_f32 v[4:5], v[228:229], v[204:205], v[4:5] op_sel_hi:[1,0,1]
	v_pk_fma_f32 v[6:7], v[228:229], v[204:205], v[6:7] op_sel:[0,1,0]
	v_pk_fma_f32 v[8:9], v[228:229], v[206:207], v[8:9] op_sel_hi:[1,0,1]
	v_pk_fma_f32 v[10:11], v[228:229], v[206:207], v[10:11] op_sel:[0,1,0]
	v_pk_fma_f32 v[12:13], v[228:229], v[208:209], v[12:13] op_sel_hi:[1,0,1]
	v_pk_fma_f32 v[14:15], v[228:229], v[208:209], v[14:15] op_sel:[0,1,0]
	v_pk_mul_f32 v[116:117], v[0:1], v[218:219] op_sel_hi:[1,0]
	v_pk_fma_f32 v[116:117], v[2:3], v[218:219], v[116:117] op_sel:[0,1,0]
	v_pk_fma_f32 v[116:117], v[4:5], v[220:221], v[116:117] op_sel_hi:[1,0,1]
	v_pk_fma_f32 v[116:117], v[6:7], v[220:221], v[116:117] op_sel:[0,1,0]
	v_pk_fma_f32 v[116:117], v[8:9], v[222:223], v[116:117] op_sel_hi:[1,0,1]
	v_pk_fma_f32 v[116:117], v[10:11], v[222:223], v[116:117] op_sel:[0,1,0]
	v_pk_fma_f32 v[116:117], v[12:13], v[224:225], v[116:117] op_sel_hi:[1,0,1]
	v_pk_fma_f32 v[116:117], v[14:15], v[224:225], v[116:117] op_sel:[0,1,0]
	ds_read_b128 v[186:189], v20 offset:47616
	ds_read_b128 v[190:193], v20 offset:47632
	v_add_f32_dpp v240, v116, v116 quad_perm:[1,0,3,2] row_mask:0xf bank_mask:0xf bound_ctrl:1
	v_add_f32_dpp v241, v117, v117 quad_perm:[1,0,3,2] row_mask:0xf bank_mask:0xf bound_ctrl:1
	ds_read_b128 v[194:197], v20 offset:47872
	v_add_f32_dpp v240, v240, v240 quad_perm:[2,3,0,1] row_mask:0xf bank_mask:0xf bound_ctrl:1
	v_add_f32_dpp v241, v241, v241 quad_perm:[2,3,0,1] row_mask:0xf bank_mask:0xf bound_ctrl:1
	ds_read_b128 v[198:201], v20 offset:47888
	v_add_f32_dpp v240, v240, v240 row_half_mirror row_mask:0xf bank_mask:0xf bound_ctrl:1
	v_add_f32_dpp v241, v241, v241 row_half_mirror row_mask:0xf bank_mask:0xf bound_ctrl:1
	ds_read_b128 v[202:205], v20 offset:48128
	ds_read_b128 v[206:209], v20 offset:48144
	ds_read_b128 v[210:213], v20 offset:48384
	ds_read_b128 v[214:217], v20 offset:48400
	ds_read_b128 v[218:221], v20 offset:48640
	ds_read_b128 v[222:225], v20 offset:48656
	ds_read_b64 v[226:227], v22 offset:48896
	ds_write_b64 v21, v[240:241] offset:7424
	s_waitcnt lgkmcnt(12)
; DEV float reduce8_dpp(float v) { v += DPPF(v, 0xB1); v += DPPF(v, 0x4E); v += DPPF(v, 0x141); return v; }
;     ...
; #pragma unroll 32
;                 for (int tok = 0; tok < 32; ++tok) {
;                     const float* bs = base0 + tok * 384;
;                     const f32x4 a0 = *(const f32x4*)bs, a1 = *(const f32x4*)(bs + 4);
;                     const f32x4 w0 = *(const f32x4*)(bs + 64), w1 = *(const f32x4*)(bs + 68);
;                     const f32x4 b0 = *(const f32x4*)(bs + 128), b1 = *(const f32x4*)(bs + 132);
;                     const f32x4 k0 = *(const f32x4*)(bs + 192), k1 = *(const f32x4*)(bs + 196);
;                     const f32x4 r0 = *(const f32x4*)(bs + 256), r1 = *(const f32x4*)(bs + 260);
;                     const f32x2 vv = *(const f32x2*)(op + (size_t)(buf * 32 + tok) * 384 + 320 + 2 * vp);
;                     const f32x2 av[4] = {(f32x2){a0[0], a0[1]}, (f32x2){a0[2], a0[3]}, (f32x2){a1[0], a1[1]}, (f32x2){a1[2], a1[3]}};
;                     const f32x2 wv[4] = {(f32x2){w0[0], w0[1]}, (f32x2){w0[2], w0[3]}, (f32x2){w1[0], w1[1]}, (f32x2){w1[2], w1[3]}};
;                     const f32x2 bv[4] = {(f32x2){b0[0], b0[1]}, (f32x2){b0[2], b0[3]}, (f32x2){b1[0], b1[1]}, (f32x2){b1[2], b1[3]}};
;                     const f32x2 kv[4] = {(f32x2){k0[0], k0[1]}, (f32x2){k0[2], k0[3]}, (f32x2){k1[0], k1[1]}, (f32x2){k1[2], k1[3]}};
;                     const f32x2 rv[4] = {(f32x2){r0[0], r0[1]}, (f32x2){r0[2], r0[3]}, (f32x2){r1[0], r1[1]}, (f32x2){r1[2], r1[3]}};
;                     float yo[2];
; #pragma unroll
;                     for (int i = 0; i < 2; ++i) {
;                         f32x2 sa2 = st[i][0] * av[0]; sa2 += st[i][1] * av[1]; sa2 += st[i][2] * av[2]; sa2 += st[i][3] * av[3];
;                         const float sa = reduce8_dpp(sa2[0] + sa2[1]);
;                         const float vi = vv[i];
;                         f32x2 y2 = (f32x2){0.f, 0.f};
; #pragma unroll
;                         for (int j = 0; j < 4; ++j) { st[i][j] = st[i][j] * wv[j] + sa * bv[j] + vi * kv[j]; y2 += st[i][j] * rv[j]; }
;                         yo[i] = reduce8_dpp(y2[0] + y2[1]);
;                     }
;                     if (kq == 0) *(f32x2*)(yb + tok * 64) = (f32x2){yo[0], yo[1]};
;                 }
	v_pk_mul_f32 v[16:17], v[0:1], v[24:25] op_sel_hi:[1,0]
	v_pk_fma_f32 v[16:17], v[2:3], v[24:25], v[16:17] op_sel:[0,1,0]
	v_pk_fma_f32 v[16:17], v[4:5], v[26:27], v[16:17] op_sel_hi:[1,0,1]
	v_pk_fma_f32 v[16:17], v[6:7], v[26:27], v[16:17] op_sel:[0,1,0]
	v_pk_fma_f32 v[16:17], v[8:9], v[28:29], v[16:17] op_sel_hi:[1,0,1]
	v_pk_fma_f32 v[16:17], v[10:11], v[28:29], v[16:17] op_sel:[0,1,0]
	v_pk_fma_f32 v[16:17], v[12:13], v[30:31], v[16:17] op_sel_hi:[1,0,1]
	v_pk_fma_f32 v[16:17], v[14:15], v[30:31], v[16:17] op_sel:[0,1,0]
	v_pk_mul_f32 v[0:1], v[0:1], v[32:33] op_sel_hi:[1,0]
	v_pk_mul_f32 v[2:3], v[2:3], v[32:33] op_sel:[0,1]
	v_add_f32_dpp v16, v16, v16 quad_perm:[1,0,3,2] row_mask:0xf bank_mask:0xf bound_ctrl:1
	v_add_f32_dpp v17, v17, v17 quad_perm:[1,0,3,2] row_mask:0xf bank_mask:0xf bound_ctrl:1
	v_pk_mul_f32 v[4:5], v[4:5], v[34:35] op_sel_hi:[1,0]
	v_pk_mul_f32 v[6:7], v[6:7], v[34:35] op_sel:[0,1]
	v_add_f32_dpp v16, v16, v16 quad_perm:[2,3,0,1] row_mask:0xf bank_mask:0xf bound_ctrl:1
	v_add_f32_dpp v17, v17, v17 quad_perm:[2,3,0,1] row_mask:0xf bank_mask:0xf bound_ctrl:1
	v_pk_mul_f32 v[8:9], v[8:9], v[36:37] op_sel_hi:[1,0]
	v_pk_mul_f32 v[10:11], v[10:11], v[36:37] op_sel:[0,1]
	v_add_f32_dpp v228, v16, v16 row_half_mirror row_mask:0xf bank_mask:0xf bound_ctrl:1
	v_add_f32_dpp v229, v17, v17 row_half_mirror row_mask:0xf bank_mask:0xf bound_ctrl:1
	v_pk_mul_f32 v[12:13], v[12:13], v[38:39] op_sel_hi:[1,0]
	v_pk_mul_f32 v[14:15], v[14:15], v[38:39] op_sel:[0,1]
	v_pk_fma_f32 v[0:1], v[64:65], v[48:49], v[0:1] op_sel_hi:[1,0,1]
	v_pk_fma_f32 v[2:3], v[64:65], v[48:49], v[2:3] op_sel:[0,1,0]
	v_pk_fma_f32 v[4:5], v[64:65], v[50:51], v[4:5] op_sel_hi:[1,0,1]
	v_pk_fma_f32 v[6:7], v[64:65], v[50:51], v[6:7] op_sel:[0,1,0]
	v_pk_fma_f32 v[8:9], v[64:65], v[52:53], v[8:9] op_sel_hi:[1,0,1]
	v_pk_fma_f32 v[10:11], v[64:65], v[52:53], v[10:11] op_sel:[0,1,0]
	v_pk_fma_f32 v[12:13], v[64:65], v[54:55], v[12:13] op_sel_hi:[1,0,1]
	v_pk_fma_f32 v[14:15], v[64:65], v[54:55], v[14:15] op_sel:[0,1,0]
	v_pk_fma_f32 v[0:1], v[228:229], v[40:41], v[0:1] op_sel_hi:[1,0,1]
	v_pk_fma_f32 v[2:3], v[228:229], v[40:41], v[2:3] op_sel:[0,1,0]
	v_pk_fma_f32 v[4:5], v[228:229], v[42:43], v[4:5] op_sel_hi:[1,0,1]
	v_pk_fma_f32 v[6:7], v[228:229], v[42:43], v[6:7] op_sel:[0,1,0]
	v_pk_fma_f32 v[8:9], v[228:229], v[44:45], v[8:9] op_sel_hi:[1,0,1]
	v_pk_fma_f32 v[10:11], v[228:229], v[44:45], v[10:11] op_sel:[0,1,0]
	v_pk_fma_f32 v[12:13], v[228:229], v[46:47], v[12:13] op_sel_hi:[1,0,1]
	v_pk_fma_f32 v[14:15], v[228:229], v[46:47], v[14:15] op_sel:[0,1,0]
	v_pk_mul_f32 v[116:117], v[0:1], v[56:57] op_sel_hi:[1,0]
	v_pk_fma_f32 v[116:117], v[2:3], v[56:57], v[116:117] op_sel:[0,1,0]
	v_pk_fma_f32 v[116:117], v[4:5], v[58:59], v[116:117] op_sel_hi:[1,0,1]
	v_pk_fma_f32 v[116:117], v[6:7], v[58:59], v[116:117] op_sel:[0,1,0]
	v_pk_fma_f32 v[116:117], v[8:9], v[60:61], v[116:117] op_sel_hi:[1,0,1]
	v_pk_fma_f32 v[116:117], v[10:11], v[60:61], v[116:117] op_sel:[0,1,0]
	v_pk_fma_f32 v[116:117], v[12:13], v[62:63], v[116:117] op_sel_hi:[1,0,1]
	v_pk_fma_f32 v[116:117], v[14:15], v[62:63], v[116:117] op_sel:[0,1,0]
	s_nop 0
	s_nop 0
	v_add_f32_dpp v240, v116, v116 quad_perm:[1,0,3,2] row_mask:0xf bank_mask:0xf bound_ctrl:1
	v_add_f32_dpp v241, v117, v117 quad_perm:[1,0,3,2] row_mask:0xf bank_mask:0xf bound_ctrl:1
	s_nop 0
	v_add_f32_dpp v240, v240, v240 quad_perm:[2,3,0,1] row_mask:0xf bank_mask:0xf bound_ctrl:1
	v_add_f32_dpp v241, v241, v241 quad_perm:[2,3,0,1] row_mask:0xf bank_mask:0xf bound_ctrl:1
	s_nop 0
	v_add_f32_dpp v240, v240, v240 row_half_mirror row_mask:0xf bank_mask:0xf bound_ctrl:1
	v_add_f32_dpp v241, v241, v241 row_half_mirror row_mask:0xf bank_mask:0xf bound_ctrl:1
	ds_write_b64 v21, v[240:241] offset:7680
	s_waitcnt lgkmcnt(0)
;     ...
;             for (int ci = 0; ci < 64; ++ci) {
;                 const int buf = ci & 1;
;                 const float* base0 = op + (size_t)buf * 32 * 384 + kq * 8;
;                 float* yb = ybuf + buf * 32 * 64 + 2 * vp;
; #pragma unroll 32
;                 for (int tok = 0; tok < 32; ++tok) {
;                     const float* bs = base0 + tok * 384;
;                     const f32x4 a0 = *(const f32x4*)bs, a1 = *(const f32x4*)(bs + 4);
;                     const f32x4 w0 = *(const f32x4*)(bs + 64), w1 = *(const f32x4*)(bs + 68);
;                     const f32x4 b0 = *(const f32x4*)(bs + 128), b1 = *(const f32x4*)(bs + 132);
;                     const f32x4 k0 = *(const f32x4*)(bs + 192), k1 = *(const f32x4*)(bs + 196);
;                     const f32x4 r0 = *(const f32x4*)(bs + 256), r1 = *(const f32x4*)(bs + 260);
;                     const f32x2 vv = *(const f32x2*)(op + (size_t)(buf * 32 + tok) * 384 + 320 + 2 * vp);
;                     const f32x2 av[4] = {(f32x2){a0[0], a0[1]}, (f32x2){a0[2], a0[3]}, (f32x2){a1[0], a1[1]}, (f32x2){a1[2], a1[3]}};
;                     const f32x2 wv[4] = {(f32x2){w0[0], w0[1]}, (f32x2){w0[2], w0[3]}, (f32x2){w1[0], w1[1]}, (f32x2){w1[2], w1[3]}};
;                     const f32x2 bv[4] = {(f32x2){b0[0], b0[1]}, (f32x2){b0[2], b0[3]}, (f32x2){b1[0], b1[1]}, (f32x2){b1[2], b1[3]}};
;                     const f32x2 kv[4] = {(f32x2){k0[0], k0[1]}, (f32x2){k0[2], k0[3]}, (f32x2){k1[0], k1[1]}, (f32x2){k1[2], k1[3]}};
;                     const f32x2 rv[4] = {(f32x2){r0[0], r0[1]}, (f32x2){r0[2], r0[3]}, (f32x2){r1[0], r1[1]}, (f32x2){r1[2], r1[3]}};
;                     float yo[2];
; #pragma unroll
;                     for (int i = 0; i < 2; ++i) {
;                         f32x2 sa2 = st[i][0] * av[0]; sa2 += st[i][1] * av[1]; sa2 += st[i][2] * av[2]; sa2 += st[i][3] * av[3];
;                         const float sa = reduce8_dpp(sa2[0] + sa2[1]);
;                         const float vi = vv[i];
;                         f32x2 y2 = (f32x2){0.f, 0.f};
; #pragma unroll
;                         for (int j = 0; j < 4; ++j) { st[i][j] = st[i][j] * wv[j] + sa * bv[j] + vi * kv[j]; y2 += st[i][j] * rv[j]; }
;                         yo[i] = reduce8_dpp(y2[0] + y2[1]);
;                     }
;                     if (kq == 0) *(f32x2*)(yb + tok * 64) = (f32x2){yo[0], yo[1]};
;                 }
	v_pk_mul_f32 v[16:17], v[0:1], v[186:187] op_sel_hi:[1,0]
	v_pk_fma_f32 v[16:17], v[2:3], v[186:187], v[16:17] op_sel:[0,1,0]
	v_pk_fma_f32 v[16:17], v[4:5], v[188:189], v[16:17] op_sel_hi:[1,0,1]
	v_pk_fma_f32 v[16:17], v[6:7], v[188:189], v[16:17] op_sel:[0,1,0]
	v_pk_fma_f32 v[16:17], v[8:9], v[190:191], v[16:17] op_sel_hi:[1,0,1]
	v_pk_fma_f32 v[16:17], v[10:11], v[190:191], v[16:17] op_sel:[0,1,0]
	v_pk_fma_f32 v[16:17], v[12:13], v[192:193], v[16:17] op_sel_hi:[1,0,1]
	v_pk_fma_f32 v[16:17], v[14:15], v[192:193], v[16:17] op_sel:[0,1,0]
	v_pk_mul_f32 v[0:1], v[0:1], v[194:195] op_sel_hi:[1,0]
	v_pk_mul_f32 v[2:3], v[2:3], v[194:195] op_sel:[0,1]
	v_add_f32_dpp v16, v16, v16 quad_perm:[1,0,3,2] row_mask:0xf bank_mask:0xf bound_ctrl:1
	v_add_f32_dpp v17, v17, v17 quad_perm:[1,0,3,2] row_mask:0xf bank_mask:0xf bound_ctrl:1
	v_pk_mul_f32 v[4:5], v[4:5], v[196:197] op_sel_hi:[1,0]
	v_pk_mul_f32 v[6:7], v[6:7], v[196:197] op_sel:[0,1]
	v_add_f32_dpp v16, v16, v16 quad_perm:[2,3,0,1] row_mask:0xf bank_mask:0xf bound_ctrl:1
	v_add_f32_dpp v17, v17, v17 quad_perm:[2,3,0,1] row_mask:0xf bank_mask:0xf bound_ctrl:1
	v_pk_mul_f32 v[8:9], v[8:9], v[198:199] op_sel_hi:[1,0]
	v_pk_mul_f32 v[10:11], v[10:11], v[198:199] op_sel:[0,1]
	v_add_f32_dpp v228, v16, v16 row_half_mirror row_mask:0xf bank_mask:0xf bound_ctrl:1
	v_add_f32_dpp v229, v17, v17 row_half_mirror row_mask:0xf bank_mask:0xf bound_ctrl:1
	v_pk_mul_f32 v[12:13], v[12:13], v[200:201] op_sel_hi:[1,0]
	v_pk_mul_f32 v[14:15], v[14:15], v[200:201] op_sel:[0,1]
	v_pk_fma_f32 v[0:1], v[226:227], v[210:211], v[0:1] op_sel_hi:[1,0,1]
	v_pk_fma_f32 v[2:3], v[226:227], v[210:211], v[2:3] op_sel:[0,1,0]
	v_pk_fma_f32 v[4:5], v[226:227], v[212:213], v[4:5] op_sel_hi:[1,0,1]
	v_pk_fma_f32 v[6:7], v[226:227], v[212:213], v[6:7] op_sel:[0,1,0]
	v_pk_fma_f32 v[8:9], v[226:227], v[214:215], v[8:9] op_sel_hi:[1,0,1]
	v_pk_fma_f32 v[10:11], v[226:227], v[214:215], v[10:11] op_sel:[0,1,0]
	v_pk_fma_f32 v[12:13], v[226:227], v[216:217], v[12:13] op_sel_hi:[1,0,1]
	v_pk_fma_f32 v[14:15], v[226:227], v[216:217], v[14:15] op_sel:[0,1,0]
	v_pk_fma_f32 v[0:1], v[228:229], v[202:203], v[0:1] op_sel_hi:[1,0,1]
	v_pk_fma_f32 v[2:3], v[228:229], v[202:203], v[2:3] op_sel:[0,1,0]
	v_pk_fma_f32 v[4:5], v[228:229], v[204:205], v[4:5] op_sel_hi:[1,0,1]
	v_pk_fma_f32 v[6:7], v[228:229], v[204:205], v[6:7] op_sel:[0,1,0]
	v_pk_fma_f32 v[8:9], v[228:229], v[206:207], v[8:9] op_sel_hi:[1,0,1]
	v_pk_fma_f32 v[10:11], v[228:229], v[206:207], v[10:11] op_sel:[0,1,0]
	v_pk_fma_f32 v[12:13], v[228:229], v[208:209], v[12:13] op_sel_hi:[1,0,1]
	v_pk_fma_f32 v[14:15], v[228:229], v[208:209], v[14:15] op_sel:[0,1,0]
	v_pk_mul_f32 v[116:117], v[0:1], v[218:219] op_sel_hi:[1,0]
	v_pk_fma_f32 v[116:117], v[2:3], v[218:219], v[116:117] op_sel:[0,1,0]
	v_pk_fma_f32 v[116:117], v[4:5], v[220:221], v[116:117] op_sel_hi:[1,0,1]
	v_pk_fma_f32 v[116:117], v[6:7], v[220:221], v[116:117] op_sel:[0,1,0]
	v_pk_fma_f32 v[116:117], v[8:9], v[222:223], v[116:117] op_sel_hi:[1,0,1]
	v_pk_fma_f32 v[116:117], v[10:11], v[222:223], v[116:117] op_sel:[0,1,0]
	v_pk_fma_f32 v[116:117], v[12:13], v[224:225], v[116:117] op_sel_hi:[1,0,1]
	v_pk_fma_f32 v[116:117], v[14:15], v[224:225], v[116:117] op_sel:[0,1,0]
	s_nop 0
	s_nop 0
	v_add_f32_dpp v240, v116, v116 quad_perm:[1,0,3,2] row_mask:0xf bank_mask:0xf bound_ctrl:1
	v_add_f32_dpp v241, v117, v117 quad_perm:[1,0,3,2] row_mask:0xf bank_mask:0xf bound_ctrl:1
	s_nop 0
	v_add_f32_dpp v240, v240, v240 quad_perm:[2,3,0,1] row_mask:0xf bank_mask:0xf bound_ctrl:1
	v_add_f32_dpp v241, v241, v241 quad_perm:[2,3,0,1] row_mask:0xf bank_mask:0xf bound_ctrl:1
	s_nop 0
	v_add_f32_dpp v240, v240, v240 row_half_mirror row_mask:0xf bank_mask:0xf bound_ctrl:1
	v_add_f32_dpp v241, v241, v241 row_half_mirror row_mask:0xf bank_mask:0xf bound_ctrl:1
	ds_write_b64 v21, v[240:241] offset:7936
	s_branch .LBB0_464
